# resid epilogues (w_out, ff2) rewritten: software-pipelined x loads, DPP row-half exchange so each x4 load/store covers full 128B lines
# speedup vs baseline: 1.0073x; 1.0073x over previous
; DI f32x4 mfma16(bf16x8 a, bf16x8 b, f32x4 c) { return __builtin_amdgcn_mfma_f32_16x16x32_bf16(a, b, c, 0, 0, 0); }
;     ...
;   for (int ks = KS0; ks < KS1; ++ks) {
;     bf16x8 af[8], bfr[4];
; #pragma unroll
;     for (int i = 0; i < 8; ++i) {
;       const int r = wm * 128 + i * 16 + (lane & 15);
;       af[i] = *(const bf16x8*)(S + r * 64 + (((ks * 4 + (lane >> 4)) ^ ((r >> 1) & 7)) << 3));
;     }
; #pragma unroll
;     for (int j = 0; j < 4; ++j) {
;       const int r = wn * 64 + j * 16 + (lane & 15);
;       bfr[j] = *(const bf16x8*)(S + 16384 + r * 64 + (((ks * 4 + (lane >> 4)) ^ ((r >> 1) & 7)) << 3));
;     }
;     __builtin_amdgcn_s_setprio(1);
; #pragma unroll
;     for (int i = 0; i < 8; ++i)
; #pragma unroll
;       for (int j = 0; j < 4; ++j) acc[i][j] = mfma16(bfr[j], af[i], acc[i][j]);
;     __builtin_amdgcn_s_setprio(0);
; DI void gemm8_accum(f32x4 (&acc)[8][4], const bf16_t* a, size_t lda, const bf16_t* b, size_t ldb, int nkb, bf16_t* L,
;                     const bool pre, const bf16_t* an, size_t ldan, const bf16_t* bn, size_t ldbn) {
;     ...
;   __syncthreads();
;   g8_store1(L + 32768, ra, lrow, lch);
;   g8_load1(ra, an, ldan, 0, lrow, lch);
;   __builtin_amdgcn_sched_barrier(0);
;   g8_compute<0, 1>(acc, L, wm, wn, lane);
;   __builtin_amdgcn_sched_barrier(0);
;   g8_store1(L + 32768 + 16384, rb, lrow, lch);
;   g8_load1(rb, bn, ldbn, 0, lrow, lch);
;   __builtin_amdgcn_sched_barrier(0);
;   g8_compute<1, 2>(acc, L, wm, wn, lane);
.Lstg_830_c:
	v_readlane_b32 s0, v254, 18
	s_add_i32 s12, s13, s0
	s_cmp_gt_u32 s12, 63
	s_cselect_b64 s[0:1], -1, 0
	s_cmp_lt_u32 s12, 64
	s_cselect_b32 s7, s12, s13
	s_lshl_b32 s2, s7, 1
	s_and_b32 s2, s2, 0x7fffffe0
	s_and_b32 s3, s7, 3
	s_or_b32 s2, s3, s2
	v_readlane_b32 s3, v252, 25
	s_or_b32 s2, s2, s3
	s_lshl_b32 s13, s11, 8
	s_mul_hi_u32 s3, s2, 0x2a3000
	s_mul_i32 s2, s2, 0x2a3000
	s_add_u32 s2, s16, s2
	s_addc_u32 s3, s17, s3
	v_mov_b32_e32 v177, v1
	v_mov_b32_e32 v175, v1
	v_mov_b32_e32 v173, v1
	v_lshl_add_u64 v[178:179], v[0:1], 1, s[2:3]
	v_lshl_add_u64 v[180:181], v[176:177], 1, s[2:3]
	v_lshl_add_u64 v[174:175], v[174:175], 1, s[2:3]
	v_lshl_add_u64 v[184:185], v[172:173], 1, s[2:3]
	s_barrier
	global_load_dwordx4 v[176:179], v[178:179], off offset:3632
	s_nop 0
	global_load_dwordx4 v[180:183], v[180:181], off offset:3632
	s_nop 0
	global_load_dwordx4 v[172:175], v[174:175], off offset:3632
	s_nop 0
	global_load_dwordx4 v[184:187], v[184:185], off offset:3632
	s_lshl_b32 s2, s7, 17
	s_and_b32 s2, s2, 0x180000
	v_readlane_b32 s20, v251, 63
	v_readlane_b32 s21, v252, 0
	s_add_u32 s2, s20, s2
	s_addc_u32 s3, s21, 0
	s_add_i32 s7, 0, 0x10000
	v_add3_u32 v0, s7, v165, v167
	s_waitcnt vmcnt(11)
	ds_write_b128 v0, v[18:21]
	s_waitcnt vmcnt(10)
	ds_write_b128 v0, v[22:25] offset:8192
	s_waitcnt vmcnt(9)
	ds_write_b128 v0, v[26:29] offset:16384
	s_waitcnt vmcnt(8)
	ds_write_b128 v0, v[30:33] offset:24576
	v_lshlrev_b32_e32 v0, 1, v169
	v_add_u32_e32 v169, 0, v0
	v_add_u32_e32 v171, v169, v195
	ds_read_b128 v[18:21], v171
	ds_read_b128 v[22:25], v171 offset:2048
	ds_read_b128 v[26:29], v171 offset:4096
	ds_read_b128 v[30:33], v171 offset:6144
	ds_read_b128 v[188:191], v171 offset:8192
	ds_read_b128 v[198:201], v171 offset:10240
	ds_read_b128 v[206:209], v171 offset:12288
	ds_read_b128 v[210:213], v171 offset:14336
	v_add_u32_e32 v169, v169, v194
	ds_read_b128 v[214:217], v169 offset:32768
	ds_read_b128 v[218:221], v169 offset:34816
	ds_read_b128 v[222:225], v169 offset:36864
	ds_read_b128 v[226:229], v169 offset:38912
	s_setprio 1
	s_waitcnt lgkmcnt(3)
	v_mfma_f32_16x16x32_bf16 v[158:161], v[214:217], v[18:21], v[158:161]
	s_waitcnt lgkmcnt(2)
	v_mfma_f32_16x16x32_bf16 v[154:157], v[218:221], v[18:21], v[154:157]
	s_waitcnt lgkmcnt(1)
	v_mfma_f32_16x16x32_bf16 v[150:153], v[222:225], v[18:21], v[150:153]
	s_waitcnt lgkmcnt(0)
	v_mfma_f32_16x16x32_bf16 v[18:21], v[226:229], v[18:21], v[146:149]
	v_mfma_f32_16x16x32_bf16 v[142:145], v[214:217], v[22:25], v[142:145]
	v_mfma_f32_16x16x32_bf16 v[138:141], v[218:221], v[22:25], v[138:141]
	v_mfma_f32_16x16x32_bf16 v[134:137], v[222:225], v[22:25], v[134:137]
	v_mfma_f32_16x16x32_bf16 v[22:25], v[226:229], v[22:25], v[130:133]
	v_mfma_f32_16x16x32_bf16 v[126:129], v[214:217], v[26:29], v[126:129]
	v_mfma_f32_16x16x32_bf16 v[122:125], v[218:221], v[26:29], v[122:125]
	v_mfma_f32_16x16x32_bf16 v[118:121], v[222:225], v[26:29], v[118:121]
	v_mfma_f32_16x16x32_bf16 v[26:29], v[226:229], v[26:29], v[114:117]
	v_mfma_f32_16x16x32_bf16 v[110:113], v[214:217], v[30:33], v[110:113]
	v_mfma_f32_16x16x32_bf16 v[106:109], v[218:221], v[30:33], v[106:109]
	v_mfma_f32_16x16x32_bf16 v[102:105], v[222:225], v[30:33], v[102:105]
	v_mfma_f32_16x16x32_bf16 v[30:33], v[226:229], v[30:33], v[98:101]
	v_mfma_f32_16x16x32_bf16 v[94:97], v[214:217], v[188:191], v[94:97]
	v_mfma_f32_16x16x32_bf16 v[90:93], v[218:221], v[188:191], v[90:93]
	v_mfma_f32_16x16x32_bf16 v[86:89], v[222:225], v[188:191], v[86:89]
	v_mfma_f32_16x16x32_bf16 v[82:85], v[226:229], v[188:191], v[82:85]
	v_mfma_f32_16x16x32_bf16 v[78:81], v[214:217], v[198:201], v[78:81]
	v_mfma_f32_16x16x32_bf16 v[74:77], v[218:221], v[198:201], v[74:77]
	v_mfma_f32_16x16x32_bf16 v[70:73], v[222:225], v[198:201], v[70:73]
	v_mfma_f32_16x16x32_bf16 v[66:69], v[226:229], v[198:201], v[66:69]
	v_mfma_f32_16x16x32_bf16 v[62:65], v[214:217], v[206:209], v[62:65]
	v_mfma_f32_16x16x32_bf16 v[58:61], v[218:221], v[206:209], v[58:61]
	v_mfma_f32_16x16x32_bf16 v[54:57], v[222:225], v[206:209], v[54:57]
	v_mfma_f32_16x16x32_bf16 v[50:53], v[226:229], v[206:209], v[50:53]
	v_mfma_f32_16x16x32_bf16 v[46:49], v[214:217], v[210:213], v[46:49]
	v_mfma_f32_16x16x32_bf16 v[38:41], v[222:225], v[210:213], v[38:41]
	v_mfma_f32_16x16x32_bf16 v[34:37], v[226:229], v[210:213], v[34:37]
	v_mfma_f32_16x16x32_bf16 v[42:45], v[218:221], v[210:213], v[42:45]
	s_setprio 0
	v_readlane_b32 s20, v254, 36
	v_mov_b32_e32 v171, v1
	v_mov_b32_e32 v169, v1
	v_add3_u32 v98, s20, v165, v167
	v_mov_b32_e32 v167, v1
	v_mov_b32_e32 v165, v1
	s_waitcnt vmcnt(7)
	ds_write_b128 v98, v[14:17]
	s_waitcnt vmcnt(6)
	ds_write_b128 v98, v[2:5] offset:8192
	s_waitcnt vmcnt(5)
	ds_write_b128 v98, v[6:9] offset:16384
	s_waitcnt vmcnt(4)
	ds_write_b128 v98, v[10:13] offset:24576
	v_lshl_add_u64 v[2:3], v[170:171], 1, s[2:3]
	v_lshl_add_u64 v[6:7], v[168:169], 1, s[2:3]
	v_lshl_add_u64 v[10:11], v[166:167], 1, s[2:3]
	v_lshl_add_u64 v[14:15], v[164:165], 1, s[2:3]
	global_load_dwordx4 v[2:5], v[2:3], off
	s_nop 0
	global_load_dwordx4 v[6:9], v[6:7], off
	s_nop 0
	global_load_dwordx4 v[10:13], v[10:11], off
	s_nop 0
	global_load_dwordx4 v[14:17], v[14:15], off
	v_lshlrev_b32_e32 v192, 1, v205
	v_add_u32_e32 v193, 0, v192
	v_add_u32_e32 v198, v193, v195
	ds_read_b128 v[98:101], v198
	ds_read_b128 v[114:117], v198 offset:2048
	ds_read_b128 v[130:133], v198 offset:4096
	ds_read_b128 v[146:149], v198 offset:6144
	ds_read_b128 v[164:167], v198 offset:8192
	ds_read_b128 v[168:171], v198 offset:10240
	ds_read_b128 v[188:191], v198 offset:12288
	ds_read_b128 v[198:201], v198 offset:14336
	v_add_u32_e32 v193, v193, v194
	ds_read_b128 v[206:209], v193 offset:32768
	ds_read_b128 v[210:213], v193 offset:34816
	ds_read_b128 v[214:217], v193 offset:36864
	ds_read_b128 v[218:221], v193 offset:38912
	s_setprio 1
	s_waitcnt lgkmcnt(3)
; DI f32x4 mfma16(bf16x8 a, bf16x8 b, f32x4 c) { return __builtin_amdgcn_mfma_f32_16x16x32_bf16(a, b, c, 0, 0, 0); }
;     ...
;   for (int ks = KS0; ks < KS1; ++ks) {
;     bf16x8 af[8], bfr[4];
; #pragma unroll
;     for (int i = 0; i < 8; ++i) {
;       const int r = wm * 128 + i * 16 + (lane & 15);
;       af[i] = *(const bf16x8*)(S + r * 64 + (((ks * 4 + (lane >> 4)) ^ ((r >> 1) & 7)) << 3));
;     }
; #pragma unroll
;     for (int j = 0; j < 4; ++j) {
;       const int r = wn * 64 + j * 16 + (lane & 15);
;       bfr[j] = *(const bf16x8*)(S + 16384 + r * 64 + (((ks * 4 + (lane >> 4)) ^ ((r >> 1) & 7)) << 3));
;     }
;     __builtin_amdgcn_s_setprio(1);
; #pragma unroll
;     for (int i = 0; i < 8; ++i)
; #pragma unroll
;       for (int j = 0; j < 4; ++j) acc[i][j] = mfma16(bfr[j], af[i], acc[i][j]);
;     __builtin_amdgcn_s_setprio(0);
; DI void gemm8_accum(f32x4 (&acc)[8][4], const bf16_t* a, size_t lda, const bf16_t* b, size_t ldb, int nkb, bf16_t* L,
;                     const bool pre, const bf16_t* an, size_t ldan, const bf16_t* bn, size_t ldbn) {
;     ...
;   g8_compute<1, 2>(acc, L, wm, wn, lane);
;   __syncthreads();
;   g8_store1(L, ra, lrow, lch);
;   __builtin_amdgcn_sched_barrier(0);
;   g8_compute<0, 1>(acc, L + 32768, wm, wn, lane);
;   __builtin_amdgcn_sched_barrier(0);
;   g8_store1(L + 16384, rb, lrow, lch);
	v_mfma_f32_16x16x32_bf16 v[158:161], v[206:209], v[98:101], v[158:161]
	s_waitcnt lgkmcnt(2)
	v_mfma_f32_16x16x32_bf16 v[154:157], v[210:213], v[98:101], v[154:157]
	s_waitcnt lgkmcnt(1)
	v_mfma_f32_16x16x32_bf16 v[150:153], v[214:217], v[98:101], v[150:153]
	s_waitcnt lgkmcnt(0)
	v_mfma_f32_16x16x32_bf16 v[18:21], v[218:221], v[98:101], v[18:21]
	v_mfma_f32_16x16x32_bf16 v[98:101], v[206:209], v[114:117], v[142:145]
	v_mfma_f32_16x16x32_bf16 v[138:141], v[210:213], v[114:117], v[138:141]
	v_mfma_f32_16x16x32_bf16 v[134:137], v[214:217], v[114:117], v[134:137]
	v_mfma_f32_16x16x32_bf16 v[22:25], v[218:221], v[114:117], v[22:25]
	v_mfma_f32_16x16x32_bf16 v[114:117], v[206:209], v[130:133], v[126:129]
	v_mfma_f32_16x16x32_bf16 v[122:125], v[210:213], v[130:133], v[122:125]
	v_mfma_f32_16x16x32_bf16 v[118:121], v[214:217], v[130:133], v[118:121]
	v_mfma_f32_16x16x32_bf16 v[26:29], v[218:221], v[130:133], v[26:29]
	v_mfma_f32_16x16x32_bf16 v[110:113], v[206:209], v[146:149], v[110:113]
	v_mfma_f32_16x16x32_bf16 v[106:109], v[210:213], v[146:149], v[106:109]
	v_mfma_f32_16x16x32_bf16 v[102:105], v[214:217], v[146:149], v[102:105]
	v_mfma_f32_16x16x32_bf16 v[30:33], v[218:221], v[146:149], v[30:33]
	v_mfma_f32_16x16x32_bf16 v[94:97], v[206:209], v[164:167], v[94:97]
	v_mfma_f32_16x16x32_bf16 v[90:93], v[210:213], v[164:167], v[90:93]
	v_mfma_f32_16x16x32_bf16 v[86:89], v[214:217], v[164:167], v[86:89]
	v_mfma_f32_16x16x32_bf16 v[82:85], v[218:221], v[164:167], v[82:85]
	v_mfma_f32_16x16x32_bf16 v[78:81], v[206:209], v[168:171], v[78:81]
	v_mfma_f32_16x16x32_bf16 v[74:77], v[210:213], v[168:171], v[74:77]
	v_mfma_f32_16x16x32_bf16 v[70:73], v[214:217], v[168:171], v[70:73]
	v_mfma_f32_16x16x32_bf16 v[66:69], v[218:221], v[168:171], v[66:69]
	v_mfma_f32_16x16x32_bf16 v[62:65], v[206:209], v[188:191], v[62:65]
	v_mfma_f32_16x16x32_bf16 v[58:61], v[210:213], v[188:191], v[58:61]
	v_mfma_f32_16x16x32_bf16 v[54:57], v[214:217], v[188:191], v[54:57]
	v_mfma_f32_16x16x32_bf16 v[50:53], v[218:221], v[188:191], v[50:53]
	v_mfma_f32_16x16x32_bf16 v[46:49], v[206:209], v[198:201], v[46:49]
	v_mfma_f32_16x16x32_bf16 v[38:41], v[214:217], v[198:201], v[38:41]
	v_mfma_f32_16x16x32_bf16 v[34:37], v[218:221], v[198:201], v[34:37]
	v_mfma_f32_16x16x32_bf16 v[42:45], v[210:213], v[198:201], v[42:45]
	s_setprio 0
	s_barrier
	s_waitcnt vmcnt(7)
	ds_write_b128 v163, v[176:179]
	s_waitcnt vmcnt(6)
	ds_write_b128 v163, v[180:183] offset:8192
	s_waitcnt vmcnt(5)
	ds_write_b128 v163, v[172:175] offset:16384
	s_waitcnt vmcnt(4)
	ds_write_b128 v163, v[184:187] offset:24576
	v_add3_u32 v176, s7, v0, v195
	ds_read_b128 v[126:129], v176
	ds_read_b128 v[130:133], v176 offset:2048
	ds_read_b128 v[142:145], v176 offset:4096
	ds_read_b128 v[146:149], v176 offset:6144
	ds_read_b128 v[164:167], v176 offset:8192
	ds_read_b128 v[168:171], v176 offset:10240
	ds_read_b128 v[172:175], v176 offset:12288
	ds_read_b128 v[176:179], v176 offset:14336
	v_add3_u32 v0, s20, v0, v194
	ds_read_b128 v[180:183], v0
	ds_read_b128 v[184:187], v0 offset:2048
	ds_read_b128 v[188:191], v0 offset:4096
	ds_read_b128 v[198:201], v0 offset:6144
	s_setprio 1
	s_waitcnt lgkmcnt(3)
	v_mfma_f32_16x16x32_bf16 v[158:161], v[180:183], v[126:129], v[158:161]
	s_waitcnt lgkmcnt(2)
	v_mfma_f32_16x16x32_bf16 v[154:157], v[184:187], v[126:129], v[154:157]
	s_waitcnt lgkmcnt(1)
	v_mfma_f32_16x16x32_bf16 v[150:153], v[188:191], v[126:129], v[150:153]
	s_waitcnt lgkmcnt(0)
	v_mfma_f32_16x16x32_bf16 v[18:21], v[198:201], v[126:129], v[18:21]
	v_mfma_f32_16x16x32_bf16 v[98:101], v[180:183], v[130:133], v[98:101]
	v_mfma_f32_16x16x32_bf16 v[126:129], v[184:187], v[130:133], v[138:141]
	v_mfma_f32_16x16x32_bf16 v[134:137], v[188:191], v[130:133], v[134:137]
	v_mfma_f32_16x16x32_bf16 v[22:25], v[198:201], v[130:133], v[22:25]
	v_mfma_f32_16x16x32_bf16 v[114:117], v[180:183], v[142:145], v[114:117]
	v_mfma_f32_16x16x32_bf16 v[122:125], v[184:187], v[142:145], v[122:125]
	v_mfma_f32_16x16x32_bf16 v[118:121], v[188:191], v[142:145], v[118:121]
	v_mfma_f32_16x16x32_bf16 v[26:29], v[198:201], v[142:145], v[26:29]
	v_mfma_f32_16x16x32_bf16 v[130:133], v[180:183], v[146:149], v[110:113]
	v_mfma_f32_16x16x32_bf16 v[30:33], v[198:201], v[146:149], v[30:33]
	v_mfma_f32_16x16x32_bf16 v[138:141], v[184:187], v[146:149], v[106:109]
	v_mfma_f32_16x16x32_bf16 v[142:145], v[188:191], v[146:149], v[102:105]
	v_mfma_f32_16x16x32_bf16 v[146:149], v[180:183], v[164:167], v[94:97]
	v_mfma_f32_16x16x32_bf16 v[206:209], v[184:187], v[164:167], v[90:93]
	v_mfma_f32_16x16x32_bf16 v[210:213], v[188:191], v[164:167], v[86:89]
	v_mfma_f32_16x16x32_bf16 v[164:167], v[198:201], v[164:167], v[82:85]
	v_mfma_f32_16x16x32_bf16 v[214:217], v[180:183], v[168:171], v[78:81]
	v_mfma_f32_16x16x32_bf16 v[218:221], v[184:187], v[168:171], v[74:77]
	v_mfma_f32_16x16x32_bf16 v[222:225], v[188:191], v[168:171], v[70:73]
	v_mfma_f32_16x16x32_bf16 v[168:171], v[198:201], v[168:171], v[66:69]
	v_mfma_f32_16x16x32_bf16 v[226:229], v[180:183], v[172:175], v[62:65]
	v_mfma_f32_16x16x32_bf16 v[230:233], v[184:187], v[172:175], v[58:61]
	v_mfma_f32_16x16x32_bf16 v[234:237], v[188:191], v[172:175], v[54:57]
	v_mfma_f32_16x16x32_bf16 v[172:175], v[198:201], v[172:175], v[50:53]
	v_mfma_f32_16x16x32_bf16 v[180:183], v[180:183], v[176:179], v[46:49]
	v_mfma_f32_16x16x32_bf16 v[184:187], v[184:187], v[176:179], v[42:45]
	v_mfma_f32_16x16x32_bf16 v[188:191], v[188:191], v[176:179], v[38:41]
	v_mfma_f32_16x16x32_bf16 v[176:179], v[198:201], v[176:179], v[34:37]
	s_setprio 0
	s_waitcnt vmcnt(3)
	ds_write_b128 v163, v[2:5] offset:32768
	s_waitcnt vmcnt(2)
; DI int TID8() { int t = threadIdx.x; asm volatile("" : "+v"(t)); return t; }
; DI void gemm8_accum(f32x4 (&acc)[8][4], const bf16_t* a, size_t lda, const bf16_t* b, size_t ldb, int nkb, bf16_t* L,
;                     const bool pre, const bf16_t* an, size_t ldan, const bf16_t* bn, size_t ldbn) {
;     ...
;   g8_store1(L + 16384, rb, lrow, lch);
;   __builtin_amdgcn_sched_barrier(0);
;   g8_compute<1, 2>(acc, L + 32768, wm, wn, lane);
;   __syncthreads();
; DI void gemm8_epi_resid(f32x4 (&acc)[8][4], int m0, int n0, int ntile8, bf16_t* L, const float* xin, float* out, bf16_t* xb, float* rowpart) {
;   const int tid = TID8(), lane = tid & 63, w = tid >> 6;
;   const int wm = w >> 2, wn = w & 3;
;   float* red = (float*)(L + 32768);
; #pragma unroll
;   for (int i = 0; i < 8; ++i) {
;     const int ml = wm * 128 + i * 16 + (lane & 15);
;     const size_t rowoff = (size_t)(m0 + ml) * DM;
;     float ss = 0.f;
; #pragma unroll
;     for (int j = 0; j < 4; ++j) {
;       const int n = n0 + wn * 64 + j * 16 + (lane >> 4) * 4;
;       const float4 xv = *(const float4*)(xin + rowoff + n);
;       const float o0 = xv.x + acc[i][j][0], o1 = xv.y + acc[i][j][1], o2 = xv.z + acc[i][j][2], o3 = xv.w + acc[i][j][3];
;       *(float4*)(out + rowoff + n) = make_float4(o0, o1, o2, o3);
;       ss += o0 * o0 + o1 * o1 + o2 * o2 + o3 * o3;
	ds_write_b128 v163, v[6:9] offset:40960
	s_waitcnt vmcnt(1)
	ds_write_b128 v163, v[10:13] offset:49152
	s_waitcnt vmcnt(0)
	ds_write_b128 v163, v[14:17] offset:57344
	v_add3_u32 v0, s7, v192, v195
	ds_read_b128 v[2:5], v0
	ds_read_b128 v[6:9], v0 offset:2048
	ds_read_b128 v[10:13], v0 offset:4096
	ds_read_b128 v[14:17], v0 offset:6144
	ds_read_b128 v[34:37], v0 offset:8192
	ds_read_b128 v[198:201], v0 offset:10240
	ds_read_b128 v[238:241], v0 offset:12288
	ds_read_b128 v[242:245], v0 offset:14336
	v_add3_u32 v0, s20, v192, v194
	ds_read_b128 v[192:195], v0
	ds_read_b128 v[246:249], v0 offset:2048
	ds_read_b128 v[38:41], v0 offset:4096
	ds_read_b128 v[42:45], v0 offset:6144
	s_setprio 1
	s_waitcnt lgkmcnt(3)
	v_mfma_f32_16x16x32_bf16 v[158:161], v[192:195], v[2:5], v[158:161]
	s_waitcnt lgkmcnt(2)
	v_mfma_f32_16x16x32_bf16 v[154:157], v[246:249], v[2:5], v[154:157]
	s_waitcnt lgkmcnt(1)
	v_mfma_f32_16x16x32_bf16 v[150:153], v[38:41], v[2:5], v[150:153]
	s_waitcnt lgkmcnt(0)
	v_mfma_f32_16x16x32_bf16 v[2:5], v[42:45], v[2:5], v[18:21]
	v_mfma_f32_16x16x32_bf16 v[110:113], v[192:195], v[6:9], v[98:101]
	v_mfma_f32_16x16x32_bf16 v[106:109], v[246:249], v[6:9], v[126:129]
	v_mfma_f32_16x16x32_bf16 v[102:105], v[38:41], v[6:9], v[134:137]
	v_mfma_f32_16x16x32_bf16 v[98:101], v[42:45], v[6:9], v[22:25]
	v_mfma_f32_16x16x32_bf16 v[94:97], v[192:195], v[10:13], v[114:117]
	v_mfma_f32_16x16x32_bf16 v[90:93], v[246:249], v[10:13], v[122:125]
	v_mfma_f32_16x16x32_bf16 v[86:89], v[38:41], v[10:13], v[118:121]
	v_mfma_f32_16x16x32_bf16 v[82:85], v[42:45], v[10:13], v[26:29]
	v_mfma_f32_16x16x32_bf16 v[78:81], v[192:195], v[14:17], v[130:133]
	v_mfma_f32_16x16x32_bf16 v[74:77], v[246:249], v[14:17], v[138:141]
	v_mfma_f32_16x16x32_bf16 v[70:73], v[38:41], v[14:17], v[142:145]
	v_mfma_f32_16x16x32_bf16 v[66:69], v[42:45], v[14:17], v[30:33]
	v_mfma_f32_16x16x32_bf16 v[62:65], v[192:195], v[34:37], v[146:149]
	v_mfma_f32_16x16x32_bf16 v[58:61], v[246:249], v[34:37], v[206:209]
	v_mfma_f32_16x16x32_bf16 v[54:57], v[38:41], v[34:37], v[210:213]
	v_mfma_f32_16x16x32_bf16 v[50:53], v[42:45], v[34:37], v[164:167]
	v_mfma_f32_16x16x32_bf16 v[46:49], v[192:195], v[198:201], v[214:217]
	v_mfma_f32_16x16x32_bf16 v[128:131], v[246:249], v[198:201], v[218:221]
	v_mfma_f32_16x16x32_bf16 v[124:127], v[38:41], v[198:201], v[222:225]
	v_mfma_f32_16x16x32_bf16 v[34:37], v[42:45], v[198:201], v[168:171]
	v_mfma_f32_16x16x32_bf16 v[30:33], v[192:195], v[238:241], v[226:229]
	v_mfma_f32_16x16x32_bf16 v[26:29], v[246:249], v[238:241], v[230:233]
	v_mfma_f32_16x16x32_bf16 v[22:25], v[38:41], v[238:241], v[234:237]
	v_mfma_f32_16x16x32_bf16 v[18:21], v[42:45], v[238:241], v[172:175]
	v_mfma_f32_16x16x32_bf16 v[14:17], v[192:195], v[242:245], v[180:183]
	v_mfma_f32_16x16x32_bf16 v[10:13], v[246:249], v[242:245], v[184:187]
	v_mfma_f32_16x16x32_bf16 v[6:9], v[38:41], v[242:245], v[188:191]
	v_mfma_f32_16x16x32_bf16 v[38:41], v[42:45], v[242:245], v[176:179]
	s_setprio 0
	v_mov_b32_e32 v118, v196
	s_barrier
	s_movk_i32 s2, 0xff80
	v_ashrrev_i32_e32 v0, 1, v118
	v_and_b32_e32 v42, 15, v118
	v_and_or_b32 v121, v0, s2, v42
	v_bfe_u32 v119, v118, 6, 2
	v_lshrrev_b32_e32 v42, 2, v118
	v_add_u32_e32 v116, s6, v121
	v_lshlrev_b32_e32 v0, 6, v119
	v_and_b32_e32 v42, 12, v42
	v_ashrrev_i32_e32 v117, 31, v116
	v_readlane_b32 s2, v254, 51
	v_or3_b32 v114, v42, s13, v0
	v_lshlrev_b64 v[122:123], 12, v[116:117]
	v_readlane_b32 s3, v254, 52
	v_lshlrev_b32_e32 v0, 2, v114
	v_readlane_b32 s24, v251, 33
	v_lshl_add_u64 v[42:43], s[2:3], 0, v[122:123]
	v_lshl_add_u64 v[140:141], v[42:43], 0, v[0:1]
	v_lshlrev_b64 v[132:133], 11, v[116:117]
	v_readlane_b32 s26, v251, 35
	v_readlane_b32 s27, v251, 36
	v_mov_b32_e32 v115, v1
	v_lshlrev_b32_e32 v114, 1, v114
	v_lshl_add_u64 v[122:123], s[26:27], 0, v[122:123]
	v_lshl_add_u64 v[132:133], s[18:19], 0, v[132:133]
	v_lshl_add_u64 v[122:123], v[122:123], 0, v[0:1]
	v_lshl_add_u64 v[144:145], v[132:133], 0, v[114:115]
	v_and_b32_e32 v146, 63, v118
	v_lshlrev_b32_e32 v120, 2, v146
	v_xor_b32_e32 v117, 64, v120
	v_xor_b32_e32 v120, 0x80, v120
	v_cmp_gt_u32_e32 vcc, 16, v146
	v_readlane_b32 s25, v251, 34
	v_lshl_add_u32 v188, v119, 10, s7
	v_lshl_add_u32 v188, v121, 2, v188
	v_mov_b32_e32 v189, v117
	v_mov_b32_e32 v190, v120
	v_and_b32_e32 v240, 63, v118
	v_cmp_gt_u32_e64 s[88:89], 16, v240
	v_and_b32_e32 v243, 15, v118
	v_bfe_u32 v242, v118, 4, 2
	v_and_b32_e32 v240, 8, v243
	v_cmp_eq_u32_e64 s[90:91], 0, v240
	v_lshlrev_b32_e32 v236, 12, v243
	v_lshl_or_b32 v236, v242, 4, v236
	v_lshlrev_b32_e32 v237, 11, v243
	v_lshl_or_b32 v237, v242, 3, v237
	v_sub_co_u32_e32 v238, vcc, v140, v236
	v_subbrev_co_u32_e32 v239, vcc, 0, v141, vcc
	s_nop 0
	v_readfirstlane_b32 s40, v238
	v_readfirstlane_b32 s41, v239
	v_sub_co_u32_e32 v238, vcc, v122, v236
	v_subbrev_co_u32_e32 v239, vcc, 0, v123, vcc
	s_nop 0
	v_readfirstlane_b32 s44, v238
	v_readfirstlane_b32 s45, v239
	v_sub_co_u32_e32 v238, vcc, v144, v237
	v_subbrev_co_u32_e32 v239, vcc, 0, v145, vcc
	s_nop 0
	v_readfirstlane_b32 s48, v238
	v_readfirstlane_b32 s49, v239
	s_add_u32 s42, s40, 0x8000
	s_addc_u32 s43, s41, 0
	s_add_u32 s46, s44, 0x8000
	s_addc_u32 s47, s45, 0
	s_add_u32 s50, s48, 0x4000
	s_addc_u32 s51, s49, 0
	v_and_b32_e32 v238, 7, v243
	v_lshrrev_b32_e32 v239, 3, v243
	v_lshlrev_b32_e32 v244, 12, v238
	v_lshl_or_b32 v244, v239, 6, v244
	v_lshl_or_b32 v244, v242, 4, v244
	v_lshlrev_b32_e32 v245, 11, v238
	v_lshl_or_b32 v245, v239, 5, v245
	v_lshl_or_b32 v245, v242, 3, v245
	global_load_dwordx4 v[192:195], v244, s[40:41]
	global_load_dwordx4 v[198:201], v244, s[40:41] offset:128
	global_load_dwordx4 v[202:205], v244, s[42:43]
	global_load_dwordx4 v[206:209], v244, s[42:43] offset:128
	s_add_u32 s40, s40, 0x10000
	s_addc_u32 s41, s41, 0
	s_add_u32 s42, s42, 0x10000
	s_addc_u32 s43, s43, 0
	global_load_dwordx4 v[216:219], v244, s[40:41]
	global_load_dwordx4 v[220:223], v244, s[40:41] offset:128
	global_load_dwordx4 v[224:227], v244, s[42:43]
	global_load_dwordx4 v[228:231], v244, s[42:43] offset:128
	s_add_u32 s40, s40, 0x10000
	s_addc_u32 s41, s41, 0
	s_add_u32 s42, s42, 0x10000
	s_addc_u32 s43, s43, 0
	s_waitcnt vmcnt(4)
; DI void gemm8_epi_resid(f32x4 (&acc)[8][4], int m0, int n0, int ntile8, bf16_t* L, const float* xin, float* out, bf16_t* xb, float* rowpart) {
;     ...
;   for (int i = 0; i < 8; ++i) {
;     const int ml = wm * 128 + i * 16 + (lane & 15);
;     const size_t rowoff = (size_t)(m0 + ml) * DM;
;     float ss = 0.f;
; #pragma unroll
;     for (int j = 0; j < 4; ++j) {
;       const int n = n0 + wn * 64 + j * 16 + (lane >> 4) * 4;
;       const float4 xv = *(const float4*)(xin + rowoff + n);
;       const float o0 = xv.x + acc[i][j][0], o1 = xv.y + acc[i][j][1], o2 = xv.z + acc[i][j][2], o3 = xv.w + acc[i][j][3];
;       *(float4*)(out + rowoff + n) = make_float4(o0, o1, o2, o3);
;       ss += o0 * o0 + o1 * o1 + o2 * o2 + o3 * o3;
;       uint2 u;
;       u.x = pack2(o0, o1);
;       u.y = pack2(o2, o3);
;       *(uint2*)(xb + rowoff + n) = u;
;     }
;     ss += shx(ss, 16, lane);
;     ss += shx(ss, 32, lane);
;     if ((lane >> 4) == 0) red[wn * 256 + ml] = ss;
;   }
	v_mov_b32_dpp v232, v154 row_ror:8 row_mask:0xf bank_mask:0xf
	v_mov_b32_dpp v233, v155 row_ror:8 row_mask:0xf bank_mask:0xf
	v_mov_b32_dpp v234, v156 row_ror:8 row_mask:0xf bank_mask:0xf
	v_mov_b32_dpp v235, v157 row_ror:8 row_mask:0xf bank_mask:0xf
	v_cndmask_b32_e64 v232, v232, v158, s[90:91]
	v_cndmask_b32_e64 v233, v233, v159, s[90:91]
	v_cndmask_b32_e64 v234, v234, v160, s[90:91]
	v_cndmask_b32_e64 v235, v235, v161, s[90:91]
	v_pk_add_f32 v[232:233], v[232:233], v[192:193]
	v_pk_add_f32 v[234:235], v[234:235], v[194:195]
	s_nop 0
	global_store_dwordx4 v244, v[232:235], s[44:45]
	v_cvt_pk_bf16_f32 v240, v232, v233
	v_cvt_pk_bf16_f32 v241, v234, v235
	v_pk_mul_f32 v[236:237], v[232:233], v[232:233]
	v_pk_mul_f32 v[238:239], v[234:235], v[234:235]
	global_store_dwordx2 v245, v[240:241], s[48:49]
	v_add_f32_e32 v242, v236, v237
	v_add_f32_e32 v242, v242, v238
	v_add_f32_e32 v242, v242, v239
	v_mov_b32_dpp v232, v158 row_ror:8 row_mask:0xf bank_mask:0xf
	v_mov_b32_dpp v233, v159 row_ror:8 row_mask:0xf bank_mask:0xf
	v_mov_b32_dpp v234, v160 row_ror:8 row_mask:0xf bank_mask:0xf
	v_mov_b32_dpp v235, v161 row_ror:8 row_mask:0xf bank_mask:0xf
	v_cndmask_b32_e64 v232, v154, v232, s[90:91]
	v_cndmask_b32_e64 v233, v155, v233, s[90:91]
	v_cndmask_b32_e64 v234, v156, v234, s[90:91]
	v_cndmask_b32_e64 v235, v157, v235, s[90:91]
	v_pk_add_f32 v[232:233], v[232:233], v[202:203]
	v_pk_add_f32 v[234:235], v[234:235], v[204:205]
	s_nop 0
	global_store_dwordx4 v244, v[232:235], s[46:47]
	v_cvt_pk_bf16_f32 v240, v232, v233
	v_cvt_pk_bf16_f32 v241, v234, v235
	v_pk_mul_f32 v[236:237], v[232:233], v[232:233]
	v_pk_mul_f32 v[238:239], v[234:235], v[234:235]
	global_store_dwordx2 v245, v[240:241], s[50:51]
	v_add_f32_e32 v191, v236, v237
	v_add_f32_e32 v191, v191, v238
	v_add_f32_e32 v191, v191, v239
	v_mov_b32_dpp v232, v2 row_ror:8 row_mask:0xf bank_mask:0xf
	v_mov_b32_dpp v233, v3 row_ror:8 row_mask:0xf bank_mask:0xf
	v_mov_b32_dpp v234, v4 row_ror:8 row_mask:0xf bank_mask:0xf
	v_mov_b32_dpp v235, v5 row_ror:8 row_mask:0xf bank_mask:0xf
	v_cndmask_b32_e64 v232, v232, v150, s[90:91]
	v_cndmask_b32_e64 v233, v233, v151, s[90:91]
	v_cndmask_b32_e64 v234, v234, v152, s[90:91]
	v_cndmask_b32_e64 v235, v235, v153, s[90:91]
	v_pk_add_f32 v[232:233], v[232:233], v[198:199]
	v_pk_add_f32 v[234:235], v[234:235], v[200:201]
	s_nop 0
	global_store_dwordx4 v244, v[232:235], s[44:45] offset:128
	v_cvt_pk_bf16_f32 v240, v232, v233
	v_cvt_pk_bf16_f32 v241, v234, v235
	v_pk_mul_f32 v[236:237], v[232:233], v[232:233]
	v_pk_mul_f32 v[238:239], v[234:235], v[234:235]
	global_store_dwordx2 v245, v[240:241], s[48:49] offset:64
	v_add_f32_e32 v242, v242, v236
	v_add_f32_e32 v242, v242, v237
	v_add_f32_e32 v242, v242, v238
	v_add_f32_e32 v242, v242, v239
	v_mov_b32_dpp v232, v150 row_ror:8 row_mask:0xf bank_mask:0xf
	v_mov_b32_dpp v233, v151 row_ror:8 row_mask:0xf bank_mask:0xf
	v_mov_b32_dpp v234, v152 row_ror:8 row_mask:0xf bank_mask:0xf
	v_mov_b32_dpp v235, v153 row_ror:8 row_mask:0xf bank_mask:0xf
	v_cndmask_b32_e64 v232, v2, v232, s[90:91]
	v_cndmask_b32_e64 v233, v3, v233, s[90:91]
	v_cndmask_b32_e64 v234, v4, v234, s[90:91]
	v_cndmask_b32_e64 v235, v5, v235, s[90:91]
	v_pk_add_f32 v[232:233], v[232:233], v[206:207]
	v_pk_add_f32 v[234:235], v[234:235], v[208:209]
	s_nop 0
	global_store_dwordx4 v244, v[232:235], s[46:47] offset:128
	v_cvt_pk_bf16_f32 v240, v232, v233
	v_cvt_pk_bf16_f32 v241, v234, v235
	v_pk_mul_f32 v[236:237], v[232:233], v[232:233]
	v_pk_mul_f32 v[238:239], v[234:235], v[234:235]
	global_store_dwordx2 v245, v[240:241], s[50:51] offset:64
	v_add_f32_e32 v191, v191, v236
	v_add_f32_e32 v191, v191, v237
	v_add_f32_e32 v191, v191, v238
	v_add_f32_e32 v191, v191, v239
	s_nop 1
	v_add_f32_dpp v242, v242, v242 row_ror:8 row_mask:0xf bank_mask:0xf
	v_add_f32_dpp v191, v191, v191 row_ror:8 row_mask:0xf bank_mask:0xf
	s_add_u32 s44, s44, 0x10000
	s_addc_u32 s45, s45, 0
	s_add_u32 s46, s46, 0x10000
	s_addc_u32 s47, s47, 0
	s_add_u32 s48, s48, 0x8000
	s_addc_u32 s49, s49, 0
	s_add_u32 s50, s50, 0x8000
	s_addc_u32 s51, s51, 0
	v_cndmask_b32_e64 v242, v191, v242, s[90:91]
	ds_bpermute_b32 v243, v189, v242
	global_load_dwordx4 v[192:195], v244, s[40:41]
	global_load_dwordx4 v[198:201], v244, s[40:41] offset:128
	global_load_dwordx4 v[202:205], v244, s[42:43]
	global_load_dwordx4 v[206:209], v244, s[42:43] offset:128
	s_add_u32 s40, s40, 0x10000
	s_addc_u32 s41, s41, 0
	s_add_u32 s42, s42, 0x10000
	s_addc_u32 s43, s43, 0
	s_waitcnt lgkmcnt(0)
	v_add_f32_e32 v242, v242, v243
	ds_bpermute_b32 v243, v190, v242
	s_waitcnt lgkmcnt(0)
	v_add_f32_e32 v242, v242, v243
	s_and_saveexec_b64 s[2:3], s[88:89]
	ds_write_b32 v188, v242
	s_or_b64 exec, exec, s[2:3]
	s_waitcnt vmcnt(12)
; DI void gemm8_epi_resid(f32x4 (&acc)[8][4], int m0, int n0, int ntile8, bf16_t* L, const float* xin, float* out, bf16_t* xb, float* rowpart) {
;     ...
;   for (int i = 0; i < 8; ++i) {
;     const int ml = wm * 128 + i * 16 + (lane & 15);
;     const size_t rowoff = (size_t)(m0 + ml) * DM;
;     float ss = 0.f;
; #pragma unroll
;     for (int j = 0; j < 4; ++j) {
;       const int n = n0 + wn * 64 + j * 16 + (lane >> 4) * 4;
;       const float4 xv = *(const float4*)(xin + rowoff + n);
;       const float o0 = xv.x + acc[i][j][0], o1 = xv.y + acc[i][j][1], o2 = xv.z + acc[i][j][2], o3 = xv.w + acc[i][j][3];
;       *(float4*)(out + rowoff + n) = make_float4(o0, o1, o2, o3);
;       ss += o0 * o0 + o1 * o1 + o2 * o2 + o3 * o3;
;       uint2 u;
;       u.x = pack2(o0, o1);
;       u.y = pack2(o2, o3);
;       *(uint2*)(xb + rowoff + n) = u;
;     }
;     ss += shx(ss, 16, lane);
;     ss += shx(ss, 32, lane);
;     if ((lane >> 4) == 0) red[wn * 256 + ml] = ss;
;   }
	v_mov_b32_dpp v232, v106 row_ror:8 row_mask:0xf bank_mask:0xf
	v_mov_b32_dpp v233, v107 row_ror:8 row_mask:0xf bank_mask:0xf
	v_mov_b32_dpp v234, v108 row_ror:8 row_mask:0xf bank_mask:0xf
	v_mov_b32_dpp v235, v109 row_ror:8 row_mask:0xf bank_mask:0xf
	v_cndmask_b32_e64 v232, v232, v110, s[90:91]
	v_cndmask_b32_e64 v233, v233, v111, s[90:91]
	v_cndmask_b32_e64 v234, v234, v112, s[90:91]
	v_cndmask_b32_e64 v235, v235, v113, s[90:91]
	v_pk_add_f32 v[232:233], v[232:233], v[216:217]
	v_pk_add_f32 v[234:235], v[234:235], v[218:219]
	s_nop 0
	global_store_dwordx4 v244, v[232:235], s[44:45]
	v_cvt_pk_bf16_f32 v240, v232, v233
	v_cvt_pk_bf16_f32 v241, v234, v235
	v_pk_mul_f32 v[236:237], v[232:233], v[232:233]
	v_pk_mul_f32 v[238:239], v[234:235], v[234:235]
	global_store_dwordx2 v245, v[240:241], s[48:49]
	v_add_f32_e32 v242, v236, v237
	v_add_f32_e32 v242, v242, v238
	v_add_f32_e32 v242, v242, v239
	v_mov_b32_dpp v232, v110 row_ror:8 row_mask:0xf bank_mask:0xf
	v_mov_b32_dpp v233, v111 row_ror:8 row_mask:0xf bank_mask:0xf
	v_mov_b32_dpp v234, v112 row_ror:8 row_mask:0xf bank_mask:0xf
	v_mov_b32_dpp v235, v113 row_ror:8 row_mask:0xf bank_mask:0xf
	v_cndmask_b32_e64 v232, v106, v232, s[90:91]
	v_cndmask_b32_e64 v233, v107, v233, s[90:91]
	v_cndmask_b32_e64 v234, v108, v234, s[90:91]
	v_cndmask_b32_e64 v235, v109, v235, s[90:91]
	v_pk_add_f32 v[232:233], v[232:233], v[224:225]
	v_pk_add_f32 v[234:235], v[234:235], v[226:227]
	s_nop 0
	global_store_dwordx4 v244, v[232:235], s[46:47]
	v_cvt_pk_bf16_f32 v240, v232, v233
	v_cvt_pk_bf16_f32 v241, v234, v235
	v_pk_mul_f32 v[236:237], v[232:233], v[232:233]
	v_pk_mul_f32 v[238:239], v[234:235], v[234:235]
	global_store_dwordx2 v245, v[240:241], s[50:51]
	v_add_f32_e32 v191, v236, v237
	v_add_f32_e32 v191, v191, v238
	v_add_f32_e32 v191, v191, v239
	v_mov_b32_dpp v232, v98 row_ror:8 row_mask:0xf bank_mask:0xf
	v_mov_b32_dpp v233, v99 row_ror:8 row_mask:0xf bank_mask:0xf
	v_mov_b32_dpp v234, v100 row_ror:8 row_mask:0xf bank_mask:0xf
	v_mov_b32_dpp v235, v101 row_ror:8 row_mask:0xf bank_mask:0xf
	v_cndmask_b32_e64 v232, v232, v102, s[90:91]
	v_cndmask_b32_e64 v233, v233, v103, s[90:91]
	v_cndmask_b32_e64 v234, v234, v104, s[90:91]
	v_cndmask_b32_e64 v235, v235, v105, s[90:91]
	v_pk_add_f32 v[232:233], v[232:233], v[220:221]
	v_pk_add_f32 v[234:235], v[234:235], v[222:223]
	s_nop 0
	global_store_dwordx4 v244, v[232:235], s[44:45] offset:128
	v_cvt_pk_bf16_f32 v240, v232, v233
	v_cvt_pk_bf16_f32 v241, v234, v235
	v_pk_mul_f32 v[236:237], v[232:233], v[232:233]
	v_pk_mul_f32 v[238:239], v[234:235], v[234:235]
	global_store_dwordx2 v245, v[240:241], s[48:49] offset:64
	v_add_f32_e32 v242, v242, v236
	v_add_f32_e32 v242, v242, v237
	v_add_f32_e32 v242, v242, v238
	v_add_f32_e32 v242, v242, v239
	v_mov_b32_dpp v232, v102 row_ror:8 row_mask:0xf bank_mask:0xf
	v_mov_b32_dpp v233, v103 row_ror:8 row_mask:0xf bank_mask:0xf
	v_mov_b32_dpp v234, v104 row_ror:8 row_mask:0xf bank_mask:0xf
	v_mov_b32_dpp v235, v105 row_ror:8 row_mask:0xf bank_mask:0xf
	v_cndmask_b32_e64 v232, v98, v232, s[90:91]
	v_cndmask_b32_e64 v233, v99, v233, s[90:91]
	v_cndmask_b32_e64 v234, v100, v234, s[90:91]
	v_cndmask_b32_e64 v235, v101, v235, s[90:91]
	v_pk_add_f32 v[232:233], v[232:233], v[228:229]
	v_pk_add_f32 v[234:235], v[234:235], v[230:231]
	s_nop 0
	global_store_dwordx4 v244, v[232:235], s[46:47] offset:128
	v_cvt_pk_bf16_f32 v240, v232, v233
	v_cvt_pk_bf16_f32 v241, v234, v235
	v_pk_mul_f32 v[236:237], v[232:233], v[232:233]
	v_pk_mul_f32 v[238:239], v[234:235], v[234:235]
	global_store_dwordx2 v245, v[240:241], s[50:51] offset:64
	v_add_f32_e32 v191, v191, v236
	v_add_f32_e32 v191, v191, v237
	v_add_f32_e32 v191, v191, v238
	v_add_f32_e32 v191, v191, v239
	s_nop 1
	v_add_f32_dpp v242, v242, v242 row_ror:8 row_mask:0xf bank_mask:0xf
	v_add_f32_dpp v191, v191, v191 row_ror:8 row_mask:0xf bank_mask:0xf
	s_add_u32 s44, s44, 0x10000
	s_addc_u32 s45, s45, 0
	s_add_u32 s46, s46, 0x10000
	s_addc_u32 s47, s47, 0
	s_add_u32 s48, s48, 0x8000
	s_addc_u32 s49, s49, 0
	s_add_u32 s50, s50, 0x8000
	s_addc_u32 s51, s51, 0
	v_cndmask_b32_e64 v242, v191, v242, s[90:91]
	ds_bpermute_b32 v243, v189, v242
	global_load_dwordx4 v[216:219], v244, s[40:41]
	global_load_dwordx4 v[220:223], v244, s[40:41] offset:128
	global_load_dwordx4 v[224:227], v244, s[42:43]
	global_load_dwordx4 v[228:231], v244, s[42:43] offset:128
	s_add_u32 s40, s40, 0x10000
	s_addc_u32 s41, s41, 0
	s_add_u32 s42, s42, 0x10000
	s_addc_u32 s43, s43, 0
	s_waitcnt lgkmcnt(0)
	v_add_f32_e32 v242, v242, v243
	ds_bpermute_b32 v243, v190, v242
	s_waitcnt lgkmcnt(0)
	v_add_f32_e32 v242, v242, v243
	s_and_saveexec_b64 s[2:3], s[88:89]
	ds_write_b32 v188, v242 offset:64
	s_or_b64 exec, exec, s[2:3]
	s_waitcnt vmcnt(12)
; DI void gemm8_epi_resid(f32x4 (&acc)[8][4], int m0, int n0, int ntile8, bf16_t* L, const float* xin, float* out, bf16_t* xb, float* rowpart) {
;     ...
;   for (int i = 0; i < 8; ++i) {
;     const int ml = wm * 128 + i * 16 + (lane & 15);
;     const size_t rowoff = (size_t)(m0 + ml) * DM;
;     float ss = 0.f;
; #pragma unroll
;     for (int j = 0; j < 4; ++j) {
;       const int n = n0 + wn * 64 + j * 16 + (lane >> 4) * 4;
;       const float4 xv = *(const float4*)(xin + rowoff + n);
;       const float o0 = xv.x + acc[i][j][0], o1 = xv.y + acc[i][j][1], o2 = xv.z + acc[i][j][2], o3 = xv.w + acc[i][j][3];
;       *(float4*)(out + rowoff + n) = make_float4(o0, o1, o2, o3);
;       ss += o0 * o0 + o1 * o1 + o2 * o2 + o3 * o3;
;       uint2 u;
;       u.x = pack2(o0, o1);
;       u.y = pack2(o2, o3);
;       *(uint2*)(xb + rowoff + n) = u;
;     }
;     ss += shx(ss, 16, lane);
;     ss += shx(ss, 32, lane);
;     if ((lane >> 4) == 0) red[wn * 256 + ml] = ss;
;   }
	v_mov_b32_dpp v232, v90 row_ror:8 row_mask:0xf bank_mask:0xf
	v_mov_b32_dpp v233, v91 row_ror:8 row_mask:0xf bank_mask:0xf
	v_mov_b32_dpp v234, v92 row_ror:8 row_mask:0xf bank_mask:0xf
	v_mov_b32_dpp v235, v93 row_ror:8 row_mask:0xf bank_mask:0xf
	v_cndmask_b32_e64 v232, v232, v94, s[90:91]
	v_cndmask_b32_e64 v233, v233, v95, s[90:91]
	v_cndmask_b32_e64 v234, v234, v96, s[90:91]
	v_cndmask_b32_e64 v235, v235, v97, s[90:91]
	v_pk_add_f32 v[232:233], v[232:233], v[192:193]
	v_pk_add_f32 v[234:235], v[234:235], v[194:195]
	s_nop 0
	global_store_dwordx4 v244, v[232:235], s[44:45]
	v_cvt_pk_bf16_f32 v240, v232, v233
	v_cvt_pk_bf16_f32 v241, v234, v235
	v_pk_mul_f32 v[236:237], v[232:233], v[232:233]
	v_pk_mul_f32 v[238:239], v[234:235], v[234:235]
	global_store_dwordx2 v245, v[240:241], s[48:49]
	v_add_f32_e32 v242, v236, v237
	v_add_f32_e32 v242, v242, v238
	v_add_f32_e32 v242, v242, v239
	v_mov_b32_dpp v232, v94 row_ror:8 row_mask:0xf bank_mask:0xf
	v_mov_b32_dpp v233, v95 row_ror:8 row_mask:0xf bank_mask:0xf
	v_mov_b32_dpp v234, v96 row_ror:8 row_mask:0xf bank_mask:0xf
	v_mov_b32_dpp v235, v97 row_ror:8 row_mask:0xf bank_mask:0xf
	v_cndmask_b32_e64 v232, v90, v232, s[90:91]
	v_cndmask_b32_e64 v233, v91, v233, s[90:91]
	v_cndmask_b32_e64 v234, v92, v234, s[90:91]
	v_cndmask_b32_e64 v235, v93, v235, s[90:91]
	v_pk_add_f32 v[232:233], v[232:233], v[202:203]
	v_pk_add_f32 v[234:235], v[234:235], v[204:205]
	s_nop 0
	global_store_dwordx4 v244, v[232:235], s[46:47]
	v_cvt_pk_bf16_f32 v240, v232, v233
	v_cvt_pk_bf16_f32 v241, v234, v235
	v_pk_mul_f32 v[236:237], v[232:233], v[232:233]
	v_pk_mul_f32 v[238:239], v[234:235], v[234:235]
	global_store_dwordx2 v245, v[240:241], s[50:51]
	v_add_f32_e32 v191, v236, v237
	v_add_f32_e32 v191, v191, v238
	v_add_f32_e32 v191, v191, v239
	v_mov_b32_dpp v232, v82 row_ror:8 row_mask:0xf bank_mask:0xf
	v_mov_b32_dpp v233, v83 row_ror:8 row_mask:0xf bank_mask:0xf
	v_mov_b32_dpp v234, v84 row_ror:8 row_mask:0xf bank_mask:0xf
	v_mov_b32_dpp v235, v85 row_ror:8 row_mask:0xf bank_mask:0xf
	v_cndmask_b32_e64 v232, v232, v86, s[90:91]
	v_cndmask_b32_e64 v233, v233, v87, s[90:91]
	v_cndmask_b32_e64 v234, v234, v88, s[90:91]
	v_cndmask_b32_e64 v235, v235, v89, s[90:91]
	v_pk_add_f32 v[232:233], v[232:233], v[198:199]
	v_pk_add_f32 v[234:235], v[234:235], v[200:201]
	s_nop 0
	global_store_dwordx4 v244, v[232:235], s[44:45] offset:128
	v_cvt_pk_bf16_f32 v240, v232, v233
	v_cvt_pk_bf16_f32 v241, v234, v235
	v_pk_mul_f32 v[236:237], v[232:233], v[232:233]
	v_pk_mul_f32 v[238:239], v[234:235], v[234:235]
	global_store_dwordx2 v245, v[240:241], s[48:49] offset:64
	v_add_f32_e32 v242, v242, v236
	v_add_f32_e32 v242, v242, v237
	v_add_f32_e32 v242, v242, v238
	v_add_f32_e32 v242, v242, v239
	v_mov_b32_dpp v232, v86 row_ror:8 row_mask:0xf bank_mask:0xf
	v_mov_b32_dpp v233, v87 row_ror:8 row_mask:0xf bank_mask:0xf
	v_mov_b32_dpp v234, v88 row_ror:8 row_mask:0xf bank_mask:0xf
	v_mov_b32_dpp v235, v89 row_ror:8 row_mask:0xf bank_mask:0xf
	v_cndmask_b32_e64 v232, v82, v232, s[90:91]
	v_cndmask_b32_e64 v233, v83, v233, s[90:91]
	v_cndmask_b32_e64 v234, v84, v234, s[90:91]
	v_cndmask_b32_e64 v235, v85, v235, s[90:91]
	v_pk_add_f32 v[232:233], v[232:233], v[206:207]
	v_pk_add_f32 v[234:235], v[234:235], v[208:209]
	s_nop 0
	global_store_dwordx4 v244, v[232:235], s[46:47] offset:128
	v_cvt_pk_bf16_f32 v240, v232, v233
	v_cvt_pk_bf16_f32 v241, v234, v235
	v_pk_mul_f32 v[236:237], v[232:233], v[232:233]
	v_pk_mul_f32 v[238:239], v[234:235], v[234:235]
	global_store_dwordx2 v245, v[240:241], s[50:51] offset:64
	v_add_f32_e32 v191, v191, v236
	v_add_f32_e32 v191, v191, v237
	v_add_f32_e32 v191, v191, v238
	v_add_f32_e32 v191, v191, v239
	s_nop 1
	v_add_f32_dpp v242, v242, v242 row_ror:8 row_mask:0xf bank_mask:0xf
	v_add_f32_dpp v191, v191, v191 row_ror:8 row_mask:0xf bank_mask:0xf
	s_add_u32 s44, s44, 0x10000
	s_addc_u32 s45, s45, 0
	s_add_u32 s46, s46, 0x10000
	s_addc_u32 s47, s47, 0
	s_add_u32 s48, s48, 0x8000
	s_addc_u32 s49, s49, 0
	s_add_u32 s50, s50, 0x8000
	s_addc_u32 s51, s51, 0
	v_cndmask_b32_e64 v242, v191, v242, s[90:91]
	ds_bpermute_b32 v243, v189, v242
	global_load_dwordx4 v[192:195], v244, s[40:41]
	global_load_dwordx4 v[198:201], v244, s[40:41] offset:128
	global_load_dwordx4 v[202:205], v244, s[42:43]
	global_load_dwordx4 v[206:209], v244, s[42:43] offset:128
	s_add_u32 s40, s40, 0x10000
	s_addc_u32 s41, s41, 0
	s_add_u32 s42, s42, 0x10000
	s_addc_u32 s43, s43, 0
	s_waitcnt lgkmcnt(0)
	v_add_f32_e32 v242, v242, v243
	ds_bpermute_b32 v243, v190, v242
	s_waitcnt lgkmcnt(0)
	v_add_f32_e32 v242, v242, v243
	s_and_saveexec_b64 s[2:3], s[88:89]
	ds_write_b32 v188, v242 offset:128
	s_or_b64 exec, exec, s[2:3]
	s_waitcnt vmcnt(12)
; DI void gemm8_epi_resid(f32x4 (&acc)[8][4], int m0, int n0, int ntile8, bf16_t* L, const float* xin, float* out, bf16_t* xb, float* rowpart) {
;     ...
;   for (int i = 0; i < 8; ++i) {
;     const int ml = wm * 128 + i * 16 + (lane & 15);
;     const size_t rowoff = (size_t)(m0 + ml) * DM;
;     float ss = 0.f;
; #pragma unroll
;     for (int j = 0; j < 4; ++j) {
;       const int n = n0 + wn * 64 + j * 16 + (lane >> 4) * 4;
;       const float4 xv = *(const float4*)(xin + rowoff + n);
;       const float o0 = xv.x + acc[i][j][0], o1 = xv.y + acc[i][j][1], o2 = xv.z + acc[i][j][2], o3 = xv.w + acc[i][j][3];
;       *(float4*)(out + rowoff + n) = make_float4(o0, o1, o2, o3);
;       ss += o0 * o0 + o1 * o1 + o2 * o2 + o3 * o3;
;       uint2 u;
;       u.x = pack2(o0, o1);
;       u.y = pack2(o2, o3);
;       *(uint2*)(xb + rowoff + n) = u;
;     }
;     ss += shx(ss, 16, lane);
;     ss += shx(ss, 32, lane);
;     if ((lane >> 4) == 0) red[wn * 256 + ml] = ss;
;   }
	v_mov_b32_dpp v232, v74 row_ror:8 row_mask:0xf bank_mask:0xf
	v_mov_b32_dpp v233, v75 row_ror:8 row_mask:0xf bank_mask:0xf
	v_mov_b32_dpp v234, v76 row_ror:8 row_mask:0xf bank_mask:0xf
	v_mov_b32_dpp v235, v77 row_ror:8 row_mask:0xf bank_mask:0xf
	v_cndmask_b32_e64 v232, v232, v78, s[90:91]
	v_cndmask_b32_e64 v233, v233, v79, s[90:91]
	v_cndmask_b32_e64 v234, v234, v80, s[90:91]
	v_cndmask_b32_e64 v235, v235, v81, s[90:91]
	v_pk_add_f32 v[232:233], v[232:233], v[216:217]
	v_pk_add_f32 v[234:235], v[234:235], v[218:219]
	s_nop 0
	global_store_dwordx4 v244, v[232:235], s[44:45]
	v_cvt_pk_bf16_f32 v240, v232, v233
	v_cvt_pk_bf16_f32 v241, v234, v235
	v_pk_mul_f32 v[236:237], v[232:233], v[232:233]
	v_pk_mul_f32 v[238:239], v[234:235], v[234:235]
	global_store_dwordx2 v245, v[240:241], s[48:49]
	v_add_f32_e32 v242, v236, v237
	v_add_f32_e32 v242, v242, v238
	v_add_f32_e32 v242, v242, v239
	v_mov_b32_dpp v232, v78 row_ror:8 row_mask:0xf bank_mask:0xf
	v_mov_b32_dpp v233, v79 row_ror:8 row_mask:0xf bank_mask:0xf
	v_mov_b32_dpp v234, v80 row_ror:8 row_mask:0xf bank_mask:0xf
	v_mov_b32_dpp v235, v81 row_ror:8 row_mask:0xf bank_mask:0xf
	v_cndmask_b32_e64 v232, v74, v232, s[90:91]
	v_cndmask_b32_e64 v233, v75, v233, s[90:91]
	v_cndmask_b32_e64 v234, v76, v234, s[90:91]
	v_cndmask_b32_e64 v235, v77, v235, s[90:91]
	v_pk_add_f32 v[232:233], v[232:233], v[224:225]
	v_pk_add_f32 v[234:235], v[234:235], v[226:227]
	s_nop 0
	global_store_dwordx4 v244, v[232:235], s[46:47]
	v_cvt_pk_bf16_f32 v240, v232, v233
	v_cvt_pk_bf16_f32 v241, v234, v235
	v_pk_mul_f32 v[236:237], v[232:233], v[232:233]
	v_pk_mul_f32 v[238:239], v[234:235], v[234:235]
	global_store_dwordx2 v245, v[240:241], s[50:51]
	v_add_f32_e32 v191, v236, v237
	v_add_f32_e32 v191, v191, v238
	v_add_f32_e32 v191, v191, v239
	v_mov_b32_dpp v232, v66 row_ror:8 row_mask:0xf bank_mask:0xf
	v_mov_b32_dpp v233, v67 row_ror:8 row_mask:0xf bank_mask:0xf
	v_mov_b32_dpp v234, v68 row_ror:8 row_mask:0xf bank_mask:0xf
	v_mov_b32_dpp v235, v69 row_ror:8 row_mask:0xf bank_mask:0xf
	v_cndmask_b32_e64 v232, v232, v70, s[90:91]
	v_cndmask_b32_e64 v233, v233, v71, s[90:91]
	v_cndmask_b32_e64 v234, v234, v72, s[90:91]
	v_cndmask_b32_e64 v235, v235, v73, s[90:91]
	v_pk_add_f32 v[232:233], v[232:233], v[220:221]
	v_pk_add_f32 v[234:235], v[234:235], v[222:223]
	s_nop 0
	global_store_dwordx4 v244, v[232:235], s[44:45] offset:128
	v_cvt_pk_bf16_f32 v240, v232, v233
	v_cvt_pk_bf16_f32 v241, v234, v235
	v_pk_mul_f32 v[236:237], v[232:233], v[232:233]
	v_pk_mul_f32 v[238:239], v[234:235], v[234:235]
	global_store_dwordx2 v245, v[240:241], s[48:49] offset:64
	v_add_f32_e32 v242, v242, v236
	v_add_f32_e32 v242, v242, v237
	v_add_f32_e32 v242, v242, v238
	v_add_f32_e32 v242, v242, v239
	v_mov_b32_dpp v232, v70 row_ror:8 row_mask:0xf bank_mask:0xf
	v_mov_b32_dpp v233, v71 row_ror:8 row_mask:0xf bank_mask:0xf
	v_mov_b32_dpp v234, v72 row_ror:8 row_mask:0xf bank_mask:0xf
	v_mov_b32_dpp v235, v73 row_ror:8 row_mask:0xf bank_mask:0xf
	v_cndmask_b32_e64 v232, v66, v232, s[90:91]
	v_cndmask_b32_e64 v233, v67, v233, s[90:91]
	v_cndmask_b32_e64 v234, v68, v234, s[90:91]
	v_cndmask_b32_e64 v235, v69, v235, s[90:91]
	v_pk_add_f32 v[232:233], v[232:233], v[228:229]
	v_pk_add_f32 v[234:235], v[234:235], v[230:231]
	s_nop 0
	global_store_dwordx4 v244, v[232:235], s[46:47] offset:128
	v_cvt_pk_bf16_f32 v240, v232, v233
	v_cvt_pk_bf16_f32 v241, v234, v235
	v_pk_mul_f32 v[236:237], v[232:233], v[232:233]
	v_pk_mul_f32 v[238:239], v[234:235], v[234:235]
	global_store_dwordx2 v245, v[240:241], s[50:51] offset:64
	v_add_f32_e32 v191, v191, v236
	v_add_f32_e32 v191, v191, v237
	v_add_f32_e32 v191, v191, v238
	v_add_f32_e32 v191, v191, v239
	s_nop 1
	v_add_f32_dpp v242, v242, v242 row_ror:8 row_mask:0xf bank_mask:0xf
	v_add_f32_dpp v191, v191, v191 row_ror:8 row_mask:0xf bank_mask:0xf
	s_add_u32 s44, s44, 0x10000
	s_addc_u32 s45, s45, 0
	s_add_u32 s46, s46, 0x10000
	s_addc_u32 s47, s47, 0
	s_add_u32 s48, s48, 0x8000
	s_addc_u32 s49, s49, 0
	s_add_u32 s50, s50, 0x8000
	s_addc_u32 s51, s51, 0
	v_cndmask_b32_e64 v242, v191, v242, s[90:91]
	ds_bpermute_b32 v243, v189, v242
	global_load_dwordx4 v[216:219], v244, s[40:41]
	global_load_dwordx4 v[220:223], v244, s[40:41] offset:128
	global_load_dwordx4 v[224:227], v244, s[42:43]
	global_load_dwordx4 v[228:231], v244, s[42:43] offset:128
	s_add_u32 s40, s40, 0x10000
	s_addc_u32 s41, s41, 0
	s_add_u32 s42, s42, 0x10000
	s_addc_u32 s43, s43, 0
	s_waitcnt lgkmcnt(0)
	v_add_f32_e32 v242, v242, v243
	ds_bpermute_b32 v243, v190, v242
	s_waitcnt lgkmcnt(0)
	v_add_f32_e32 v242, v242, v243
	s_and_saveexec_b64 s[2:3], s[88:89]
	ds_write_b32 v188, v242 offset:192
	s_or_b64 exec, exec, s[2:3]
	s_waitcnt vmcnt(12)
; DI void gemm8_epi_resid(f32x4 (&acc)[8][4], int m0, int n0, int ntile8, bf16_t* L, const float* xin, float* out, bf16_t* xb, float* rowpart) {
;     ...
;   for (int i = 0; i < 8; ++i) {
;     const int ml = wm * 128 + i * 16 + (lane & 15);
;     const size_t rowoff = (size_t)(m0 + ml) * DM;
;     float ss = 0.f;
; #pragma unroll
;     for (int j = 0; j < 4; ++j) {
;       const int n = n0 + wn * 64 + j * 16 + (lane >> 4) * 4;
;       const float4 xv = *(const float4*)(xin + rowoff + n);
;       const float o0 = xv.x + acc[i][j][0], o1 = xv.y + acc[i][j][1], o2 = xv.z + acc[i][j][2], o3 = xv.w + acc[i][j][3];
;       *(float4*)(out + rowoff + n) = make_float4(o0, o1, o2, o3);
;       ss += o0 * o0 + o1 * o1 + o2 * o2 + o3 * o3;
;       uint2 u;
;       u.x = pack2(o0, o1);
;       u.y = pack2(o2, o3);
;       *(uint2*)(xb + rowoff + n) = u;
;     }
;     ss += shx(ss, 16, lane);
;     ss += shx(ss, 32, lane);
;     if ((lane >> 4) == 0) red[wn * 256 + ml] = ss;
;   }
	v_mov_b32_dpp v232, v58 row_ror:8 row_mask:0xf bank_mask:0xf
	v_mov_b32_dpp v233, v59 row_ror:8 row_mask:0xf bank_mask:0xf
	v_mov_b32_dpp v234, v60 row_ror:8 row_mask:0xf bank_mask:0xf
	v_mov_b32_dpp v235, v61 row_ror:8 row_mask:0xf bank_mask:0xf
	v_cndmask_b32_e64 v232, v232, v62, s[90:91]
	v_cndmask_b32_e64 v233, v233, v63, s[90:91]
	v_cndmask_b32_e64 v234, v234, v64, s[90:91]
	v_cndmask_b32_e64 v235, v235, v65, s[90:91]
	v_pk_add_f32 v[232:233], v[232:233], v[192:193]
	v_pk_add_f32 v[234:235], v[234:235], v[194:195]
	s_nop 0
	global_store_dwordx4 v244, v[232:235], s[44:45]
	v_cvt_pk_bf16_f32 v240, v232, v233
	v_cvt_pk_bf16_f32 v241, v234, v235
	v_pk_mul_f32 v[236:237], v[232:233], v[232:233]
	v_pk_mul_f32 v[238:239], v[234:235], v[234:235]
	global_store_dwordx2 v245, v[240:241], s[48:49]
	v_add_f32_e32 v242, v236, v237
	v_add_f32_e32 v242, v242, v238
	v_add_f32_e32 v242, v242, v239
	v_mov_b32_dpp v232, v62 row_ror:8 row_mask:0xf bank_mask:0xf
	v_mov_b32_dpp v233, v63 row_ror:8 row_mask:0xf bank_mask:0xf
	v_mov_b32_dpp v234, v64 row_ror:8 row_mask:0xf bank_mask:0xf
	v_mov_b32_dpp v235, v65 row_ror:8 row_mask:0xf bank_mask:0xf
	v_cndmask_b32_e64 v232, v58, v232, s[90:91]
	v_cndmask_b32_e64 v233, v59, v233, s[90:91]
	v_cndmask_b32_e64 v234, v60, v234, s[90:91]
	v_cndmask_b32_e64 v235, v61, v235, s[90:91]
	v_pk_add_f32 v[232:233], v[232:233], v[202:203]
	v_pk_add_f32 v[234:235], v[234:235], v[204:205]
	s_nop 0
	global_store_dwordx4 v244, v[232:235], s[46:47]
	v_cvt_pk_bf16_f32 v240, v232, v233
	v_cvt_pk_bf16_f32 v241, v234, v235
	v_pk_mul_f32 v[236:237], v[232:233], v[232:233]
	v_pk_mul_f32 v[238:239], v[234:235], v[234:235]
	global_store_dwordx2 v245, v[240:241], s[50:51]
	v_add_f32_e32 v191, v236, v237
	v_add_f32_e32 v191, v191, v238
	v_add_f32_e32 v191, v191, v239
	v_mov_b32_dpp v232, v50 row_ror:8 row_mask:0xf bank_mask:0xf
	v_mov_b32_dpp v233, v51 row_ror:8 row_mask:0xf bank_mask:0xf
	v_mov_b32_dpp v234, v52 row_ror:8 row_mask:0xf bank_mask:0xf
	v_mov_b32_dpp v235, v53 row_ror:8 row_mask:0xf bank_mask:0xf
	v_cndmask_b32_e64 v232, v232, v54, s[90:91]
	v_cndmask_b32_e64 v233, v233, v55, s[90:91]
	v_cndmask_b32_e64 v234, v234, v56, s[90:91]
	v_cndmask_b32_e64 v235, v235, v57, s[90:91]
	v_pk_add_f32 v[232:233], v[232:233], v[198:199]
	v_pk_add_f32 v[234:235], v[234:235], v[200:201]
	s_nop 0
	global_store_dwordx4 v244, v[232:235], s[44:45] offset:128
	v_cvt_pk_bf16_f32 v240, v232, v233
	v_cvt_pk_bf16_f32 v241, v234, v235
	v_pk_mul_f32 v[236:237], v[232:233], v[232:233]
	v_pk_mul_f32 v[238:239], v[234:235], v[234:235]
	global_store_dwordx2 v245, v[240:241], s[48:49] offset:64
	v_add_f32_e32 v242, v242, v236
	v_add_f32_e32 v242, v242, v237
	v_add_f32_e32 v242, v242, v238
	v_add_f32_e32 v242, v242, v239
	v_mov_b32_dpp v232, v54 row_ror:8 row_mask:0xf bank_mask:0xf
	v_mov_b32_dpp v233, v55 row_ror:8 row_mask:0xf bank_mask:0xf
	v_mov_b32_dpp v234, v56 row_ror:8 row_mask:0xf bank_mask:0xf
	v_mov_b32_dpp v235, v57 row_ror:8 row_mask:0xf bank_mask:0xf
	v_cndmask_b32_e64 v232, v50, v232, s[90:91]
	v_cndmask_b32_e64 v233, v51, v233, s[90:91]
	v_cndmask_b32_e64 v234, v52, v234, s[90:91]
	v_cndmask_b32_e64 v235, v53, v235, s[90:91]
	v_pk_add_f32 v[232:233], v[232:233], v[206:207]
	v_pk_add_f32 v[234:235], v[234:235], v[208:209]
	s_nop 0
	global_store_dwordx4 v244, v[232:235], s[46:47] offset:128
	v_cvt_pk_bf16_f32 v240, v232, v233
	v_cvt_pk_bf16_f32 v241, v234, v235
	v_pk_mul_f32 v[236:237], v[232:233], v[232:233]
	v_pk_mul_f32 v[238:239], v[234:235], v[234:235]
	global_store_dwordx2 v245, v[240:241], s[50:51] offset:64
	v_add_f32_e32 v191, v191, v236
	v_add_f32_e32 v191, v191, v237
	v_add_f32_e32 v191, v191, v238
	v_add_f32_e32 v191, v191, v239
	s_nop 1
	v_add_f32_dpp v242, v242, v242 row_ror:8 row_mask:0xf bank_mask:0xf
	v_add_f32_dpp v191, v191, v191 row_ror:8 row_mask:0xf bank_mask:0xf
	s_add_u32 s44, s44, 0x10000
	s_addc_u32 s45, s45, 0
	s_add_u32 s46, s46, 0x10000
	s_addc_u32 s47, s47, 0
	s_add_u32 s48, s48, 0x8000
	s_addc_u32 s49, s49, 0
	s_add_u32 s50, s50, 0x8000
	s_addc_u32 s51, s51, 0
	v_cndmask_b32_e64 v242, v191, v242, s[90:91]
	ds_bpermute_b32 v243, v189, v242
	global_load_dwordx4 v[192:195], v244, s[40:41]
	global_load_dwordx4 v[198:201], v244, s[40:41] offset:128
	global_load_dwordx4 v[202:205], v244, s[42:43]
	global_load_dwordx4 v[206:209], v244, s[42:43] offset:128
	s_add_u32 s40, s40, 0x10000
	s_addc_u32 s41, s41, 0
	s_add_u32 s42, s42, 0x10000
	s_addc_u32 s43, s43, 0
	s_waitcnt lgkmcnt(0)
	v_add_f32_e32 v242, v242, v243
	ds_bpermute_b32 v243, v190, v242
	s_waitcnt lgkmcnt(0)
	v_add_f32_e32 v242, v242, v243
	s_and_saveexec_b64 s[2:3], s[88:89]
	ds_write_b32 v188, v242 offset:256
	s_or_b64 exec, exec, s[2:3]
	s_waitcnt vmcnt(12)
; DI void gemm8_epi_resid(f32x4 (&acc)[8][4], int m0, int n0, int ntile8, bf16_t* L, const float* xin, float* out, bf16_t* xb, float* rowpart) {
;     ...
;   for (int i = 0; i < 8; ++i) {
;     const int ml = wm * 128 + i * 16 + (lane & 15);
;     const size_t rowoff = (size_t)(m0 + ml) * DM;
;     float ss = 0.f;
; #pragma unroll
;     for (int j = 0; j < 4; ++j) {
;       const int n = n0 + wn * 64 + j * 16 + (lane >> 4) * 4;
;       const float4 xv = *(const float4*)(xin + rowoff + n);
;       const float o0 = xv.x + acc[i][j][0], o1 = xv.y + acc[i][j][1], o2 = xv.z + acc[i][j][2], o3 = xv.w + acc[i][j][3];
;       *(float4*)(out + rowoff + n) = make_float4(o0, o1, o2, o3);
;       ss += o0 * o0 + o1 * o1 + o2 * o2 + o3 * o3;
;       uint2 u;
;       u.x = pack2(o0, o1);
;       u.y = pack2(o2, o3);
;       *(uint2*)(xb + rowoff + n) = u;
;     }
;     ss += shx(ss, 16, lane);
;     ss += shx(ss, 32, lane);
;     if ((lane >> 4) == 0) red[wn * 256 + ml] = ss;
;   }
	v_mov_b32_dpp v232, v128 row_ror:8 row_mask:0xf bank_mask:0xf
	v_mov_b32_dpp v233, v129 row_ror:8 row_mask:0xf bank_mask:0xf
	v_mov_b32_dpp v234, v130 row_ror:8 row_mask:0xf bank_mask:0xf
	v_mov_b32_dpp v235, v131 row_ror:8 row_mask:0xf bank_mask:0xf
	v_cndmask_b32_e64 v232, v232, v46, s[90:91]
	v_cndmask_b32_e64 v233, v233, v47, s[90:91]
	v_cndmask_b32_e64 v234, v234, v48, s[90:91]
	v_cndmask_b32_e64 v235, v235, v49, s[90:91]
	v_pk_add_f32 v[232:233], v[232:233], v[216:217]
	v_pk_add_f32 v[234:235], v[234:235], v[218:219]
	s_nop 0
	global_store_dwordx4 v244, v[232:235], s[44:45]
	v_cvt_pk_bf16_f32 v240, v232, v233
	v_cvt_pk_bf16_f32 v241, v234, v235
	v_pk_mul_f32 v[236:237], v[232:233], v[232:233]
	v_pk_mul_f32 v[238:239], v[234:235], v[234:235]
	global_store_dwordx2 v245, v[240:241], s[48:49]
	v_add_f32_e32 v242, v236, v237
	v_add_f32_e32 v242, v242, v238
	v_add_f32_e32 v242, v242, v239
	v_mov_b32_dpp v232, v46 row_ror:8 row_mask:0xf bank_mask:0xf
	v_mov_b32_dpp v233, v47 row_ror:8 row_mask:0xf bank_mask:0xf
	v_mov_b32_dpp v234, v48 row_ror:8 row_mask:0xf bank_mask:0xf
	v_mov_b32_dpp v235, v49 row_ror:8 row_mask:0xf bank_mask:0xf
	v_cndmask_b32_e64 v232, v128, v232, s[90:91]
	v_cndmask_b32_e64 v233, v129, v233, s[90:91]
	v_cndmask_b32_e64 v234, v130, v234, s[90:91]
	v_cndmask_b32_e64 v235, v131, v235, s[90:91]
	v_pk_add_f32 v[232:233], v[232:233], v[224:225]
	v_pk_add_f32 v[234:235], v[234:235], v[226:227]
	s_nop 0
	global_store_dwordx4 v244, v[232:235], s[46:47]
	v_cvt_pk_bf16_f32 v240, v232, v233
	v_cvt_pk_bf16_f32 v241, v234, v235
	v_pk_mul_f32 v[236:237], v[232:233], v[232:233]
	v_pk_mul_f32 v[238:239], v[234:235], v[234:235]
	global_store_dwordx2 v245, v[240:241], s[50:51]
	v_add_f32_e32 v191, v236, v237
	v_add_f32_e32 v191, v191, v238
	v_add_f32_e32 v191, v191, v239
	v_mov_b32_dpp v232, v34 row_ror:8 row_mask:0xf bank_mask:0xf
	v_mov_b32_dpp v233, v35 row_ror:8 row_mask:0xf bank_mask:0xf
	v_mov_b32_dpp v234, v36 row_ror:8 row_mask:0xf bank_mask:0xf
	v_mov_b32_dpp v235, v37 row_ror:8 row_mask:0xf bank_mask:0xf
	v_cndmask_b32_e64 v232, v232, v124, s[90:91]
	v_cndmask_b32_e64 v233, v233, v125, s[90:91]
	v_cndmask_b32_e64 v234, v234, v126, s[90:91]
	v_cndmask_b32_e64 v235, v235, v127, s[90:91]
	v_pk_add_f32 v[232:233], v[232:233], v[220:221]
	v_pk_add_f32 v[234:235], v[234:235], v[222:223]
	s_nop 0
	global_store_dwordx4 v244, v[232:235], s[44:45] offset:128
	v_cvt_pk_bf16_f32 v240, v232, v233
	v_cvt_pk_bf16_f32 v241, v234, v235
	v_pk_mul_f32 v[236:237], v[232:233], v[232:233]
	v_pk_mul_f32 v[238:239], v[234:235], v[234:235]
	global_store_dwordx2 v245, v[240:241], s[48:49] offset:64
	v_add_f32_e32 v242, v242, v236
	v_add_f32_e32 v242, v242, v237
	v_add_f32_e32 v242, v242, v238
	v_add_f32_e32 v242, v242, v239
	v_mov_b32_dpp v232, v124 row_ror:8 row_mask:0xf bank_mask:0xf
	v_mov_b32_dpp v233, v125 row_ror:8 row_mask:0xf bank_mask:0xf
	v_mov_b32_dpp v234, v126 row_ror:8 row_mask:0xf bank_mask:0xf
	v_mov_b32_dpp v235, v127 row_ror:8 row_mask:0xf bank_mask:0xf
	v_cndmask_b32_e64 v232, v34, v232, s[90:91]
	v_cndmask_b32_e64 v233, v35, v233, s[90:91]
	v_cndmask_b32_e64 v234, v36, v234, s[90:91]
	v_cndmask_b32_e64 v235, v37, v235, s[90:91]
	v_pk_add_f32 v[232:233], v[232:233], v[228:229]
	v_pk_add_f32 v[234:235], v[234:235], v[230:231]
	s_nop 0
	global_store_dwordx4 v244, v[232:235], s[46:47] offset:128
	v_cvt_pk_bf16_f32 v240, v232, v233
	v_cvt_pk_bf16_f32 v241, v234, v235
	v_pk_mul_f32 v[236:237], v[232:233], v[232:233]
	v_pk_mul_f32 v[238:239], v[234:235], v[234:235]
	global_store_dwordx2 v245, v[240:241], s[50:51] offset:64
	v_add_f32_e32 v191, v191, v236
	v_add_f32_e32 v191, v191, v237
	v_add_f32_e32 v191, v191, v238
	v_add_f32_e32 v191, v191, v239
	s_nop 1
	v_add_f32_dpp v242, v242, v242 row_ror:8 row_mask:0xf bank_mask:0xf
	v_add_f32_dpp v191, v191, v191 row_ror:8 row_mask:0xf bank_mask:0xf
	s_add_u32 s44, s44, 0x10000
	s_addc_u32 s45, s45, 0
	s_add_u32 s46, s46, 0x10000
	s_addc_u32 s47, s47, 0
	s_add_u32 s48, s48, 0x8000
	s_addc_u32 s49, s49, 0
	s_add_u32 s50, s50, 0x8000
	s_addc_u32 s51, s51, 0
	v_cndmask_b32_e64 v242, v191, v242, s[90:91]
	ds_bpermute_b32 v243, v189, v242
	global_load_dwordx4 v[216:219], v244, s[40:41]
	global_load_dwordx4 v[220:223], v244, s[40:41] offset:128
	global_load_dwordx4 v[224:227], v244, s[42:43]
	global_load_dwordx4 v[228:231], v244, s[42:43] offset:128
	s_add_u32 s40, s40, 0x10000
	s_addc_u32 s41, s41, 0
	s_add_u32 s42, s42, 0x10000
	s_addc_u32 s43, s43, 0
	s_waitcnt lgkmcnt(0)
	v_add_f32_e32 v242, v242, v243
	ds_bpermute_b32 v243, v190, v242
	s_waitcnt lgkmcnt(0)
	v_add_f32_e32 v242, v242, v243
	s_and_saveexec_b64 s[2:3], s[88:89]
	ds_write_b32 v188, v242 offset:320
	s_or_b64 exec, exec, s[2:3]
	s_waitcnt vmcnt(12)
; DI void gemm8_epi_resid(f32x4 (&acc)[8][4], int m0, int n0, int ntile8, bf16_t* L, const float* xin, float* out, bf16_t* xb, float* rowpart) {
;     ...
;   for (int i = 0; i < 8; ++i) {
;     const int ml = wm * 128 + i * 16 + (lane & 15);
;     const size_t rowoff = (size_t)(m0 + ml) * DM;
;     float ss = 0.f;
; #pragma unroll
;     for (int j = 0; j < 4; ++j) {
;       const int n = n0 + wn * 64 + j * 16 + (lane >> 4) * 4;
;       const float4 xv = *(const float4*)(xin + rowoff + n);
;       const float o0 = xv.x + acc[i][j][0], o1 = xv.y + acc[i][j][1], o2 = xv.z + acc[i][j][2], o3 = xv.w + acc[i][j][3];
;       *(float4*)(out + rowoff + n) = make_float4(o0, o1, o2, o3);
;       ss += o0 * o0 + o1 * o1 + o2 * o2 + o3 * o3;
;       uint2 u;
;       u.x = pack2(o0, o1);
;       u.y = pack2(o2, o3);
;       *(uint2*)(xb + rowoff + n) = u;
;     }
;     ss += shx(ss, 16, lane);
;     ss += shx(ss, 32, lane);
;     if ((lane >> 4) == 0) red[wn * 256 + ml] = ss;
;   }
	v_mov_b32_dpp v232, v26 row_ror:8 row_mask:0xf bank_mask:0xf
	v_mov_b32_dpp v233, v27 row_ror:8 row_mask:0xf bank_mask:0xf
	v_mov_b32_dpp v234, v28 row_ror:8 row_mask:0xf bank_mask:0xf
	v_mov_b32_dpp v235, v29 row_ror:8 row_mask:0xf bank_mask:0xf
	v_cndmask_b32_e64 v232, v232, v30, s[90:91]
	v_cndmask_b32_e64 v233, v233, v31, s[90:91]
	v_cndmask_b32_e64 v234, v234, v32, s[90:91]
	v_cndmask_b32_e64 v235, v235, v33, s[90:91]
	v_pk_add_f32 v[232:233], v[232:233], v[192:193]
	v_pk_add_f32 v[234:235], v[234:235], v[194:195]
	s_nop 0
	global_store_dwordx4 v244, v[232:235], s[44:45]
	v_cvt_pk_bf16_f32 v240, v232, v233
	v_cvt_pk_bf16_f32 v241, v234, v235
	v_pk_mul_f32 v[236:237], v[232:233], v[232:233]
	v_pk_mul_f32 v[238:239], v[234:235], v[234:235]
	global_store_dwordx2 v245, v[240:241], s[48:49]
	v_add_f32_e32 v242, v236, v237
	v_add_f32_e32 v242, v242, v238
	v_add_f32_e32 v242, v242, v239
	v_mov_b32_dpp v232, v30 row_ror:8 row_mask:0xf bank_mask:0xf
	v_mov_b32_dpp v233, v31 row_ror:8 row_mask:0xf bank_mask:0xf
	v_mov_b32_dpp v234, v32 row_ror:8 row_mask:0xf bank_mask:0xf
	v_mov_b32_dpp v235, v33 row_ror:8 row_mask:0xf bank_mask:0xf
	v_cndmask_b32_e64 v232, v26, v232, s[90:91]
	v_cndmask_b32_e64 v233, v27, v233, s[90:91]
	v_cndmask_b32_e64 v234, v28, v234, s[90:91]
	v_cndmask_b32_e64 v235, v29, v235, s[90:91]
	v_pk_add_f32 v[232:233], v[232:233], v[202:203]
	v_pk_add_f32 v[234:235], v[234:235], v[204:205]
	s_nop 0
	global_store_dwordx4 v244, v[232:235], s[46:47]
	v_cvt_pk_bf16_f32 v240, v232, v233
	v_cvt_pk_bf16_f32 v241, v234, v235
	v_pk_mul_f32 v[236:237], v[232:233], v[232:233]
	v_pk_mul_f32 v[238:239], v[234:235], v[234:235]
	global_store_dwordx2 v245, v[240:241], s[50:51]
	v_add_f32_e32 v191, v236, v237
	v_add_f32_e32 v191, v191, v238
	v_add_f32_e32 v191, v191, v239
	v_mov_b32_dpp v232, v18 row_ror:8 row_mask:0xf bank_mask:0xf
	v_mov_b32_dpp v233, v19 row_ror:8 row_mask:0xf bank_mask:0xf
	v_mov_b32_dpp v234, v20 row_ror:8 row_mask:0xf bank_mask:0xf
	v_mov_b32_dpp v235, v21 row_ror:8 row_mask:0xf bank_mask:0xf
	v_cndmask_b32_e64 v232, v232, v22, s[90:91]
	v_cndmask_b32_e64 v233, v233, v23, s[90:91]
	v_cndmask_b32_e64 v234, v234, v24, s[90:91]
	v_cndmask_b32_e64 v235, v235, v25, s[90:91]
	v_pk_add_f32 v[232:233], v[232:233], v[198:199]
	v_pk_add_f32 v[234:235], v[234:235], v[200:201]
	s_nop 0
	global_store_dwordx4 v244, v[232:235], s[44:45] offset:128
	v_cvt_pk_bf16_f32 v240, v232, v233
	v_cvt_pk_bf16_f32 v241, v234, v235
	v_pk_mul_f32 v[236:237], v[232:233], v[232:233]
	v_pk_mul_f32 v[238:239], v[234:235], v[234:235]
	global_store_dwordx2 v245, v[240:241], s[48:49] offset:64
	v_add_f32_e32 v242, v242, v236
	v_add_f32_e32 v242, v242, v237
	v_add_f32_e32 v242, v242, v238
	v_add_f32_e32 v242, v242, v239
	v_mov_b32_dpp v232, v22 row_ror:8 row_mask:0xf bank_mask:0xf
	v_mov_b32_dpp v233, v23 row_ror:8 row_mask:0xf bank_mask:0xf
	v_mov_b32_dpp v234, v24 row_ror:8 row_mask:0xf bank_mask:0xf
	v_mov_b32_dpp v235, v25 row_ror:8 row_mask:0xf bank_mask:0xf
	v_cndmask_b32_e64 v232, v18, v232, s[90:91]
	v_cndmask_b32_e64 v233, v19, v233, s[90:91]
	v_cndmask_b32_e64 v234, v20, v234, s[90:91]
	v_cndmask_b32_e64 v235, v21, v235, s[90:91]
	v_pk_add_f32 v[232:233], v[232:233], v[206:207]
	v_pk_add_f32 v[234:235], v[234:235], v[208:209]
	s_nop 0
	global_store_dwordx4 v244, v[232:235], s[46:47] offset:128
	v_cvt_pk_bf16_f32 v240, v232, v233
	v_cvt_pk_bf16_f32 v241, v234, v235
	v_pk_mul_f32 v[236:237], v[232:233], v[232:233]
	v_pk_mul_f32 v[238:239], v[234:235], v[234:235]
	global_store_dwordx2 v245, v[240:241], s[50:51] offset:64
	v_add_f32_e32 v191, v191, v236
	v_add_f32_e32 v191, v191, v237
	v_add_f32_e32 v191, v191, v238
	v_add_f32_e32 v191, v191, v239
	s_nop 1
	v_add_f32_dpp v242, v242, v242 row_ror:8 row_mask:0xf bank_mask:0xf
	v_add_f32_dpp v191, v191, v191 row_ror:8 row_mask:0xf bank_mask:0xf
	s_add_u32 s44, s44, 0x10000
	s_addc_u32 s45, s45, 0
	s_add_u32 s46, s46, 0x10000
	s_addc_u32 s47, s47, 0
	s_add_u32 s48, s48, 0x8000
	s_addc_u32 s49, s49, 0
	s_add_u32 s50, s50, 0x8000
	s_addc_u32 s51, s51, 0
	v_cndmask_b32_e64 v242, v191, v242, s[90:91]
	ds_bpermute_b32 v243, v189, v242
	s_waitcnt lgkmcnt(0)
	v_add_f32_e32 v242, v242, v243
	ds_bpermute_b32 v243, v190, v242
	s_waitcnt lgkmcnt(0)
	v_add_f32_e32 v242, v242, v243
	s_and_saveexec_b64 s[2:3], s[88:89]
	ds_write_b32 v188, v242 offset:384
	s_or_b64 exec, exec, s[2:3]
	s_waitcnt vmcnt(8)
; DI void gemm8_epi_resid(f32x4 (&acc)[8][4], int m0, int n0, int ntile8, bf16_t* L, const float* xin, float* out, bf16_t* xb, float* rowpart) {
;     ...
;   for (int i = 0; i < 8; ++i) {
;     const int ml = wm * 128 + i * 16 + (lane & 15);
;     const size_t rowoff = (size_t)(m0 + ml) * DM;
;     float ss = 0.f;
; #pragma unroll
;     for (int j = 0; j < 4; ++j) {
;       const int n = n0 + wn * 64 + j * 16 + (lane >> 4) * 4;
;       const float4 xv = *(const float4*)(xin + rowoff + n);
;       const float o0 = xv.x + acc[i][j][0], o1 = xv.y + acc[i][j][1], o2 = xv.z + acc[i][j][2], o3 = xv.w + acc[i][j][3];
;       *(float4*)(out + rowoff + n) = make_float4(o0, o1, o2, o3);
;       ss += o0 * o0 + o1 * o1 + o2 * o2 + o3 * o3;
;       uint2 u;
;       u.x = pack2(o0, o1);
;       u.y = pack2(o2, o3);
;       *(uint2*)(xb + rowoff + n) = u;
;     }
;     ss += shx(ss, 16, lane);
;     ss += shx(ss, 32, lane);
;     if ((lane >> 4) == 0) red[wn * 256 + ml] = ss;
;   }
	v_mov_b32_dpp v232, v10 row_ror:8 row_mask:0xf bank_mask:0xf
	v_mov_b32_dpp v233, v11 row_ror:8 row_mask:0xf bank_mask:0xf
	v_mov_b32_dpp v234, v12 row_ror:8 row_mask:0xf bank_mask:0xf
	v_mov_b32_dpp v235, v13 row_ror:8 row_mask:0xf bank_mask:0xf
	v_cndmask_b32_e64 v232, v232, v14, s[90:91]
	v_cndmask_b32_e64 v233, v233, v15, s[90:91]
	v_cndmask_b32_e64 v234, v234, v16, s[90:91]
	v_cndmask_b32_e64 v235, v235, v17, s[90:91]
	v_pk_add_f32 v[232:233], v[232:233], v[216:217]
	v_pk_add_f32 v[234:235], v[234:235], v[218:219]
	s_nop 0
	global_store_dwordx4 v244, v[232:235], s[44:45]
	v_cvt_pk_bf16_f32 v240, v232, v233
	v_cvt_pk_bf16_f32 v241, v234, v235
	v_pk_mul_f32 v[236:237], v[232:233], v[232:233]
	v_pk_mul_f32 v[238:239], v[234:235], v[234:235]
	global_store_dwordx2 v245, v[240:241], s[48:49]
	v_add_f32_e32 v242, v236, v237
	v_add_f32_e32 v242, v242, v238
	v_add_f32_e32 v242, v242, v239
	v_mov_b32_dpp v232, v14 row_ror:8 row_mask:0xf bank_mask:0xf
	v_mov_b32_dpp v233, v15 row_ror:8 row_mask:0xf bank_mask:0xf
	v_mov_b32_dpp v234, v16 row_ror:8 row_mask:0xf bank_mask:0xf
	v_mov_b32_dpp v235, v17 row_ror:8 row_mask:0xf bank_mask:0xf
	v_cndmask_b32_e64 v232, v10, v232, s[90:91]
	v_cndmask_b32_e64 v233, v11, v233, s[90:91]
	v_cndmask_b32_e64 v234, v12, v234, s[90:91]
	v_cndmask_b32_e64 v235, v13, v235, s[90:91]
	v_pk_add_f32 v[232:233], v[232:233], v[224:225]
	v_pk_add_f32 v[234:235], v[234:235], v[226:227]
	s_nop 0
	global_store_dwordx4 v244, v[232:235], s[46:47]
	v_cvt_pk_bf16_f32 v240, v232, v233
	v_cvt_pk_bf16_f32 v241, v234, v235
	v_pk_mul_f32 v[236:237], v[232:233], v[232:233]
	v_pk_mul_f32 v[238:239], v[234:235], v[234:235]
	global_store_dwordx2 v245, v[240:241], s[50:51]
	v_add_f32_e32 v191, v236, v237
	v_add_f32_e32 v191, v191, v238
	v_add_f32_e32 v191, v191, v239
	v_mov_b32_dpp v232, v38 row_ror:8 row_mask:0xf bank_mask:0xf
	v_mov_b32_dpp v233, v39 row_ror:8 row_mask:0xf bank_mask:0xf
	v_mov_b32_dpp v234, v40 row_ror:8 row_mask:0xf bank_mask:0xf
	v_mov_b32_dpp v235, v41 row_ror:8 row_mask:0xf bank_mask:0xf
	v_cndmask_b32_e64 v232, v232, v6, s[90:91]
	v_cndmask_b32_e64 v233, v233, v7, s[90:91]
	v_cndmask_b32_e64 v234, v234, v8, s[90:91]
	v_cndmask_b32_e64 v235, v235, v9, s[90:91]
	v_pk_add_f32 v[232:233], v[232:233], v[220:221]
	v_pk_add_f32 v[234:235], v[234:235], v[222:223]
	s_nop 0
	global_store_dwordx4 v244, v[232:235], s[44:45] offset:128
	v_cvt_pk_bf16_f32 v240, v232, v233
	v_cvt_pk_bf16_f32 v241, v234, v235
	v_pk_mul_f32 v[236:237], v[232:233], v[232:233]
	v_pk_mul_f32 v[238:239], v[234:235], v[234:235]
	global_store_dwordx2 v245, v[240:241], s[48:49] offset:64
	v_add_f32_e32 v242, v242, v236
	v_add_f32_e32 v242, v242, v237
	v_add_f32_e32 v242, v242, v238
	v_add_f32_e32 v242, v242, v239
	v_mov_b32_dpp v232, v6 row_ror:8 row_mask:0xf bank_mask:0xf
	v_mov_b32_dpp v233, v7 row_ror:8 row_mask:0xf bank_mask:0xf
	v_mov_b32_dpp v234, v8 row_ror:8 row_mask:0xf bank_mask:0xf
	v_mov_b32_dpp v235, v9 row_ror:8 row_mask:0xf bank_mask:0xf
	v_cndmask_b32_e64 v232, v38, v232, s[90:91]
	v_cndmask_b32_e64 v233, v39, v233, s[90:91]
	v_cndmask_b32_e64 v234, v40, v234, s[90:91]
	v_cndmask_b32_e64 v235, v41, v235, s[90:91]
	v_pk_add_f32 v[232:233], v[232:233], v[228:229]
	v_pk_add_f32 v[234:235], v[234:235], v[230:231]
	s_nop 0
	global_store_dwordx4 v244, v[232:235], s[46:47] offset:128
	v_cvt_pk_bf16_f32 v240, v232, v233
	v_cvt_pk_bf16_f32 v241, v234, v235
	v_pk_mul_f32 v[236:237], v[232:233], v[232:233]
	v_pk_mul_f32 v[238:239], v[234:235], v[234:235]
	global_store_dwordx2 v245, v[240:241], s[50:51] offset:64
	v_add_f32_e32 v191, v191, v236
	v_add_f32_e32 v191, v191, v237
	v_add_f32_e32 v191, v191, v238
	v_add_f32_e32 v191, v191, v239
	s_nop 1
	v_add_f32_dpp v242, v242, v242 row_ror:8 row_mask:0xf bank_mask:0xf
	v_add_f32_dpp v191, v191, v191 row_ror:8 row_mask:0xf bank_mask:0xf
	s_add_u32 s44, s44, 0x10000
	s_addc_u32 s45, s45, 0
	s_add_u32 s46, s46, 0x10000
	s_addc_u32 s47, s47, 0
	s_add_u32 s48, s48, 0x8000
	s_addc_u32 s49, s49, 0
	s_add_u32 s50, s50, 0x8000
	s_addc_u32 s51, s51, 0
	v_cndmask_b32_e64 v242, v191, v242, s[90:91]
	ds_bpermute_b32 v243, v189, v242
	s_waitcnt lgkmcnt(0)
	v_add_f32_e32 v242, v242, v243
	ds_bpermute_b32 v243, v190, v242
	s_waitcnt lgkmcnt(0)
	v_add_f32_e32 v242, v242, v243
	s_and_saveexec_b64 s[2:3], s[88:89]
	ds_write_b32 v188, v242 offset:448
	s_or_b64 exec, exec, s[2:3]
	s_branch .LBB0_824

; DI f32x4 mfma16(bf16x8 a, bf16x8 b, f32x4 c) { return __builtin_amdgcn_mfma_f32_16x16x32_bf16(a, b, c, 0, 0, 0); }
;     ...
;   for (int ks = KS0; ks < KS1; ++ks) {
;     bf16x8 af[8], bfr[4];
; #pragma unroll
;     for (int i = 0; i < 8; ++i) {
;       const int r = wm * 128 + i * 16 + (lane & 15);
;       af[i] = *(const bf16x8*)(S + r * 64 + (((ks * 4 + (lane >> 4)) ^ ((r >> 1) & 7)) << 3));
;     }
; #pragma unroll
;     for (int j = 0; j < 4; ++j) {
;       const int r = wn * 64 + j * 16 + (lane & 15);
;       bfr[j] = *(const bf16x8*)(S + 16384 + r * 64 + (((ks * 4 + (lane >> 4)) ^ ((r >> 1) & 7)) << 3));
;     }
;     __builtin_amdgcn_s_setprio(1);
; #pragma unroll
;     for (int i = 0; i < 8; ++i)
; #pragma unroll
;       for (int j = 0; j < 4; ++j) acc[i][j] = mfma16(bfr[j], af[i], acc[i][j]);
;     __builtin_amdgcn_s_setprio(0);
; DI void gemm8_accum(f32x4 (&acc)[8][4], const bf16_t* a, size_t lda, const bf16_t* b, size_t ldb, int nkb, bf16_t* L,
;                     const bool pre, const bf16_t* an, size_t ldan, const bf16_t* bn, size_t ldbn) {
;     ...
;   __syncthreads();
;   g8_store1(L + 32768, ra, lrow, lch);
;   g8_load1(ra, an, ldan, 0, lrow, lch);
;   __builtin_amdgcn_sched_barrier(0);
;   g8_compute<0, 1>(acc, L, wm, wn, lane);
;   __builtin_amdgcn_sched_barrier(0);
;   g8_store1(L + 32768 + 16384, rb, lrow, lch);
;   g8_load1(rb, bn, ldbn, 0, lrow, lch);
;   __builtin_amdgcn_sched_barrier(0);
;   g8_compute<1, 2>(acc, L, wm, wn, lane);
.Lstg_942_c:
	v_readlane_b32 s0, v254, 18
	s_add_i32 s12, s13, s0
	s_cmp_gt_u32 s12, 63
	s_cselect_b64 s[0:1], -1, 0
	s_cmp_lt_u32 s12, 64
	s_cselect_b32 s7, s12, s13
	s_lshl_b32 s2, s7, 1
	s_and_b32 s2, s2, 0x7fffffe0
	s_and_b32 s3, s7, 3
	s_or_b32 s2, s3, s2
	v_readlane_b32 s3, v252, 25
	s_or_b32 s28, s2, s3
	s_lshl_b32 s13, s11, 8
	s_lshl_b64 s[2:3], s[28:29], 21
	s_add_u32 s2, s16, s2
	v_mov_b32_e32 v169, v1
	v_mov_b32_e32 v167, v1
	s_addc_u32 s3, s17, s3
	v_lshlrev_b64 v[184:185], 1, v[168:169]
	v_lshlrev_b64 v[166:167], 1, v[166:167]
	v_lshlrev_b64 v[226:227], 1, v[0:1]
	v_lshl_add_u64 v[170:171], s[2:3], 0, v[164:165]
	v_lshl_add_u64 v[172:173], s[2:3], 0, v[184:185]
	v_lshl_add_u64 v[176:177], s[2:3], 0, v[166:167]
	v_lshl_add_u64 v[180:181], s[2:3], 0, v[226:227]
	s_barrier
	global_load_dwordx4 v[168:171], v[170:171], off
	s_nop 0
	global_load_dwordx4 v[172:175], v[172:173], off
	s_nop 0
	global_load_dwordx4 v[176:179], v[176:177], off
	s_nop 0
	global_load_dwordx4 v[180:183], v[180:181], off
	s_lshl_b32 s2, s7, 19
	s_and_b32 s2, s2, 0x600000
	v_readlane_b32 s20, v251, 59
	v_readlane_b32 s21, v251, 60
	s_add_u32 s2, s20, s2
	s_addc_u32 s3, s21, 0
	s_add_i32 s7, 0, 0x10000
	v_add3_u32 v0, s7, v189, v190
	s_waitcnt vmcnt(11)
	ds_write_b128 v0, v[22:25]
	s_waitcnt vmcnt(9)
	ds_write_b128 v0, v[18:21] offset:8192
	ds_write_b128 v0, v[26:29] offset:16384
	s_waitcnt vmcnt(8)
	ds_write_b128 v0, v[30:33] offset:24576
	v_lshlrev_b32_e32 v0, 1, v191
	v_add_u32_e32 v191, 0, v0
	v_add_u32_e32 v206, v191, v187
	ds_read_b128 v[18:21], v206
	ds_read_b128 v[22:25], v206 offset:2048
	ds_read_b128 v[26:29], v206 offset:4096
	ds_read_b128 v[30:33], v206 offset:6144
	ds_read_b128 v[192:195], v206 offset:8192
	ds_read_b128 v[198:201], v206 offset:10240
	ds_read_b128 v[202:205], v206 offset:12288
	ds_read_b128 v[206:209], v206 offset:14336
	v_add_u32_e32 v191, v191, v186
	ds_read_b128 v[210:213], v191 offset:32768
	ds_read_b128 v[214:217], v191 offset:34816
	ds_read_b128 v[218:221], v191 offset:36864
	ds_read_b128 v[222:225], v191 offset:38912
	s_setprio 1
	s_waitcnt lgkmcnt(3)
	v_mfma_f32_16x16x32_bf16 v[158:161], v[210:213], v[18:21], v[158:161]
	s_waitcnt lgkmcnt(2)
	v_mfma_f32_16x16x32_bf16 v[154:157], v[214:217], v[18:21], v[154:157]
	s_waitcnt lgkmcnt(1)
	v_mfma_f32_16x16x32_bf16 v[150:153], v[218:221], v[18:21], v[150:153]
	s_waitcnt lgkmcnt(0)
	v_mfma_f32_16x16x32_bf16 v[18:21], v[222:225], v[18:21], v[146:149]
	v_mfma_f32_16x16x32_bf16 v[142:145], v[210:213], v[22:25], v[142:145]
	v_mfma_f32_16x16x32_bf16 v[138:141], v[214:217], v[22:25], v[138:141]
	v_mfma_f32_16x16x32_bf16 v[134:137], v[218:221], v[22:25], v[134:137]
	v_mfma_f32_16x16x32_bf16 v[22:25], v[222:225], v[22:25], v[130:133]
	v_mfma_f32_16x16x32_bf16 v[126:129], v[210:213], v[26:29], v[126:129]
	v_mfma_f32_16x16x32_bf16 v[122:125], v[214:217], v[26:29], v[122:125]
	v_mfma_f32_16x16x32_bf16 v[118:121], v[218:221], v[26:29], v[118:121]
	v_mfma_f32_16x16x32_bf16 v[26:29], v[222:225], v[26:29], v[114:117]
	v_mfma_f32_16x16x32_bf16 v[110:113], v[210:213], v[30:33], v[110:113]
	v_mfma_f32_16x16x32_bf16 v[106:109], v[214:217], v[30:33], v[106:109]
	v_mfma_f32_16x16x32_bf16 v[102:105], v[218:221], v[30:33], v[102:105]
	v_mfma_f32_16x16x32_bf16 v[30:33], v[222:225], v[30:33], v[98:101]
	v_mfma_f32_16x16x32_bf16 v[94:97], v[210:213], v[192:195], v[94:97]
	v_mfma_f32_16x16x32_bf16 v[90:93], v[214:217], v[192:195], v[90:93]
	v_mfma_f32_16x16x32_bf16 v[86:89], v[218:221], v[192:195], v[86:89]
	v_mfma_f32_16x16x32_bf16 v[82:85], v[222:225], v[192:195], v[82:85]
	v_mfma_f32_16x16x32_bf16 v[78:81], v[210:213], v[198:201], v[78:81]
	v_mfma_f32_16x16x32_bf16 v[74:77], v[214:217], v[198:201], v[74:77]
	v_mfma_f32_16x16x32_bf16 v[70:73], v[218:221], v[198:201], v[70:73]
	v_mfma_f32_16x16x32_bf16 v[66:69], v[222:225], v[198:201], v[66:69]
	v_mfma_f32_16x16x32_bf16 v[62:65], v[210:213], v[202:205], v[62:65]
	v_mfma_f32_16x16x32_bf16 v[58:61], v[214:217], v[202:205], v[58:61]
	v_mfma_f32_16x16x32_bf16 v[54:57], v[218:221], v[202:205], v[54:57]
	v_mfma_f32_16x16x32_bf16 v[50:53], v[222:225], v[202:205], v[50:53]
	v_mfma_f32_16x16x32_bf16 v[46:49], v[210:213], v[206:209], v[46:49]
	v_mfma_f32_16x16x32_bf16 v[42:45], v[214:217], v[206:209], v[42:45]
	v_mfma_f32_16x16x32_bf16 v[38:41], v[218:221], v[206:209], v[38:41]
	v_mfma_f32_16x16x32_bf16 v[34:37], v[222:225], v[206:209], v[34:37]
	s_setprio 0
	v_readlane_b32 s20, v254, 36
	s_nop 1
	v_add3_u32 v98, s20, v189, v190
	s_waitcnt vmcnt(7)
	ds_write_b128 v98, v[14:17]
	s_waitcnt vmcnt(6)
	ds_write_b128 v98, v[2:5] offset:8192
	s_waitcnt vmcnt(5)
	ds_write_b128 v98, v[6:9] offset:16384
	s_waitcnt vmcnt(4)
	ds_write_b128 v98, v[10:13] offset:24576
	v_lshl_add_u64 v[2:3], s[2:3], 0, v[164:165]
	v_lshl_add_u64 v[6:7], s[2:3], 0, v[184:185]
	v_lshl_add_u64 v[10:11], s[2:3], 0, v[166:167]
	v_lshl_add_u64 v[14:15], s[2:3], 0, v[226:227]
	global_load_dwordx4 v[2:5], v[2:3], off
	s_nop 0
	global_load_dwordx4 v[6:9], v[6:7], off
	s_nop 0
	global_load_dwordx4 v[10:13], v[10:11], off
	s_nop 0
	global_load_dwordx4 v[14:17], v[14:15], off
	v_lshlrev_b32_e32 v184, 1, v188
	v_add_u32_e32 v185, 0, v184
	v_add_u32_e32 v198, v185, v187
	ds_read_b128 v[98:101], v198
	ds_read_b128 v[114:117], v198 offset:2048
	ds_read_b128 v[130:133], v198 offset:4096
	ds_read_b128 v[146:149], v198 offset:6144
	ds_read_b128 v[164:167], v198 offset:8192
	ds_read_b128 v[188:191], v198 offset:10240
	ds_read_b128 v[192:195], v198 offset:12288
	ds_read_b128 v[198:201], v198 offset:14336
	v_add_u32_e32 v185, v185, v186
	ds_read_b128 v[202:205], v185 offset:32768
	ds_read_b128 v[206:209], v185 offset:34816
	ds_read_b128 v[210:213], v185 offset:36864
	ds_read_b128 v[214:217], v185 offset:38912
	s_setprio 1
	s_waitcnt lgkmcnt(3)
; DI f32x4 mfma16(bf16x8 a, bf16x8 b, f32x4 c) { return __builtin_amdgcn_mfma_f32_16x16x32_bf16(a, b, c, 0, 0, 0); }
;     ...
;   for (int ks = KS0; ks < KS1; ++ks) {
;     bf16x8 af[8], bfr[4];
; #pragma unroll
;     for (int i = 0; i < 8; ++i) {
;       const int r = wm * 128 + i * 16 + (lane & 15);
;       af[i] = *(const bf16x8*)(S + r * 64 + (((ks * 4 + (lane >> 4)) ^ ((r >> 1) & 7)) << 3));
;     }
; #pragma unroll
;     for (int j = 0; j < 4; ++j) {
;       const int r = wn * 64 + j * 16 + (lane & 15);
;       bfr[j] = *(const bf16x8*)(S + 16384 + r * 64 + (((ks * 4 + (lane >> 4)) ^ ((r >> 1) & 7)) << 3));
;     }
;     __builtin_amdgcn_s_setprio(1);
; #pragma unroll
;     for (int i = 0; i < 8; ++i)
; #pragma unroll
;       for (int j = 0; j < 4; ++j) acc[i][j] = mfma16(bfr[j], af[i], acc[i][j]);
;     __builtin_amdgcn_s_setprio(0);
; DI void gemm8_accum(f32x4 (&acc)[8][4], const bf16_t* a, size_t lda, const bf16_t* b, size_t ldb, int nkb, bf16_t* L,
;                     const bool pre, const bf16_t* an, size_t ldan, const bf16_t* bn, size_t ldbn) {
;     ...
;   g8_compute<1, 2>(acc, L, wm, wn, lane);
;   __syncthreads();
;   g8_store1(L, ra, lrow, lch);
;   __builtin_amdgcn_sched_barrier(0);
;   g8_compute<0, 1>(acc, L + 32768, wm, wn, lane);
;   __builtin_amdgcn_sched_barrier(0);
;   g8_store1(L + 16384, rb, lrow, lch);
	v_mfma_f32_16x16x32_bf16 v[158:161], v[202:205], v[98:101], v[158:161]
	s_waitcnt lgkmcnt(2)
	v_mfma_f32_16x16x32_bf16 v[154:157], v[206:209], v[98:101], v[154:157]
	s_waitcnt lgkmcnt(1)
	v_mfma_f32_16x16x32_bf16 v[150:153], v[210:213], v[98:101], v[150:153]
	s_waitcnt lgkmcnt(0)
	v_mfma_f32_16x16x32_bf16 v[18:21], v[214:217], v[98:101], v[18:21]
	v_mfma_f32_16x16x32_bf16 v[98:101], v[202:205], v[114:117], v[142:145]
	v_mfma_f32_16x16x32_bf16 v[138:141], v[206:209], v[114:117], v[138:141]
	v_mfma_f32_16x16x32_bf16 v[134:137], v[210:213], v[114:117], v[134:137]
	v_mfma_f32_16x16x32_bf16 v[22:25], v[214:217], v[114:117], v[22:25]
	v_mfma_f32_16x16x32_bf16 v[114:117], v[202:205], v[130:133], v[126:129]
	v_mfma_f32_16x16x32_bf16 v[122:125], v[206:209], v[130:133], v[122:125]
	v_mfma_f32_16x16x32_bf16 v[118:121], v[210:213], v[130:133], v[118:121]
	v_mfma_f32_16x16x32_bf16 v[26:29], v[214:217], v[130:133], v[26:29]
	v_mfma_f32_16x16x32_bf16 v[110:113], v[202:205], v[146:149], v[110:113]
	v_mfma_f32_16x16x32_bf16 v[106:109], v[206:209], v[146:149], v[106:109]
	v_mfma_f32_16x16x32_bf16 v[102:105], v[210:213], v[146:149], v[102:105]
	v_mfma_f32_16x16x32_bf16 v[30:33], v[214:217], v[146:149], v[30:33]
	v_mfma_f32_16x16x32_bf16 v[94:97], v[202:205], v[164:167], v[94:97]
	v_mfma_f32_16x16x32_bf16 v[90:93], v[206:209], v[164:167], v[90:93]
	v_mfma_f32_16x16x32_bf16 v[86:89], v[210:213], v[164:167], v[86:89]
	v_mfma_f32_16x16x32_bf16 v[82:85], v[214:217], v[164:167], v[82:85]
	v_mfma_f32_16x16x32_bf16 v[78:81], v[202:205], v[188:191], v[78:81]
	v_mfma_f32_16x16x32_bf16 v[74:77], v[206:209], v[188:191], v[74:77]
	v_mfma_f32_16x16x32_bf16 v[70:73], v[210:213], v[188:191], v[70:73]
	v_mfma_f32_16x16x32_bf16 v[66:69], v[214:217], v[188:191], v[66:69]
	v_mfma_f32_16x16x32_bf16 v[62:65], v[202:205], v[192:195], v[62:65]
	v_mfma_f32_16x16x32_bf16 v[58:61], v[206:209], v[192:195], v[58:61]
	v_mfma_f32_16x16x32_bf16 v[54:57], v[210:213], v[192:195], v[54:57]
	v_mfma_f32_16x16x32_bf16 v[50:53], v[214:217], v[192:195], v[50:53]
	v_mfma_f32_16x16x32_bf16 v[46:49], v[202:205], v[198:201], v[46:49]
	v_mfma_f32_16x16x32_bf16 v[42:45], v[206:209], v[198:201], v[42:45]
	v_mfma_f32_16x16x32_bf16 v[38:41], v[210:213], v[198:201], v[38:41]
	v_mfma_f32_16x16x32_bf16 v[34:37], v[214:217], v[198:201], v[34:37]
	s_setprio 0
	s_barrier
	s_waitcnt vmcnt(7)
	ds_write_b128 v163, v[168:171]
	s_waitcnt vmcnt(6)
	ds_write_b128 v163, v[172:175] offset:8192
	s_waitcnt vmcnt(5)
	ds_write_b128 v163, v[176:179] offset:16384
	s_waitcnt vmcnt(4)
	ds_write_b128 v163, v[180:183] offset:24576
	v_add3_u32 v176, s7, v0, v187
	ds_read_b128 v[126:129], v176
	ds_read_b128 v[130:133], v176 offset:2048
	ds_read_b128 v[142:145], v176 offset:4096
	ds_read_b128 v[146:149], v176 offset:6144
	ds_read_b128 v[164:167], v176 offset:8192
	ds_read_b128 v[168:171], v176 offset:10240
	ds_read_b128 v[172:175], v176 offset:12288
	ds_read_b128 v[176:179], v176 offset:14336
	v_add3_u32 v0, s20, v0, v186
	ds_read_b128 v[180:183], v0
	ds_read_b128 v[188:191], v0 offset:2048
	ds_read_b128 v[192:195], v0 offset:4096
	ds_read_b128 v[198:201], v0 offset:6144
	s_setprio 1
	s_waitcnt lgkmcnt(3)
	v_mfma_f32_16x16x32_bf16 v[158:161], v[180:183], v[126:129], v[158:161]
	s_waitcnt lgkmcnt(2)
	v_mfma_f32_16x16x32_bf16 v[154:157], v[188:191], v[126:129], v[154:157]
	s_waitcnt lgkmcnt(1)
	v_mfma_f32_16x16x32_bf16 v[150:153], v[192:195], v[126:129], v[150:153]
	s_waitcnt lgkmcnt(0)
	v_mfma_f32_16x16x32_bf16 v[18:21], v[198:201], v[126:129], v[18:21]
	v_mfma_f32_16x16x32_bf16 v[98:101], v[180:183], v[130:133], v[98:101]
	v_mfma_f32_16x16x32_bf16 v[126:129], v[188:191], v[130:133], v[138:141]
	v_mfma_f32_16x16x32_bf16 v[22:25], v[198:201], v[130:133], v[22:25]
	v_mfma_f32_16x16x32_bf16 v[114:117], v[180:183], v[142:145], v[114:117]
	v_mfma_f32_16x16x32_bf16 v[122:125], v[188:191], v[142:145], v[122:125]
	v_mfma_f32_16x16x32_bf16 v[118:121], v[192:195], v[142:145], v[118:121]
	v_mfma_f32_16x16x32_bf16 v[26:29], v[198:201], v[142:145], v[26:29]
	v_mfma_f32_16x16x32_bf16 v[30:33], v[198:201], v[146:149], v[30:33]
	v_mfma_f32_16x16x32_bf16 v[134:137], v[192:195], v[130:133], v[134:137]
	v_mfma_f32_16x16x32_bf16 v[130:133], v[180:183], v[146:149], v[110:113]
	v_mfma_f32_16x16x32_bf16 v[138:141], v[188:191], v[146:149], v[106:109]
	v_mfma_f32_16x16x32_bf16 v[142:145], v[192:195], v[146:149], v[102:105]
	v_mfma_f32_16x16x32_bf16 v[146:149], v[180:183], v[164:167], v[94:97]
	v_mfma_f32_16x16x32_bf16 v[202:205], v[188:191], v[164:167], v[90:93]
	v_mfma_f32_16x16x32_bf16 v[206:209], v[192:195], v[164:167], v[86:89]
	v_mfma_f32_16x16x32_bf16 v[164:167], v[198:201], v[164:167], v[82:85]
	v_mfma_f32_16x16x32_bf16 v[210:213], v[180:183], v[168:171], v[78:81]
	v_mfma_f32_16x16x32_bf16 v[214:217], v[188:191], v[168:171], v[74:77]
	v_mfma_f32_16x16x32_bf16 v[218:221], v[192:195], v[168:171], v[70:73]
	v_mfma_f32_16x16x32_bf16 v[168:171], v[198:201], v[168:171], v[66:69]
	v_mfma_f32_16x16x32_bf16 v[222:225], v[180:183], v[172:175], v[62:65]
	v_mfma_f32_16x16x32_bf16 v[226:229], v[188:191], v[172:175], v[58:61]
	v_mfma_f32_16x16x32_bf16 v[230:233], v[192:195], v[172:175], v[54:57]
	v_mfma_f32_16x16x32_bf16 v[172:175], v[198:201], v[172:175], v[50:53]
	v_mfma_f32_16x16x32_bf16 v[180:183], v[180:183], v[176:179], v[46:49]
	v_mfma_f32_16x16x32_bf16 v[188:191], v[188:191], v[176:179], v[42:45]
	v_mfma_f32_16x16x32_bf16 v[192:195], v[192:195], v[176:179], v[38:41]
	v_mfma_f32_16x16x32_bf16 v[176:179], v[198:201], v[176:179], v[34:37]
	s_setprio 0
	s_waitcnt vmcnt(3)
	ds_write_b128 v163, v[2:5] offset:32768
	s_waitcnt vmcnt(2)
; DI int TID8() { int t = threadIdx.x; asm volatile("" : "+v"(t)); return t; }
; DI void gemm8_accum(f32x4 (&acc)[8][4], const bf16_t* a, size_t lda, const bf16_t* b, size_t ldb, int nkb, bf16_t* L,
;                     const bool pre, const bf16_t* an, size_t ldan, const bf16_t* bn, size_t ldbn) {
;     ...
;   g8_store1(L + 16384, rb, lrow, lch);
;   __builtin_amdgcn_sched_barrier(0);
;   g8_compute<1, 2>(acc, L + 32768, wm, wn, lane);
;   __syncthreads();
; DI void gemm8_epi_resid(f32x4 (&acc)[8][4], int m0, int n0, int ntile8, bf16_t* L, const float* xin, float* out, bf16_t* xb, float* rowpart) {
;   const int tid = TID8(), lane = tid & 63, w = tid >> 6;
;   const int wm = w >> 2, wn = w & 3;
;   float* red = (float*)(L + 32768);
; #pragma unroll
;   for (int i = 0; i < 8; ++i) {
;     const int ml = wm * 128 + i * 16 + (lane & 15);
;     const size_t rowoff = (size_t)(m0 + ml) * DM;
;     float ss = 0.f;
; #pragma unroll
;     for (int j = 0; j < 4; ++j) {
;       const int n = n0 + wn * 64 + j * 16 + (lane >> 4) * 4;
;       const float4 xv = *(const float4*)(xin + rowoff + n);
;       const float o0 = xv.x + acc[i][j][0], o1 = xv.y + acc[i][j][1], o2 = xv.z + acc[i][j][2], o3 = xv.w + acc[i][j][3];
;       *(float4*)(out + rowoff + n) = make_float4(o0, o1, o2, o3);
;       ss += o0 * o0 + o1 * o1 + o2 * o2 + o3 * o3;
	ds_write_b128 v163, v[6:9] offset:40960
	s_waitcnt vmcnt(1)
	ds_write_b128 v163, v[10:13] offset:49152
	s_waitcnt vmcnt(0)
	ds_write_b128 v163, v[14:17] offset:57344
	v_add3_u32 v0, s7, v184, v187
	ds_read_b128 v[2:5], v0
	ds_read_b128 v[6:9], v0 offset:2048
	ds_read_b128 v[10:13], v0 offset:4096
	ds_read_b128 v[14:17], v0 offset:6144
	ds_read_b128 v[34:37], v0 offset:8192
	ds_read_b128 v[198:201], v0 offset:10240
	ds_read_b128 v[234:237], v0 offset:12288
	ds_read_b128 v[238:241], v0 offset:14336
	v_add3_u32 v0, s20, v184, v186
	ds_read_b128 v[184:187], v0
	ds_read_b128 v[242:245], v0 offset:2048
	ds_read_b128 v[246:249], v0 offset:4096
	ds_read_b128 v[38:41], v0 offset:6144
	s_setprio 1
	s_waitcnt lgkmcnt(3)
	v_mfma_f32_16x16x32_bf16 v[158:161], v[184:187], v[2:5], v[158:161]
	s_waitcnt lgkmcnt(2)
	v_mfma_f32_16x16x32_bf16 v[154:157], v[242:245], v[2:5], v[154:157]
	s_waitcnt lgkmcnt(1)
	v_mfma_f32_16x16x32_bf16 v[150:153], v[246:249], v[2:5], v[150:153]
	s_waitcnt lgkmcnt(0)
	v_mfma_f32_16x16x32_bf16 v[2:5], v[38:41], v[2:5], v[18:21]
	v_mfma_f32_16x16x32_bf16 v[110:113], v[184:187], v[6:9], v[98:101]
	v_mfma_f32_16x16x32_bf16 v[106:109], v[242:245], v[6:9], v[126:129]
	v_mfma_f32_16x16x32_bf16 v[102:105], v[246:249], v[6:9], v[134:137]
	v_mfma_f32_16x16x32_bf16 v[98:101], v[38:41], v[6:9], v[22:25]
	v_mfma_f32_16x16x32_bf16 v[94:97], v[184:187], v[10:13], v[114:117]
	v_mfma_f32_16x16x32_bf16 v[90:93], v[242:245], v[10:13], v[122:125]
	v_mfma_f32_16x16x32_bf16 v[86:89], v[246:249], v[10:13], v[118:121]
	v_mfma_f32_16x16x32_bf16 v[82:85], v[38:41], v[10:13], v[26:29]
	v_mfma_f32_16x16x32_bf16 v[78:81], v[184:187], v[14:17], v[130:133]
	v_mfma_f32_16x16x32_bf16 v[74:77], v[242:245], v[14:17], v[138:141]
	v_mfma_f32_16x16x32_bf16 v[70:73], v[246:249], v[14:17], v[142:145]
	v_mfma_f32_16x16x32_bf16 v[66:69], v[38:41], v[14:17], v[30:33]
	v_mfma_f32_16x16x32_bf16 v[62:65], v[184:187], v[34:37], v[146:149]
	v_mfma_f32_16x16x32_bf16 v[58:61], v[242:245], v[34:37], v[202:205]
	v_mfma_f32_16x16x32_bf16 v[54:57], v[246:249], v[34:37], v[206:209]
	v_mfma_f32_16x16x32_bf16 v[50:53], v[38:41], v[34:37], v[164:167]
	v_mfma_f32_16x16x32_bf16 v[46:49], v[184:187], v[198:201], v[210:213]
	v_mfma_f32_16x16x32_bf16 v[42:45], v[242:245], v[198:201], v[214:217]
	v_mfma_f32_16x16x32_bf16 v[124:127], v[246:249], v[198:201], v[218:221]
	v_mfma_f32_16x16x32_bf16 v[34:37], v[38:41], v[198:201], v[168:171]
	v_mfma_f32_16x16x32_bf16 v[30:33], v[184:187], v[234:237], v[222:225]
	v_mfma_f32_16x16x32_bf16 v[26:29], v[242:245], v[234:237], v[226:229]
	v_mfma_f32_16x16x32_bf16 v[22:25], v[246:249], v[234:237], v[230:233]
	v_mfma_f32_16x16x32_bf16 v[18:21], v[38:41], v[234:237], v[172:175]
	v_mfma_f32_16x16x32_bf16 v[14:17], v[184:187], v[238:241], v[180:183]
	v_mfma_f32_16x16x32_bf16 v[10:13], v[242:245], v[238:241], v[188:191]
	v_mfma_f32_16x16x32_bf16 v[6:9], v[246:249], v[238:241], v[192:195]
	v_mfma_f32_16x16x32_bf16 v[38:41], v[38:41], v[238:241], v[176:179]
	s_setprio 0
	v_mov_b32_e32 v118, v196
	s_barrier
	s_movk_i32 s2, 0xff80
	v_ashrrev_i32_e32 v115, 1, v118
	v_and_b32_e32 v116, 15, v118
	v_bfe_u32 v114, v118, 6, 2
	v_and_or_b32 v121, v115, s2, v116
	v_lshrrev_b32_e32 v116, 2, v118
	v_and_b32_e32 v0, 63, v118
	v_lshlrev_b32_e32 v115, 6, v114
	v_and_b32_e32 v116, 12, v116
	v_or3_b32 v138, v116, s13, v115
	v_lshlrev_b32_e32 v115, 2, v0
	v_lshl_add_u32 v146, v114, 10, s7
	v_add_u32_e32 v114, s6, v121
	v_xor_b32_e32 v120, 64, v115
	v_xor_b32_e32 v119, 0x80, v115
	v_ashrrev_i32_e32 v115, 31, v114
	v_readlane_b32 s24, v251, 33
	v_lshlrev_b64 v[116:117], 12, v[114:115]
	v_readlane_b32 s26, v251, 35
	v_readlane_b32 s27, v251, 36
	v_cmp_gt_u32_e32 vcc, 16, v0
	v_lshlrev_b32_e32 v0, 2, v138
	v_lshl_add_u64 v[116:117], s[26:27], 0, v[116:117]
	v_lshl_add_u64 v[132:133], v[116:117], 0, v[0:1]
	v_lshlrev_b64 v[122:123], 11, v[114:115]
	v_lshl_add_u64 v[122:123], s[18:19], 0, v[122:123]
	v_lshlrev_b32_e32 v116, 1, v138
	v_mov_b32_e32 v117, v1
	v_lshl_add_u64 v[122:123], v[122:123], 0, v[116:117]
	v_readlane_b32 s25, v251, 34
	v_lshl_add_u32 v188, v121, 2, v146
	v_mov_b32_e32 v189, v120
	v_mov_b32_e32 v190, v119
	v_and_b32_e32 v240, 63, v118
	v_cmp_gt_u32_e64 s[88:89], 16, v240
	v_and_b32_e32 v243, 15, v118
	v_bfe_u32 v242, v118, 4, 2
	v_and_b32_e32 v240, 8, v243
	v_cmp_eq_u32_e64 s[90:91], 0, v240
	v_lshlrev_b32_e32 v236, 12, v243
	v_lshl_or_b32 v236, v242, 4, v236
	v_lshlrev_b32_e32 v237, 11, v243
	v_lshl_or_b32 v237, v242, 3, v237
	v_sub_co_u32_e32 v238, vcc, v132, v236
	v_subbrev_co_u32_e32 v239, vcc, 0, v133, vcc
	s_nop 0
	v_readfirstlane_b32 s40, v238
	v_readfirstlane_b32 s41, v239
	v_sub_co_u32_e32 v238, vcc, v132, v236
	v_subbrev_co_u32_e32 v239, vcc, 0, v133, vcc
	s_nop 0
	v_readfirstlane_b32 s44, v238
	v_readfirstlane_b32 s45, v239
	v_sub_co_u32_e32 v238, vcc, v122, v237
	v_subbrev_co_u32_e32 v239, vcc, 0, v123, vcc
	s_nop 0
	v_readfirstlane_b32 s48, v238
	v_readfirstlane_b32 s49, v239
	s_add_u32 s42, s40, 0x8000
	s_addc_u32 s43, s41, 0
	s_add_u32 s46, s44, 0x8000
	s_addc_u32 s47, s45, 0
	s_add_u32 s50, s48, 0x4000
	s_addc_u32 s51, s49, 0
	v_and_b32_e32 v238, 7, v243
	v_lshrrev_b32_e32 v239, 3, v243
	v_lshlrev_b32_e32 v244, 12, v238
	v_lshl_or_b32 v244, v239, 6, v244
	v_lshl_or_b32 v244, v242, 4, v244
	v_lshlrev_b32_e32 v245, 11, v238
	v_lshl_or_b32 v245, v239, 5, v245
	v_lshl_or_b32 v245, v242, 3, v245
	global_load_dwordx4 v[192:195], v244, s[40:41]
	global_load_dwordx4 v[198:201], v244, s[40:41] offset:128
	global_load_dwordx4 v[202:205], v244, s[42:43]
	global_load_dwordx4 v[206:209], v244, s[42:43] offset:128
	s_add_u32 s40, s40, 0x10000
	s_addc_u32 s41, s41, 0
	s_add_u32 s42, s42, 0x10000
	s_addc_u32 s43, s43, 0
	global_load_dwordx4 v[216:219], v244, s[40:41]
	global_load_dwordx4 v[220:223], v244, s[40:41] offset:128
	global_load_dwordx4 v[224:227], v244, s[42:43]
	global_load_dwordx4 v[228:231], v244, s[42:43] offset:128
	s_add_u32 s40, s40, 0x10000
	s_addc_u32 s41, s41, 0
	s_add_u32 s42, s42, 0x10000
	s_addc_u32 s43, s43, 0
	s_waitcnt vmcnt(4)
; DI void gemm8_epi_resid(f32x4 (&acc)[8][4], int m0, int n0, int ntile8, bf16_t* L, const float* xin, float* out, bf16_t* xb, float* rowpart) {
;     ...
;   for (int i = 0; i < 8; ++i) {
;     const int ml = wm * 128 + i * 16 + (lane & 15);
;     const size_t rowoff = (size_t)(m0 + ml) * DM;
;     float ss = 0.f;
; #pragma unroll
;     for (int j = 0; j < 4; ++j) {
;       const int n = n0 + wn * 64 + j * 16 + (lane >> 4) * 4;
;       const float4 xv = *(const float4*)(xin + rowoff + n);
;       const float o0 = xv.x + acc[i][j][0], o1 = xv.y + acc[i][j][1], o2 = xv.z + acc[i][j][2], o3 = xv.w + acc[i][j][3];
;       *(float4*)(out + rowoff + n) = make_float4(o0, o1, o2, o3);
;       ss += o0 * o0 + o1 * o1 + o2 * o2 + o3 * o3;
;       uint2 u;
;       u.x = pack2(o0, o1);
;       u.y = pack2(o2, o3);
;       *(uint2*)(xb + rowoff + n) = u;
;     }
;     ss += shx(ss, 16, lane);
;     ss += shx(ss, 32, lane);
;     if ((lane >> 4) == 0) red[wn * 256 + ml] = ss;
;   }
	v_mov_b32_dpp v232, v154 row_ror:8 row_mask:0xf bank_mask:0xf
	v_mov_b32_dpp v233, v155 row_ror:8 row_mask:0xf bank_mask:0xf
	v_mov_b32_dpp v234, v156 row_ror:8 row_mask:0xf bank_mask:0xf
	v_mov_b32_dpp v235, v157 row_ror:8 row_mask:0xf bank_mask:0xf
	v_cndmask_b32_e64 v232, v232, v158, s[90:91]
	v_cndmask_b32_e64 v233, v233, v159, s[90:91]
	v_cndmask_b32_e64 v234, v234, v160, s[90:91]
	v_cndmask_b32_e64 v235, v235, v161, s[90:91]
	v_pk_add_f32 v[232:233], v[232:233], v[192:193]
	v_pk_add_f32 v[234:235], v[234:235], v[194:195]
	s_nop 0
	global_store_dwordx4 v244, v[232:235], s[44:45]
	v_cvt_pk_bf16_f32 v240, v232, v233
	v_cvt_pk_bf16_f32 v241, v234, v235
	v_pk_mul_f32 v[236:237], v[232:233], v[232:233]
	v_pk_mul_f32 v[238:239], v[234:235], v[234:235]
	global_store_dwordx2 v245, v[240:241], s[48:49]
	v_add_f32_e32 v242, v236, v237
	v_add_f32_e32 v242, v242, v238
	v_add_f32_e32 v242, v242, v239
	v_mov_b32_dpp v232, v158 row_ror:8 row_mask:0xf bank_mask:0xf
	v_mov_b32_dpp v233, v159 row_ror:8 row_mask:0xf bank_mask:0xf
	v_mov_b32_dpp v234, v160 row_ror:8 row_mask:0xf bank_mask:0xf
	v_mov_b32_dpp v235, v161 row_ror:8 row_mask:0xf bank_mask:0xf
	v_cndmask_b32_e64 v232, v154, v232, s[90:91]
	v_cndmask_b32_e64 v233, v155, v233, s[90:91]
	v_cndmask_b32_e64 v234, v156, v234, s[90:91]
	v_cndmask_b32_e64 v235, v157, v235, s[90:91]
	v_pk_add_f32 v[232:233], v[232:233], v[202:203]
	v_pk_add_f32 v[234:235], v[234:235], v[204:205]
	s_nop 0
	global_store_dwordx4 v244, v[232:235], s[46:47]
	v_cvt_pk_bf16_f32 v240, v232, v233
	v_cvt_pk_bf16_f32 v241, v234, v235
	v_pk_mul_f32 v[236:237], v[232:233], v[232:233]
	v_pk_mul_f32 v[238:239], v[234:235], v[234:235]
	global_store_dwordx2 v245, v[240:241], s[50:51]
	v_add_f32_e32 v191, v236, v237
	v_add_f32_e32 v191, v191, v238
	v_add_f32_e32 v191, v191, v239
	v_mov_b32_dpp v232, v2 row_ror:8 row_mask:0xf bank_mask:0xf
	v_mov_b32_dpp v233, v3 row_ror:8 row_mask:0xf bank_mask:0xf
	v_mov_b32_dpp v234, v4 row_ror:8 row_mask:0xf bank_mask:0xf
	v_mov_b32_dpp v235, v5 row_ror:8 row_mask:0xf bank_mask:0xf
	v_cndmask_b32_e64 v232, v232, v150, s[90:91]
	v_cndmask_b32_e64 v233, v233, v151, s[90:91]
	v_cndmask_b32_e64 v234, v234, v152, s[90:91]
	v_cndmask_b32_e64 v235, v235, v153, s[90:91]
	v_pk_add_f32 v[232:233], v[232:233], v[198:199]
	v_pk_add_f32 v[234:235], v[234:235], v[200:201]
	s_nop 0
	global_store_dwordx4 v244, v[232:235], s[44:45] offset:128
	v_cvt_pk_bf16_f32 v240, v232, v233
	v_cvt_pk_bf16_f32 v241, v234, v235
	v_pk_mul_f32 v[236:237], v[232:233], v[232:233]
	v_pk_mul_f32 v[238:239], v[234:235], v[234:235]
	global_store_dwordx2 v245, v[240:241], s[48:49] offset:64
	v_add_f32_e32 v242, v242, v236
	v_add_f32_e32 v242, v242, v237
	v_add_f32_e32 v242, v242, v238
	v_add_f32_e32 v242, v242, v239
	v_mov_b32_dpp v232, v150 row_ror:8 row_mask:0xf bank_mask:0xf
	v_mov_b32_dpp v233, v151 row_ror:8 row_mask:0xf bank_mask:0xf
	v_mov_b32_dpp v234, v152 row_ror:8 row_mask:0xf bank_mask:0xf
	v_mov_b32_dpp v235, v153 row_ror:8 row_mask:0xf bank_mask:0xf
	v_cndmask_b32_e64 v232, v2, v232, s[90:91]
	v_cndmask_b32_e64 v233, v3, v233, s[90:91]
	v_cndmask_b32_e64 v234, v4, v234, s[90:91]
	v_cndmask_b32_e64 v235, v5, v235, s[90:91]
	v_pk_add_f32 v[232:233], v[232:233], v[206:207]
	v_pk_add_f32 v[234:235], v[234:235], v[208:209]
	s_nop 0
	global_store_dwordx4 v244, v[232:235], s[46:47] offset:128
	v_cvt_pk_bf16_f32 v240, v232, v233
	v_cvt_pk_bf16_f32 v241, v234, v235
	v_pk_mul_f32 v[236:237], v[232:233], v[232:233]
	v_pk_mul_f32 v[238:239], v[234:235], v[234:235]
	global_store_dwordx2 v245, v[240:241], s[50:51] offset:64
	v_add_f32_e32 v191, v191, v236
	v_add_f32_e32 v191, v191, v237
	v_add_f32_e32 v191, v191, v238
	v_add_f32_e32 v191, v191, v239
	s_nop 1
	v_add_f32_dpp v242, v242, v242 row_ror:8 row_mask:0xf bank_mask:0xf
	v_add_f32_dpp v191, v191, v191 row_ror:8 row_mask:0xf bank_mask:0xf
	s_add_u32 s44, s44, 0x10000
	s_addc_u32 s45, s45, 0
	s_add_u32 s46, s46, 0x10000
	s_addc_u32 s47, s47, 0
	s_add_u32 s48, s48, 0x8000
	s_addc_u32 s49, s49, 0
	s_add_u32 s50, s50, 0x8000
	s_addc_u32 s51, s51, 0
	v_cndmask_b32_e64 v242, v191, v242, s[90:91]
	ds_bpermute_b32 v243, v189, v242
	global_load_dwordx4 v[192:195], v244, s[40:41]
	global_load_dwordx4 v[198:201], v244, s[40:41] offset:128
	global_load_dwordx4 v[202:205], v244, s[42:43]
	global_load_dwordx4 v[206:209], v244, s[42:43] offset:128
	s_add_u32 s40, s40, 0x10000
	s_addc_u32 s41, s41, 0
	s_add_u32 s42, s42, 0x10000
	s_addc_u32 s43, s43, 0
	s_waitcnt lgkmcnt(0)
	v_add_f32_e32 v242, v242, v243
	ds_bpermute_b32 v243, v190, v242
	s_waitcnt lgkmcnt(0)
	v_add_f32_e32 v242, v242, v243
	s_and_saveexec_b64 s[2:3], s[88:89]
	ds_write_b32 v188, v242
	s_or_b64 exec, exec, s[2:3]
	s_waitcnt vmcnt(12)
; DI void gemm8_epi_resid(f32x4 (&acc)[8][4], int m0, int n0, int ntile8, bf16_t* L, const float* xin, float* out, bf16_t* xb, float* rowpart) {
;     ...
;   for (int i = 0; i < 8; ++i) {
;     const int ml = wm * 128 + i * 16 + (lane & 15);
;     const size_t rowoff = (size_t)(m0 + ml) * DM;
;     float ss = 0.f;
; #pragma unroll
;     for (int j = 0; j < 4; ++j) {
;       const int n = n0 + wn * 64 + j * 16 + (lane >> 4) * 4;
;       const float4 xv = *(const float4*)(xin + rowoff + n);
;       const float o0 = xv.x + acc[i][j][0], o1 = xv.y + acc[i][j][1], o2 = xv.z + acc[i][j][2], o3 = xv.w + acc[i][j][3];
;       *(float4*)(out + rowoff + n) = make_float4(o0, o1, o2, o3);
;       ss += o0 * o0 + o1 * o1 + o2 * o2 + o3 * o3;
;       uint2 u;
;       u.x = pack2(o0, o1);
;       u.y = pack2(o2, o3);
;       *(uint2*)(xb + rowoff + n) = u;
;     }
;     ss += shx(ss, 16, lane);
;     ss += shx(ss, 32, lane);
;     if ((lane >> 4) == 0) red[wn * 256 + ml] = ss;
;   }
	v_mov_b32_dpp v232, v106 row_ror:8 row_mask:0xf bank_mask:0xf
	v_mov_b32_dpp v233, v107 row_ror:8 row_mask:0xf bank_mask:0xf
	v_mov_b32_dpp v234, v108 row_ror:8 row_mask:0xf bank_mask:0xf
	v_mov_b32_dpp v235, v109 row_ror:8 row_mask:0xf bank_mask:0xf
	v_cndmask_b32_e64 v232, v232, v110, s[90:91]
	v_cndmask_b32_e64 v233, v233, v111, s[90:91]
	v_cndmask_b32_e64 v234, v234, v112, s[90:91]
	v_cndmask_b32_e64 v235, v235, v113, s[90:91]
	v_pk_add_f32 v[232:233], v[232:233], v[216:217]
	v_pk_add_f32 v[234:235], v[234:235], v[218:219]
	s_nop 0
	global_store_dwordx4 v244, v[232:235], s[44:45]
	v_cvt_pk_bf16_f32 v240, v232, v233
	v_cvt_pk_bf16_f32 v241, v234, v235
	v_pk_mul_f32 v[236:237], v[232:233], v[232:233]
	v_pk_mul_f32 v[238:239], v[234:235], v[234:235]
	global_store_dwordx2 v245, v[240:241], s[48:49]
	v_add_f32_e32 v242, v236, v237
	v_add_f32_e32 v242, v242, v238
	v_add_f32_e32 v242, v242, v239
	v_mov_b32_dpp v232, v110 row_ror:8 row_mask:0xf bank_mask:0xf
	v_mov_b32_dpp v233, v111 row_ror:8 row_mask:0xf bank_mask:0xf
	v_mov_b32_dpp v234, v112 row_ror:8 row_mask:0xf bank_mask:0xf
	v_mov_b32_dpp v235, v113 row_ror:8 row_mask:0xf bank_mask:0xf
	v_cndmask_b32_e64 v232, v106, v232, s[90:91]
	v_cndmask_b32_e64 v233, v107, v233, s[90:91]
	v_cndmask_b32_e64 v234, v108, v234, s[90:91]
	v_cndmask_b32_e64 v235, v109, v235, s[90:91]
	v_pk_add_f32 v[232:233], v[232:233], v[224:225]
	v_pk_add_f32 v[234:235], v[234:235], v[226:227]
	s_nop 0
	global_store_dwordx4 v244, v[232:235], s[46:47]
	v_cvt_pk_bf16_f32 v240, v232, v233
	v_cvt_pk_bf16_f32 v241, v234, v235
	v_pk_mul_f32 v[236:237], v[232:233], v[232:233]
	v_pk_mul_f32 v[238:239], v[234:235], v[234:235]
	global_store_dwordx2 v245, v[240:241], s[50:51]
	v_add_f32_e32 v191, v236, v237
	v_add_f32_e32 v191, v191, v238
	v_add_f32_e32 v191, v191, v239
	v_mov_b32_dpp v232, v98 row_ror:8 row_mask:0xf bank_mask:0xf
	v_mov_b32_dpp v233, v99 row_ror:8 row_mask:0xf bank_mask:0xf
	v_mov_b32_dpp v234, v100 row_ror:8 row_mask:0xf bank_mask:0xf
	v_mov_b32_dpp v235, v101 row_ror:8 row_mask:0xf bank_mask:0xf
	v_cndmask_b32_e64 v232, v232, v102, s[90:91]
	v_cndmask_b32_e64 v233, v233, v103, s[90:91]
	v_cndmask_b32_e64 v234, v234, v104, s[90:91]
	v_cndmask_b32_e64 v235, v235, v105, s[90:91]
	v_pk_add_f32 v[232:233], v[232:233], v[220:221]
	v_pk_add_f32 v[234:235], v[234:235], v[222:223]
	s_nop 0
	global_store_dwordx4 v244, v[232:235], s[44:45] offset:128
	v_cvt_pk_bf16_f32 v240, v232, v233
	v_cvt_pk_bf16_f32 v241, v234, v235
	v_pk_mul_f32 v[236:237], v[232:233], v[232:233]
	v_pk_mul_f32 v[238:239], v[234:235], v[234:235]
	global_store_dwordx2 v245, v[240:241], s[48:49] offset:64
	v_add_f32_e32 v242, v242, v236
	v_add_f32_e32 v242, v242, v237
	v_add_f32_e32 v242, v242, v238
	v_add_f32_e32 v242, v242, v239
	v_mov_b32_dpp v232, v102 row_ror:8 row_mask:0xf bank_mask:0xf
	v_mov_b32_dpp v233, v103 row_ror:8 row_mask:0xf bank_mask:0xf
	v_mov_b32_dpp v234, v104 row_ror:8 row_mask:0xf bank_mask:0xf
	v_mov_b32_dpp v235, v105 row_ror:8 row_mask:0xf bank_mask:0xf
	v_cndmask_b32_e64 v232, v98, v232, s[90:91]
	v_cndmask_b32_e64 v233, v99, v233, s[90:91]
	v_cndmask_b32_e64 v234, v100, v234, s[90:91]
	v_cndmask_b32_e64 v235, v101, v235, s[90:91]
	v_pk_add_f32 v[232:233], v[232:233], v[228:229]
	v_pk_add_f32 v[234:235], v[234:235], v[230:231]
	s_nop 0
	global_store_dwordx4 v244, v[232:235], s[46:47] offset:128
	v_cvt_pk_bf16_f32 v240, v232, v233
	v_cvt_pk_bf16_f32 v241, v234, v235
	v_pk_mul_f32 v[236:237], v[232:233], v[232:233]
	v_pk_mul_f32 v[238:239], v[234:235], v[234:235]
	global_store_dwordx2 v245, v[240:241], s[50:51] offset:64
	v_add_f32_e32 v191, v191, v236
	v_add_f32_e32 v191, v191, v237
	v_add_f32_e32 v191, v191, v238
	v_add_f32_e32 v191, v191, v239
	s_nop 1
	v_add_f32_dpp v242, v242, v242 row_ror:8 row_mask:0xf bank_mask:0xf
	v_add_f32_dpp v191, v191, v191 row_ror:8 row_mask:0xf bank_mask:0xf
	s_add_u32 s44, s44, 0x10000
	s_addc_u32 s45, s45, 0
	s_add_u32 s46, s46, 0x10000
	s_addc_u32 s47, s47, 0
	s_add_u32 s48, s48, 0x8000
	s_addc_u32 s49, s49, 0
	s_add_u32 s50, s50, 0x8000
	s_addc_u32 s51, s51, 0
	v_cndmask_b32_e64 v242, v191, v242, s[90:91]
	ds_bpermute_b32 v243, v189, v242
	global_load_dwordx4 v[216:219], v244, s[40:41]
	global_load_dwordx4 v[220:223], v244, s[40:41] offset:128
	global_load_dwordx4 v[224:227], v244, s[42:43]
	global_load_dwordx4 v[228:231], v244, s[42:43] offset:128
	s_add_u32 s40, s40, 0x10000
	s_addc_u32 s41, s41, 0
	s_add_u32 s42, s42, 0x10000
	s_addc_u32 s43, s43, 0
	s_waitcnt lgkmcnt(0)
	v_add_f32_e32 v242, v242, v243
	ds_bpermute_b32 v243, v190, v242
	s_waitcnt lgkmcnt(0)
	v_add_f32_e32 v242, v242, v243
	s_and_saveexec_b64 s[2:3], s[88:89]
	ds_write_b32 v188, v242 offset:64
	s_or_b64 exec, exec, s[2:3]
	s_waitcnt vmcnt(12)
; DI void gemm8_epi_resid(f32x4 (&acc)[8][4], int m0, int n0, int ntile8, bf16_t* L, const float* xin, float* out, bf16_t* xb, float* rowpart) {
;     ...
;   for (int i = 0; i < 8; ++i) {
;     const int ml = wm * 128 + i * 16 + (lane & 15);
;     const size_t rowoff = (size_t)(m0 + ml) * DM;
;     float ss = 0.f;
; #pragma unroll
;     for (int j = 0; j < 4; ++j) {
;       const int n = n0 + wn * 64 + j * 16 + (lane >> 4) * 4;
;       const float4 xv = *(const float4*)(xin + rowoff + n);
;       const float o0 = xv.x + acc[i][j][0], o1 = xv.y + acc[i][j][1], o2 = xv.z + acc[i][j][2], o3 = xv.w + acc[i][j][3];
;       *(float4*)(out + rowoff + n) = make_float4(o0, o1, o2, o3);
;       ss += o0 * o0 + o1 * o1 + o2 * o2 + o3 * o3;
;       uint2 u;
;       u.x = pack2(o0, o1);
;       u.y = pack2(o2, o3);
;       *(uint2*)(xb + rowoff + n) = u;
;     }
;     ss += shx(ss, 16, lane);
;     ss += shx(ss, 32, lane);
;     if ((lane >> 4) == 0) red[wn * 256 + ml] = ss;
;   }
	v_mov_b32_dpp v232, v90 row_ror:8 row_mask:0xf bank_mask:0xf
	v_mov_b32_dpp v233, v91 row_ror:8 row_mask:0xf bank_mask:0xf
	v_mov_b32_dpp v234, v92 row_ror:8 row_mask:0xf bank_mask:0xf
	v_mov_b32_dpp v235, v93 row_ror:8 row_mask:0xf bank_mask:0xf
	v_cndmask_b32_e64 v232, v232, v94, s[90:91]
	v_cndmask_b32_e64 v233, v233, v95, s[90:91]
	v_cndmask_b32_e64 v234, v234, v96, s[90:91]
	v_cndmask_b32_e64 v235, v235, v97, s[90:91]
	v_pk_add_f32 v[232:233], v[232:233], v[192:193]
	v_pk_add_f32 v[234:235], v[234:235], v[194:195]
	s_nop 0
	global_store_dwordx4 v244, v[232:235], s[44:45]
	v_cvt_pk_bf16_f32 v240, v232, v233
	v_cvt_pk_bf16_f32 v241, v234, v235
	v_pk_mul_f32 v[236:237], v[232:233], v[232:233]
	v_pk_mul_f32 v[238:239], v[234:235], v[234:235]
	global_store_dwordx2 v245, v[240:241], s[48:49]
	v_add_f32_e32 v242, v236, v237
	v_add_f32_e32 v242, v242, v238
	v_add_f32_e32 v242, v242, v239
	v_mov_b32_dpp v232, v94 row_ror:8 row_mask:0xf bank_mask:0xf
	v_mov_b32_dpp v233, v95 row_ror:8 row_mask:0xf bank_mask:0xf
	v_mov_b32_dpp v234, v96 row_ror:8 row_mask:0xf bank_mask:0xf
	v_mov_b32_dpp v235, v97 row_ror:8 row_mask:0xf bank_mask:0xf
	v_cndmask_b32_e64 v232, v90, v232, s[90:91]
	v_cndmask_b32_e64 v233, v91, v233, s[90:91]
	v_cndmask_b32_e64 v234, v92, v234, s[90:91]
	v_cndmask_b32_e64 v235, v93, v235, s[90:91]
	v_pk_add_f32 v[232:233], v[232:233], v[202:203]
	v_pk_add_f32 v[234:235], v[234:235], v[204:205]
	s_nop 0
	global_store_dwordx4 v244, v[232:235], s[46:47]
	v_cvt_pk_bf16_f32 v240, v232, v233
	v_cvt_pk_bf16_f32 v241, v234, v235
	v_pk_mul_f32 v[236:237], v[232:233], v[232:233]
	v_pk_mul_f32 v[238:239], v[234:235], v[234:235]
	global_store_dwordx2 v245, v[240:241], s[50:51]
	v_add_f32_e32 v191, v236, v237
	v_add_f32_e32 v191, v191, v238
	v_add_f32_e32 v191, v191, v239
	v_mov_b32_dpp v232, v82 row_ror:8 row_mask:0xf bank_mask:0xf
	v_mov_b32_dpp v233, v83 row_ror:8 row_mask:0xf bank_mask:0xf
	v_mov_b32_dpp v234, v84 row_ror:8 row_mask:0xf bank_mask:0xf
	v_mov_b32_dpp v235, v85 row_ror:8 row_mask:0xf bank_mask:0xf
	v_cndmask_b32_e64 v232, v232, v86, s[90:91]
	v_cndmask_b32_e64 v233, v233, v87, s[90:91]
	v_cndmask_b32_e64 v234, v234, v88, s[90:91]
	v_cndmask_b32_e64 v235, v235, v89, s[90:91]
	v_pk_add_f32 v[232:233], v[232:233], v[198:199]
	v_pk_add_f32 v[234:235], v[234:235], v[200:201]
	s_nop 0
	global_store_dwordx4 v244, v[232:235], s[44:45] offset:128
	v_cvt_pk_bf16_f32 v240, v232, v233
	v_cvt_pk_bf16_f32 v241, v234, v235
	v_pk_mul_f32 v[236:237], v[232:233], v[232:233]
	v_pk_mul_f32 v[238:239], v[234:235], v[234:235]
	global_store_dwordx2 v245, v[240:241], s[48:49] offset:64
	v_add_f32_e32 v242, v242, v236
	v_add_f32_e32 v242, v242, v237
	v_add_f32_e32 v242, v242, v238
	v_add_f32_e32 v242, v242, v239
	v_mov_b32_dpp v232, v86 row_ror:8 row_mask:0xf bank_mask:0xf
	v_mov_b32_dpp v233, v87 row_ror:8 row_mask:0xf bank_mask:0xf
	v_mov_b32_dpp v234, v88 row_ror:8 row_mask:0xf bank_mask:0xf
	v_mov_b32_dpp v235, v89 row_ror:8 row_mask:0xf bank_mask:0xf
	v_cndmask_b32_e64 v232, v82, v232, s[90:91]
	v_cndmask_b32_e64 v233, v83, v233, s[90:91]
	v_cndmask_b32_e64 v234, v84, v234, s[90:91]
	v_cndmask_b32_e64 v235, v85, v235, s[90:91]
	v_pk_add_f32 v[232:233], v[232:233], v[206:207]
	v_pk_add_f32 v[234:235], v[234:235], v[208:209]
	s_nop 0
	global_store_dwordx4 v244, v[232:235], s[46:47] offset:128
	v_cvt_pk_bf16_f32 v240, v232, v233
	v_cvt_pk_bf16_f32 v241, v234, v235
	v_pk_mul_f32 v[236:237], v[232:233], v[232:233]
	v_pk_mul_f32 v[238:239], v[234:235], v[234:235]
	global_store_dwordx2 v245, v[240:241], s[50:51] offset:64
	v_add_f32_e32 v191, v191, v236
	v_add_f32_e32 v191, v191, v237
	v_add_f32_e32 v191, v191, v238
	v_add_f32_e32 v191, v191, v239
	s_nop 1
	v_add_f32_dpp v242, v242, v242 row_ror:8 row_mask:0xf bank_mask:0xf
	v_add_f32_dpp v191, v191, v191 row_ror:8 row_mask:0xf bank_mask:0xf
	s_add_u32 s44, s44, 0x10000
	s_addc_u32 s45, s45, 0
	s_add_u32 s46, s46, 0x10000
	s_addc_u32 s47, s47, 0
	s_add_u32 s48, s48, 0x8000
	s_addc_u32 s49, s49, 0
	s_add_u32 s50, s50, 0x8000
	s_addc_u32 s51, s51, 0
	v_cndmask_b32_e64 v242, v191, v242, s[90:91]
	ds_bpermute_b32 v243, v189, v242
	global_load_dwordx4 v[192:195], v244, s[40:41]
	global_load_dwordx4 v[198:201], v244, s[40:41] offset:128
	global_load_dwordx4 v[202:205], v244, s[42:43]
	global_load_dwordx4 v[206:209], v244, s[42:43] offset:128
	s_add_u32 s40, s40, 0x10000
	s_addc_u32 s41, s41, 0
	s_add_u32 s42, s42, 0x10000
	s_addc_u32 s43, s43, 0
	s_waitcnt lgkmcnt(0)
	v_add_f32_e32 v242, v242, v243
	ds_bpermute_b32 v243, v190, v242
	s_waitcnt lgkmcnt(0)
	v_add_f32_e32 v242, v242, v243
	s_and_saveexec_b64 s[2:3], s[88:89]
	ds_write_b32 v188, v242 offset:128
	s_or_b64 exec, exec, s[2:3]
	s_waitcnt vmcnt(12)
; DI void gemm8_epi_resid(f32x4 (&acc)[8][4], int m0, int n0, int ntile8, bf16_t* L, const float* xin, float* out, bf16_t* xb, float* rowpart) {
;     ...
;   for (int i = 0; i < 8; ++i) {
;     const int ml = wm * 128 + i * 16 + (lane & 15);
;     const size_t rowoff = (size_t)(m0 + ml) * DM;
;     float ss = 0.f;
; #pragma unroll
;     for (int j = 0; j < 4; ++j) {
;       const int n = n0 + wn * 64 + j * 16 + (lane >> 4) * 4;
;       const float4 xv = *(const float4*)(xin + rowoff + n);
;       const float o0 = xv.x + acc[i][j][0], o1 = xv.y + acc[i][j][1], o2 = xv.z + acc[i][j][2], o3 = xv.w + acc[i][j][3];
;       *(float4*)(out + rowoff + n) = make_float4(o0, o1, o2, o3);
;       ss += o0 * o0 + o1 * o1 + o2 * o2 + o3 * o3;
;       uint2 u;
;       u.x = pack2(o0, o1);
;       u.y = pack2(o2, o3);
;       *(uint2*)(xb + rowoff + n) = u;
;     }
;     ss += shx(ss, 16, lane);
;     ss += shx(ss, 32, lane);
;     if ((lane >> 4) == 0) red[wn * 256 + ml] = ss;
;   }
	v_mov_b32_dpp v232, v74 row_ror:8 row_mask:0xf bank_mask:0xf
	v_mov_b32_dpp v233, v75 row_ror:8 row_mask:0xf bank_mask:0xf
	v_mov_b32_dpp v234, v76 row_ror:8 row_mask:0xf bank_mask:0xf
	v_mov_b32_dpp v235, v77 row_ror:8 row_mask:0xf bank_mask:0xf
	v_cndmask_b32_e64 v232, v232, v78, s[90:91]
	v_cndmask_b32_e64 v233, v233, v79, s[90:91]
	v_cndmask_b32_e64 v234, v234, v80, s[90:91]
	v_cndmask_b32_e64 v235, v235, v81, s[90:91]
	v_pk_add_f32 v[232:233], v[232:233], v[216:217]
	v_pk_add_f32 v[234:235], v[234:235], v[218:219]
	s_nop 0
	global_store_dwordx4 v244, v[232:235], s[44:45]
	v_cvt_pk_bf16_f32 v240, v232, v233
	v_cvt_pk_bf16_f32 v241, v234, v235
	v_pk_mul_f32 v[236:237], v[232:233], v[232:233]
	v_pk_mul_f32 v[238:239], v[234:235], v[234:235]
	global_store_dwordx2 v245, v[240:241], s[48:49]
	v_add_f32_e32 v242, v236, v237
	v_add_f32_e32 v242, v242, v238
	v_add_f32_e32 v242, v242, v239
	v_mov_b32_dpp v232, v78 row_ror:8 row_mask:0xf bank_mask:0xf
	v_mov_b32_dpp v233, v79 row_ror:8 row_mask:0xf bank_mask:0xf
	v_mov_b32_dpp v234, v80 row_ror:8 row_mask:0xf bank_mask:0xf
	v_mov_b32_dpp v235, v81 row_ror:8 row_mask:0xf bank_mask:0xf
	v_cndmask_b32_e64 v232, v74, v232, s[90:91]
	v_cndmask_b32_e64 v233, v75, v233, s[90:91]
	v_cndmask_b32_e64 v234, v76, v234, s[90:91]
	v_cndmask_b32_e64 v235, v77, v235, s[90:91]
	v_pk_add_f32 v[232:233], v[232:233], v[224:225]
	v_pk_add_f32 v[234:235], v[234:235], v[226:227]
	s_nop 0
	global_store_dwordx4 v244, v[232:235], s[46:47]
	v_cvt_pk_bf16_f32 v240, v232, v233
	v_cvt_pk_bf16_f32 v241, v234, v235
	v_pk_mul_f32 v[236:237], v[232:233], v[232:233]
	v_pk_mul_f32 v[238:239], v[234:235], v[234:235]
	global_store_dwordx2 v245, v[240:241], s[50:51]
	v_add_f32_e32 v191, v236, v237
	v_add_f32_e32 v191, v191, v238
	v_add_f32_e32 v191, v191, v239
	v_mov_b32_dpp v232, v66 row_ror:8 row_mask:0xf bank_mask:0xf
	v_mov_b32_dpp v233, v67 row_ror:8 row_mask:0xf bank_mask:0xf
	v_mov_b32_dpp v234, v68 row_ror:8 row_mask:0xf bank_mask:0xf
	v_mov_b32_dpp v235, v69 row_ror:8 row_mask:0xf bank_mask:0xf
	v_cndmask_b32_e64 v232, v232, v70, s[90:91]
	v_cndmask_b32_e64 v233, v233, v71, s[90:91]
	v_cndmask_b32_e64 v234, v234, v72, s[90:91]
	v_cndmask_b32_e64 v235, v235, v73, s[90:91]
	v_pk_add_f32 v[232:233], v[232:233], v[220:221]
	v_pk_add_f32 v[234:235], v[234:235], v[222:223]
	s_nop 0
	global_store_dwordx4 v244, v[232:235], s[44:45] offset:128
	v_cvt_pk_bf16_f32 v240, v232, v233
	v_cvt_pk_bf16_f32 v241, v234, v235
	v_pk_mul_f32 v[236:237], v[232:233], v[232:233]
	v_pk_mul_f32 v[238:239], v[234:235], v[234:235]
	global_store_dwordx2 v245, v[240:241], s[48:49] offset:64
	v_add_f32_e32 v242, v242, v236
	v_add_f32_e32 v242, v242, v237
	v_add_f32_e32 v242, v242, v238
	v_add_f32_e32 v242, v242, v239
	v_mov_b32_dpp v232, v70 row_ror:8 row_mask:0xf bank_mask:0xf
	v_mov_b32_dpp v233, v71 row_ror:8 row_mask:0xf bank_mask:0xf
	v_mov_b32_dpp v234, v72 row_ror:8 row_mask:0xf bank_mask:0xf
	v_mov_b32_dpp v235, v73 row_ror:8 row_mask:0xf bank_mask:0xf
	v_cndmask_b32_e64 v232, v66, v232, s[90:91]
	v_cndmask_b32_e64 v233, v67, v233, s[90:91]
	v_cndmask_b32_e64 v234, v68, v234, s[90:91]
	v_cndmask_b32_e64 v235, v69, v235, s[90:91]
	v_pk_add_f32 v[232:233], v[232:233], v[228:229]
	v_pk_add_f32 v[234:235], v[234:235], v[230:231]
	s_nop 0
	global_store_dwordx4 v244, v[232:235], s[46:47] offset:128
	v_cvt_pk_bf16_f32 v240, v232, v233
	v_cvt_pk_bf16_f32 v241, v234, v235
	v_pk_mul_f32 v[236:237], v[232:233], v[232:233]
	v_pk_mul_f32 v[238:239], v[234:235], v[234:235]
	global_store_dwordx2 v245, v[240:241], s[50:51] offset:64
	v_add_f32_e32 v191, v191, v236
	v_add_f32_e32 v191, v191, v237
	v_add_f32_e32 v191, v191, v238
	v_add_f32_e32 v191, v191, v239
	s_nop 1
	v_add_f32_dpp v242, v242, v242 row_ror:8 row_mask:0xf bank_mask:0xf
	v_add_f32_dpp v191, v191, v191 row_ror:8 row_mask:0xf bank_mask:0xf
	s_add_u32 s44, s44, 0x10000
	s_addc_u32 s45, s45, 0
	s_add_u32 s46, s46, 0x10000
	s_addc_u32 s47, s47, 0
	s_add_u32 s48, s48, 0x8000
	s_addc_u32 s49, s49, 0
	s_add_u32 s50, s50, 0x8000
	s_addc_u32 s51, s51, 0
	v_cndmask_b32_e64 v242, v191, v242, s[90:91]
	ds_bpermute_b32 v243, v189, v242
	global_load_dwordx4 v[216:219], v244, s[40:41]
	global_load_dwordx4 v[220:223], v244, s[40:41] offset:128
	global_load_dwordx4 v[224:227], v244, s[42:43]
	global_load_dwordx4 v[228:231], v244, s[42:43] offset:128
	s_add_u32 s40, s40, 0x10000
	s_addc_u32 s41, s41, 0
	s_add_u32 s42, s42, 0x10000
	s_addc_u32 s43, s43, 0
	s_waitcnt lgkmcnt(0)
	v_add_f32_e32 v242, v242, v243
	ds_bpermute_b32 v243, v190, v242
	s_waitcnt lgkmcnt(0)
	v_add_f32_e32 v242, v242, v243
	s_and_saveexec_b64 s[2:3], s[88:89]
	ds_write_b32 v188, v242 offset:192
	s_or_b64 exec, exec, s[2:3]
	s_waitcnt vmcnt(12)
; DI void gemm8_epi_resid(f32x4 (&acc)[8][4], int m0, int n0, int ntile8, bf16_t* L, const float* xin, float* out, bf16_t* xb, float* rowpart) {
;     ...
;   for (int i = 0; i < 8; ++i) {
;     const int ml = wm * 128 + i * 16 + (lane & 15);
;     const size_t rowoff = (size_t)(m0 + ml) * DM;
;     float ss = 0.f;
; #pragma unroll
;     for (int j = 0; j < 4; ++j) {
;       const int n = n0 + wn * 64 + j * 16 + (lane >> 4) * 4;
;       const float4 xv = *(const float4*)(xin + rowoff + n);
;       const float o0 = xv.x + acc[i][j][0], o1 = xv.y + acc[i][j][1], o2 = xv.z + acc[i][j][2], o3 = xv.w + acc[i][j][3];
;       *(float4*)(out + rowoff + n) = make_float4(o0, o1, o2, o3);
;       ss += o0 * o0 + o1 * o1 + o2 * o2 + o3 * o3;
;       uint2 u;
;       u.x = pack2(o0, o1);
;       u.y = pack2(o2, o3);
;       *(uint2*)(xb + rowoff + n) = u;
;     }
;     ss += shx(ss, 16, lane);
;     ss += shx(ss, 32, lane);
;     if ((lane >> 4) == 0) red[wn * 256 + ml] = ss;
;   }
	v_mov_b32_dpp v232, v58 row_ror:8 row_mask:0xf bank_mask:0xf
	v_mov_b32_dpp v233, v59 row_ror:8 row_mask:0xf bank_mask:0xf
	v_mov_b32_dpp v234, v60 row_ror:8 row_mask:0xf bank_mask:0xf
	v_mov_b32_dpp v235, v61 row_ror:8 row_mask:0xf bank_mask:0xf
	v_cndmask_b32_e64 v232, v232, v62, s[90:91]
	v_cndmask_b32_e64 v233, v233, v63, s[90:91]
	v_cndmask_b32_e64 v234, v234, v64, s[90:91]
	v_cndmask_b32_e64 v235, v235, v65, s[90:91]
	v_pk_add_f32 v[232:233], v[232:233], v[192:193]
	v_pk_add_f32 v[234:235], v[234:235], v[194:195]
	s_nop 0
	global_store_dwordx4 v244, v[232:235], s[44:45]
	v_cvt_pk_bf16_f32 v240, v232, v233
	v_cvt_pk_bf16_f32 v241, v234, v235
	v_pk_mul_f32 v[236:237], v[232:233], v[232:233]
	v_pk_mul_f32 v[238:239], v[234:235], v[234:235]
	global_store_dwordx2 v245, v[240:241], s[48:49]
	v_add_f32_e32 v242, v236, v237
	v_add_f32_e32 v242, v242, v238
	v_add_f32_e32 v242, v242, v239
	v_mov_b32_dpp v232, v62 row_ror:8 row_mask:0xf bank_mask:0xf
	v_mov_b32_dpp v233, v63 row_ror:8 row_mask:0xf bank_mask:0xf
	v_mov_b32_dpp v234, v64 row_ror:8 row_mask:0xf bank_mask:0xf
	v_mov_b32_dpp v235, v65 row_ror:8 row_mask:0xf bank_mask:0xf
	v_cndmask_b32_e64 v232, v58, v232, s[90:91]
	v_cndmask_b32_e64 v233, v59, v233, s[90:91]
	v_cndmask_b32_e64 v234, v60, v234, s[90:91]
	v_cndmask_b32_e64 v235, v61, v235, s[90:91]
	v_pk_add_f32 v[232:233], v[232:233], v[202:203]
	v_pk_add_f32 v[234:235], v[234:235], v[204:205]
	s_nop 0
	global_store_dwordx4 v244, v[232:235], s[46:47]
	v_cvt_pk_bf16_f32 v240, v232, v233
	v_cvt_pk_bf16_f32 v241, v234, v235
	v_pk_mul_f32 v[236:237], v[232:233], v[232:233]
	v_pk_mul_f32 v[238:239], v[234:235], v[234:235]
	global_store_dwordx2 v245, v[240:241], s[50:51]
	v_add_f32_e32 v191, v236, v237
	v_add_f32_e32 v191, v191, v238
	v_add_f32_e32 v191, v191, v239
	v_mov_b32_dpp v232, v50 row_ror:8 row_mask:0xf bank_mask:0xf
	v_mov_b32_dpp v233, v51 row_ror:8 row_mask:0xf bank_mask:0xf
	v_mov_b32_dpp v234, v52 row_ror:8 row_mask:0xf bank_mask:0xf
	v_mov_b32_dpp v235, v53 row_ror:8 row_mask:0xf bank_mask:0xf
	v_cndmask_b32_e64 v232, v232, v54, s[90:91]
	v_cndmask_b32_e64 v233, v233, v55, s[90:91]
	v_cndmask_b32_e64 v234, v234, v56, s[90:91]
	v_cndmask_b32_e64 v235, v235, v57, s[90:91]
	v_pk_add_f32 v[232:233], v[232:233], v[198:199]
	v_pk_add_f32 v[234:235], v[234:235], v[200:201]
	s_nop 0
	global_store_dwordx4 v244, v[232:235], s[44:45] offset:128
	v_cvt_pk_bf16_f32 v240, v232, v233
	v_cvt_pk_bf16_f32 v241, v234, v235
	v_pk_mul_f32 v[236:237], v[232:233], v[232:233]
	v_pk_mul_f32 v[238:239], v[234:235], v[234:235]
	global_store_dwordx2 v245, v[240:241], s[48:49] offset:64
	v_add_f32_e32 v242, v242, v236
	v_add_f32_e32 v242, v242, v237
	v_add_f32_e32 v242, v242, v238
	v_add_f32_e32 v242, v242, v239
	v_mov_b32_dpp v232, v54 row_ror:8 row_mask:0xf bank_mask:0xf
	v_mov_b32_dpp v233, v55 row_ror:8 row_mask:0xf bank_mask:0xf
	v_mov_b32_dpp v234, v56 row_ror:8 row_mask:0xf bank_mask:0xf
	v_mov_b32_dpp v235, v57 row_ror:8 row_mask:0xf bank_mask:0xf
	v_cndmask_b32_e64 v232, v50, v232, s[90:91]
	v_cndmask_b32_e64 v233, v51, v233, s[90:91]
	v_cndmask_b32_e64 v234, v52, v234, s[90:91]
	v_cndmask_b32_e64 v235, v53, v235, s[90:91]
	v_pk_add_f32 v[232:233], v[232:233], v[206:207]
	v_pk_add_f32 v[234:235], v[234:235], v[208:209]
	s_nop 0
	global_store_dwordx4 v244, v[232:235], s[46:47] offset:128
	v_cvt_pk_bf16_f32 v240, v232, v233
	v_cvt_pk_bf16_f32 v241, v234, v235
	v_pk_mul_f32 v[236:237], v[232:233], v[232:233]
	v_pk_mul_f32 v[238:239], v[234:235], v[234:235]
	global_store_dwordx2 v245, v[240:241], s[50:51] offset:64
	v_add_f32_e32 v191, v191, v236
	v_add_f32_e32 v191, v191, v237
	v_add_f32_e32 v191, v191, v238
	v_add_f32_e32 v191, v191, v239
	s_nop 1
	v_add_f32_dpp v242, v242, v242 row_ror:8 row_mask:0xf bank_mask:0xf
	v_add_f32_dpp v191, v191, v191 row_ror:8 row_mask:0xf bank_mask:0xf
	s_add_u32 s44, s44, 0x10000
	s_addc_u32 s45, s45, 0
	s_add_u32 s46, s46, 0x10000
	s_addc_u32 s47, s47, 0
	s_add_u32 s48, s48, 0x8000
	s_addc_u32 s49, s49, 0
	s_add_u32 s50, s50, 0x8000
	s_addc_u32 s51, s51, 0
	v_cndmask_b32_e64 v242, v191, v242, s[90:91]
	ds_bpermute_b32 v243, v189, v242
	global_load_dwordx4 v[192:195], v244, s[40:41]
	global_load_dwordx4 v[198:201], v244, s[40:41] offset:128
	global_load_dwordx4 v[202:205], v244, s[42:43]
	global_load_dwordx4 v[206:209], v244, s[42:43] offset:128
	s_add_u32 s40, s40, 0x10000
	s_addc_u32 s41, s41, 0
	s_add_u32 s42, s42, 0x10000
	s_addc_u32 s43, s43, 0
	s_waitcnt lgkmcnt(0)
	v_add_f32_e32 v242, v242, v243
	ds_bpermute_b32 v243, v190, v242
	s_waitcnt lgkmcnt(0)
	v_add_f32_e32 v242, v242, v243
	s_and_saveexec_b64 s[2:3], s[88:89]
	ds_write_b32 v188, v242 offset:256
	s_or_b64 exec, exec, s[2:3]
	s_waitcnt vmcnt(12)
; DI void gemm8_epi_resid(f32x4 (&acc)[8][4], int m0, int n0, int ntile8, bf16_t* L, const float* xin, float* out, bf16_t* xb, float* rowpart) {
;     ...
;   for (int i = 0; i < 8; ++i) {
;     const int ml = wm * 128 + i * 16 + (lane & 15);
;     const size_t rowoff = (size_t)(m0 + ml) * DM;
;     float ss = 0.f;
; #pragma unroll
;     for (int j = 0; j < 4; ++j) {
;       const int n = n0 + wn * 64 + j * 16 + (lane >> 4) * 4;
;       const float4 xv = *(const float4*)(xin + rowoff + n);
;       const float o0 = xv.x + acc[i][j][0], o1 = xv.y + acc[i][j][1], o2 = xv.z + acc[i][j][2], o3 = xv.w + acc[i][j][3];
;       *(float4*)(out + rowoff + n) = make_float4(o0, o1, o2, o3);
;       ss += o0 * o0 + o1 * o1 + o2 * o2 + o3 * o3;
;       uint2 u;
;       u.x = pack2(o0, o1);
;       u.y = pack2(o2, o3);
;       *(uint2*)(xb + rowoff + n) = u;
;     }
;     ss += shx(ss, 16, lane);
;     ss += shx(ss, 32, lane);
;     if ((lane >> 4) == 0) red[wn * 256 + ml] = ss;
;   }
	v_mov_b32_dpp v232, v42 row_ror:8 row_mask:0xf bank_mask:0xf
	v_mov_b32_dpp v233, v43 row_ror:8 row_mask:0xf bank_mask:0xf
	v_mov_b32_dpp v234, v44 row_ror:8 row_mask:0xf bank_mask:0xf
	v_mov_b32_dpp v235, v45 row_ror:8 row_mask:0xf bank_mask:0xf
	v_cndmask_b32_e64 v232, v232, v46, s[90:91]
	v_cndmask_b32_e64 v233, v233, v47, s[90:91]
	v_cndmask_b32_e64 v234, v234, v48, s[90:91]
	v_cndmask_b32_e64 v235, v235, v49, s[90:91]
	v_pk_add_f32 v[232:233], v[232:233], v[216:217]
	v_pk_add_f32 v[234:235], v[234:235], v[218:219]
	s_nop 0
	global_store_dwordx4 v244, v[232:235], s[44:45]
	v_cvt_pk_bf16_f32 v240, v232, v233
	v_cvt_pk_bf16_f32 v241, v234, v235
	v_pk_mul_f32 v[236:237], v[232:233], v[232:233]
	v_pk_mul_f32 v[238:239], v[234:235], v[234:235]
	global_store_dwordx2 v245, v[240:241], s[48:49]
	v_add_f32_e32 v242, v236, v237
	v_add_f32_e32 v242, v242, v238
	v_add_f32_e32 v242, v242, v239
	v_mov_b32_dpp v232, v46 row_ror:8 row_mask:0xf bank_mask:0xf
	v_mov_b32_dpp v233, v47 row_ror:8 row_mask:0xf bank_mask:0xf
	v_mov_b32_dpp v234, v48 row_ror:8 row_mask:0xf bank_mask:0xf
	v_mov_b32_dpp v235, v49 row_ror:8 row_mask:0xf bank_mask:0xf
	v_cndmask_b32_e64 v232, v42, v232, s[90:91]
	v_cndmask_b32_e64 v233, v43, v233, s[90:91]
	v_cndmask_b32_e64 v234, v44, v234, s[90:91]
	v_cndmask_b32_e64 v235, v45, v235, s[90:91]
	v_pk_add_f32 v[232:233], v[232:233], v[224:225]
	v_pk_add_f32 v[234:235], v[234:235], v[226:227]
	s_nop 0
	global_store_dwordx4 v244, v[232:235], s[46:47]
	v_cvt_pk_bf16_f32 v240, v232, v233
	v_cvt_pk_bf16_f32 v241, v234, v235
	v_pk_mul_f32 v[236:237], v[232:233], v[232:233]
	v_pk_mul_f32 v[238:239], v[234:235], v[234:235]
	global_store_dwordx2 v245, v[240:241], s[50:51]
	v_add_f32_e32 v191, v236, v237
	v_add_f32_e32 v191, v191, v238
	v_add_f32_e32 v191, v191, v239
	v_mov_b32_dpp v232, v34 row_ror:8 row_mask:0xf bank_mask:0xf
	v_mov_b32_dpp v233, v35 row_ror:8 row_mask:0xf bank_mask:0xf
	v_mov_b32_dpp v234, v36 row_ror:8 row_mask:0xf bank_mask:0xf
	v_mov_b32_dpp v235, v37 row_ror:8 row_mask:0xf bank_mask:0xf
	v_cndmask_b32_e64 v232, v232, v124, s[90:91]
	v_cndmask_b32_e64 v233, v233, v125, s[90:91]
	v_cndmask_b32_e64 v234, v234, v126, s[90:91]
	v_cndmask_b32_e64 v235, v235, v127, s[90:91]
	v_pk_add_f32 v[232:233], v[232:233], v[220:221]
	v_pk_add_f32 v[234:235], v[234:235], v[222:223]
	s_nop 0
	global_store_dwordx4 v244, v[232:235], s[44:45] offset:128
	v_cvt_pk_bf16_f32 v240, v232, v233
	v_cvt_pk_bf16_f32 v241, v234, v235
	v_pk_mul_f32 v[236:237], v[232:233], v[232:233]
	v_pk_mul_f32 v[238:239], v[234:235], v[234:235]
	global_store_dwordx2 v245, v[240:241], s[48:49] offset:64
	v_add_f32_e32 v242, v242, v236
	v_add_f32_e32 v242, v242, v237
	v_add_f32_e32 v242, v242, v238
	v_add_f32_e32 v242, v242, v239
	v_mov_b32_dpp v232, v124 row_ror:8 row_mask:0xf bank_mask:0xf
	v_mov_b32_dpp v233, v125 row_ror:8 row_mask:0xf bank_mask:0xf
	v_mov_b32_dpp v234, v126 row_ror:8 row_mask:0xf bank_mask:0xf
	v_mov_b32_dpp v235, v127 row_ror:8 row_mask:0xf bank_mask:0xf
	v_cndmask_b32_e64 v232, v34, v232, s[90:91]
	v_cndmask_b32_e64 v233, v35, v233, s[90:91]
	v_cndmask_b32_e64 v234, v36, v234, s[90:91]
	v_cndmask_b32_e64 v235, v37, v235, s[90:91]
	v_pk_add_f32 v[232:233], v[232:233], v[228:229]
	v_pk_add_f32 v[234:235], v[234:235], v[230:231]
	s_nop 0
	global_store_dwordx4 v244, v[232:235], s[46:47] offset:128
	v_cvt_pk_bf16_f32 v240, v232, v233
	v_cvt_pk_bf16_f32 v241, v234, v235
	v_pk_mul_f32 v[236:237], v[232:233], v[232:233]
	v_pk_mul_f32 v[238:239], v[234:235], v[234:235]
	global_store_dwordx2 v245, v[240:241], s[50:51] offset:64
	v_add_f32_e32 v191, v191, v236
	v_add_f32_e32 v191, v191, v237
	v_add_f32_e32 v191, v191, v238
	v_add_f32_e32 v191, v191, v239
	s_nop 1
	v_add_f32_dpp v242, v242, v242 row_ror:8 row_mask:0xf bank_mask:0xf
	v_add_f32_dpp v191, v191, v191 row_ror:8 row_mask:0xf bank_mask:0xf
	s_add_u32 s44, s44, 0x10000
	s_addc_u32 s45, s45, 0
	s_add_u32 s46, s46, 0x10000
	s_addc_u32 s47, s47, 0
	s_add_u32 s48, s48, 0x8000
	s_addc_u32 s49, s49, 0
	s_add_u32 s50, s50, 0x8000
	s_addc_u32 s51, s51, 0
	v_cndmask_b32_e64 v242, v191, v242, s[90:91]
	ds_bpermute_b32 v243, v189, v242
	global_load_dwordx4 v[216:219], v244, s[40:41]
	global_load_dwordx4 v[220:223], v244, s[40:41] offset:128
	global_load_dwordx4 v[224:227], v244, s[42:43]
	global_load_dwordx4 v[228:231], v244, s[42:43] offset:128
	s_add_u32 s40, s40, 0x10000
	s_addc_u32 s41, s41, 0
	s_add_u32 s42, s42, 0x10000
	s_addc_u32 s43, s43, 0
	s_waitcnt lgkmcnt(0)
	v_add_f32_e32 v242, v242, v243
	ds_bpermute_b32 v243, v190, v242
	s_waitcnt lgkmcnt(0)
	v_add_f32_e32 v242, v242, v243
	s_and_saveexec_b64 s[2:3], s[88:89]
	ds_write_b32 v188, v242 offset:320
	s_or_b64 exec, exec, s[2:3]
	s_waitcnt vmcnt(12)
; DI void gemm8_epi_resid(f32x4 (&acc)[8][4], int m0, int n0, int ntile8, bf16_t* L, const float* xin, float* out, bf16_t* xb, float* rowpart) {
;     ...
;   for (int i = 0; i < 8; ++i) {
;     const int ml = wm * 128 + i * 16 + (lane & 15);
;     const size_t rowoff = (size_t)(m0 + ml) * DM;
;     float ss = 0.f;
; #pragma unroll
;     for (int j = 0; j < 4; ++j) {
;       const int n = n0 + wn * 64 + j * 16 + (lane >> 4) * 4;
;       const float4 xv = *(const float4*)(xin + rowoff + n);
;       const float o0 = xv.x + acc[i][j][0], o1 = xv.y + acc[i][j][1], o2 = xv.z + acc[i][j][2], o3 = xv.w + acc[i][j][3];
;       *(float4*)(out + rowoff + n) = make_float4(o0, o1, o2, o3);
;       ss += o0 * o0 + o1 * o1 + o2 * o2 + o3 * o3;
;       uint2 u;
;       u.x = pack2(o0, o1);
;       u.y = pack2(o2, o3);
;       *(uint2*)(xb + rowoff + n) = u;
;     }
;     ss += shx(ss, 16, lane);
;     ss += shx(ss, 32, lane);
;     if ((lane >> 4) == 0) red[wn * 256 + ml] = ss;
;   }
	v_mov_b32_dpp v232, v26 row_ror:8 row_mask:0xf bank_mask:0xf
	v_mov_b32_dpp v233, v27 row_ror:8 row_mask:0xf bank_mask:0xf
	v_mov_b32_dpp v234, v28 row_ror:8 row_mask:0xf bank_mask:0xf
	v_mov_b32_dpp v235, v29 row_ror:8 row_mask:0xf bank_mask:0xf
	v_cndmask_b32_e64 v232, v232, v30, s[90:91]
	v_cndmask_b32_e64 v233, v233, v31, s[90:91]
	v_cndmask_b32_e64 v234, v234, v32, s[90:91]
	v_cndmask_b32_e64 v235, v235, v33, s[90:91]
	v_pk_add_f32 v[232:233], v[232:233], v[192:193]
	v_pk_add_f32 v[234:235], v[234:235], v[194:195]
	s_nop 0
	global_store_dwordx4 v244, v[232:235], s[44:45]
	v_cvt_pk_bf16_f32 v240, v232, v233
	v_cvt_pk_bf16_f32 v241, v234, v235
	v_pk_mul_f32 v[236:237], v[232:233], v[232:233]
	v_pk_mul_f32 v[238:239], v[234:235], v[234:235]
	global_store_dwordx2 v245, v[240:241], s[48:49]
	v_add_f32_e32 v242, v236, v237
	v_add_f32_e32 v242, v242, v238
	v_add_f32_e32 v242, v242, v239
	v_mov_b32_dpp v232, v30 row_ror:8 row_mask:0xf bank_mask:0xf
	v_mov_b32_dpp v233, v31 row_ror:8 row_mask:0xf bank_mask:0xf
	v_mov_b32_dpp v234, v32 row_ror:8 row_mask:0xf bank_mask:0xf
	v_mov_b32_dpp v235, v33 row_ror:8 row_mask:0xf bank_mask:0xf
	v_cndmask_b32_e64 v232, v26, v232, s[90:91]
	v_cndmask_b32_e64 v233, v27, v233, s[90:91]
	v_cndmask_b32_e64 v234, v28, v234, s[90:91]
	v_cndmask_b32_e64 v235, v29, v235, s[90:91]
	v_pk_add_f32 v[232:233], v[232:233], v[202:203]
	v_pk_add_f32 v[234:235], v[234:235], v[204:205]
	s_nop 0
	global_store_dwordx4 v244, v[232:235], s[46:47]
	v_cvt_pk_bf16_f32 v240, v232, v233
	v_cvt_pk_bf16_f32 v241, v234, v235
	v_pk_mul_f32 v[236:237], v[232:233], v[232:233]
	v_pk_mul_f32 v[238:239], v[234:235], v[234:235]
	global_store_dwordx2 v245, v[240:241], s[50:51]
	v_add_f32_e32 v191, v236, v237
	v_add_f32_e32 v191, v191, v238
	v_add_f32_e32 v191, v191, v239
	v_mov_b32_dpp v232, v18 row_ror:8 row_mask:0xf bank_mask:0xf
	v_mov_b32_dpp v233, v19 row_ror:8 row_mask:0xf bank_mask:0xf
	v_mov_b32_dpp v234, v20 row_ror:8 row_mask:0xf bank_mask:0xf
	v_mov_b32_dpp v235, v21 row_ror:8 row_mask:0xf bank_mask:0xf
	v_cndmask_b32_e64 v232, v232, v22, s[90:91]
	v_cndmask_b32_e64 v233, v233, v23, s[90:91]
	v_cndmask_b32_e64 v234, v234, v24, s[90:91]
	v_cndmask_b32_e64 v235, v235, v25, s[90:91]
	v_pk_add_f32 v[232:233], v[232:233], v[198:199]
	v_pk_add_f32 v[234:235], v[234:235], v[200:201]
	s_nop 0
	global_store_dwordx4 v244, v[232:235], s[44:45] offset:128
	v_cvt_pk_bf16_f32 v240, v232, v233
	v_cvt_pk_bf16_f32 v241, v234, v235
	v_pk_mul_f32 v[236:237], v[232:233], v[232:233]
	v_pk_mul_f32 v[238:239], v[234:235], v[234:235]
	global_store_dwordx2 v245, v[240:241], s[48:49] offset:64
	v_add_f32_e32 v242, v242, v236
	v_add_f32_e32 v242, v242, v237
	v_add_f32_e32 v242, v242, v238
	v_add_f32_e32 v242, v242, v239
	v_mov_b32_dpp v232, v22 row_ror:8 row_mask:0xf bank_mask:0xf
	v_mov_b32_dpp v233, v23 row_ror:8 row_mask:0xf bank_mask:0xf
	v_mov_b32_dpp v234, v24 row_ror:8 row_mask:0xf bank_mask:0xf
	v_mov_b32_dpp v235, v25 row_ror:8 row_mask:0xf bank_mask:0xf
	v_cndmask_b32_e64 v232, v18, v232, s[90:91]
	v_cndmask_b32_e64 v233, v19, v233, s[90:91]
	v_cndmask_b32_e64 v234, v20, v234, s[90:91]
	v_cndmask_b32_e64 v235, v21, v235, s[90:91]
	v_pk_add_f32 v[232:233], v[232:233], v[206:207]
	v_pk_add_f32 v[234:235], v[234:235], v[208:209]
	s_nop 0
	global_store_dwordx4 v244, v[232:235], s[46:47] offset:128
	v_cvt_pk_bf16_f32 v240, v232, v233
	v_cvt_pk_bf16_f32 v241, v234, v235
	v_pk_mul_f32 v[236:237], v[232:233], v[232:233]
	v_pk_mul_f32 v[238:239], v[234:235], v[234:235]
	global_store_dwordx2 v245, v[240:241], s[50:51] offset:64
	v_add_f32_e32 v191, v191, v236
	v_add_f32_e32 v191, v191, v237
	v_add_f32_e32 v191, v191, v238
	v_add_f32_e32 v191, v191, v239
	s_nop 1
	v_add_f32_dpp v242, v242, v242 row_ror:8 row_mask:0xf bank_mask:0xf
	v_add_f32_dpp v191, v191, v191 row_ror:8 row_mask:0xf bank_mask:0xf
	s_add_u32 s44, s44, 0x10000
	s_addc_u32 s45, s45, 0
	s_add_u32 s46, s46, 0x10000
	s_addc_u32 s47, s47, 0
	s_add_u32 s48, s48, 0x8000
	s_addc_u32 s49, s49, 0
	s_add_u32 s50, s50, 0x8000
	s_addc_u32 s51, s51, 0
	v_cndmask_b32_e64 v242, v191, v242, s[90:91]
	ds_bpermute_b32 v243, v189, v242
	s_waitcnt lgkmcnt(0)
	v_add_f32_e32 v242, v242, v243
	ds_bpermute_b32 v243, v190, v242
	s_waitcnt lgkmcnt(0)
	v_add_f32_e32 v242, v242, v243
	s_and_saveexec_b64 s[2:3], s[88:89]
	ds_write_b32 v188, v242 offset:384
	s_or_b64 exec, exec, s[2:3]
	s_waitcnt vmcnt(8)
; DI void gemm8_epi_resid(f32x4 (&acc)[8][4], int m0, int n0, int ntile8, bf16_t* L, const float* xin, float* out, bf16_t* xb, float* rowpart) {
;     ...
; #pragma unroll
;   for (int i = 0; i < 8; ++i) {
;     const int ml = wm * 128 + i * 16 + (lane & 15);
;     const size_t rowoff = (size_t)(m0 + ml) * DM;
;     float ss = 0.f;
; #pragma unroll
;     for (int j = 0; j < 4; ++j) {
;       const int n = n0 + wn * 64 + j * 16 + (lane >> 4) * 4;
;       const float4 xv = *(const float4*)(xin + rowoff + n);
;       const float o0 = xv.x + acc[i][j][0], o1 = xv.y + acc[i][j][1], o2 = xv.z + acc[i][j][2], o3 = xv.w + acc[i][j][3];
;       *(float4*)(out + rowoff + n) = make_float4(o0, o1, o2, o3);
;       ss += o0 * o0 + o1 * o1 + o2 * o2 + o3 * o3;
;       uint2 u;
;       u.x = pack2(o0, o1);
;       u.y = pack2(o2, o3);
;       *(uint2*)(xb + rowoff + n) = u;
;     }
;     ss += shx(ss, 16, lane);
;     ss += shx(ss, 32, lane);
;     if ((lane >> 4) == 0) red[wn * 256 + ml] = ss;
;   }
	v_mov_b32_dpp v232, v10 row_ror:8 row_mask:0xf bank_mask:0xf
	v_mov_b32_dpp v233, v11 row_ror:8 row_mask:0xf bank_mask:0xf
	v_mov_b32_dpp v234, v12 row_ror:8 row_mask:0xf bank_mask:0xf
	v_mov_b32_dpp v235, v13 row_ror:8 row_mask:0xf bank_mask:0xf
	v_cndmask_b32_e64 v232, v232, v14, s[90:91]
	v_cndmask_b32_e64 v233, v233, v15, s[90:91]
	v_cndmask_b32_e64 v234, v234, v16, s[90:91]
	v_cndmask_b32_e64 v235, v235, v17, s[90:91]
	v_pk_add_f32 v[232:233], v[232:233], v[216:217]
	v_pk_add_f32 v[234:235], v[234:235], v[218:219]
	s_nop 0
	global_store_dwordx4 v244, v[232:235], s[44:45]
	v_cvt_pk_bf16_f32 v240, v232, v233
	v_cvt_pk_bf16_f32 v241, v234, v235
	v_pk_mul_f32 v[236:237], v[232:233], v[232:233]
	v_pk_mul_f32 v[238:239], v[234:235], v[234:235]
	global_store_dwordx2 v245, v[240:241], s[48:49]
	v_add_f32_e32 v242, v236, v237
	v_add_f32_e32 v242, v242, v238
	v_add_f32_e32 v242, v242, v239
	v_mov_b32_dpp v232, v14 row_ror:8 row_mask:0xf bank_mask:0xf
	v_mov_b32_dpp v233, v15 row_ror:8 row_mask:0xf bank_mask:0xf
	v_mov_b32_dpp v234, v16 row_ror:8 row_mask:0xf bank_mask:0xf
	v_mov_b32_dpp v235, v17 row_ror:8 row_mask:0xf bank_mask:0xf
	v_cndmask_b32_e64 v232, v10, v232, s[90:91]
	v_cndmask_b32_e64 v233, v11, v233, s[90:91]
	v_cndmask_b32_e64 v234, v12, v234, s[90:91]
	v_cndmask_b32_e64 v235, v13, v235, s[90:91]
	v_pk_add_f32 v[232:233], v[232:233], v[224:225]
	v_pk_add_f32 v[234:235], v[234:235], v[226:227]
	s_nop 0
	global_store_dwordx4 v244, v[232:235], s[46:47]
	v_cvt_pk_bf16_f32 v240, v232, v233
	v_cvt_pk_bf16_f32 v241, v234, v235
	v_pk_mul_f32 v[236:237], v[232:233], v[232:233]
	v_pk_mul_f32 v[238:239], v[234:235], v[234:235]
	global_store_dwordx2 v245, v[240:241], s[50:51]
	v_add_f32_e32 v191, v236, v237
	v_add_f32_e32 v191, v191, v238
	v_add_f32_e32 v191, v191, v239
	v_mov_b32_dpp v232, v38 row_ror:8 row_mask:0xf bank_mask:0xf
	v_mov_b32_dpp v233, v39 row_ror:8 row_mask:0xf bank_mask:0xf
	v_mov_b32_dpp v234, v40 row_ror:8 row_mask:0xf bank_mask:0xf
	v_mov_b32_dpp v235, v41 row_ror:8 row_mask:0xf bank_mask:0xf
	v_cndmask_b32_e64 v232, v232, v6, s[90:91]
	v_cndmask_b32_e64 v233, v233, v7, s[90:91]
	v_cndmask_b32_e64 v234, v234, v8, s[90:91]
	v_cndmask_b32_e64 v235, v235, v9, s[90:91]
	v_pk_add_f32 v[232:233], v[232:233], v[220:221]
	v_pk_add_f32 v[234:235], v[234:235], v[222:223]
	s_nop 0
	global_store_dwordx4 v244, v[232:235], s[44:45] offset:128
	v_cvt_pk_bf16_f32 v240, v232, v233
	v_cvt_pk_bf16_f32 v241, v234, v235
	v_pk_mul_f32 v[236:237], v[232:233], v[232:233]
	v_pk_mul_f32 v[238:239], v[234:235], v[234:235]
	global_store_dwordx2 v245, v[240:241], s[48:49] offset:64
	v_add_f32_e32 v242, v242, v236
	v_add_f32_e32 v242, v242, v237
	v_add_f32_e32 v242, v242, v238
	v_add_f32_e32 v242, v242, v239
	v_mov_b32_dpp v232, v6 row_ror:8 row_mask:0xf bank_mask:0xf
	v_mov_b32_dpp v233, v7 row_ror:8 row_mask:0xf bank_mask:0xf
	v_mov_b32_dpp v234, v8 row_ror:8 row_mask:0xf bank_mask:0xf
	v_mov_b32_dpp v235, v9 row_ror:8 row_mask:0xf bank_mask:0xf
	v_cndmask_b32_e64 v232, v38, v232, s[90:91]
	v_cndmask_b32_e64 v233, v39, v233, s[90:91]
	v_cndmask_b32_e64 v234, v40, v234, s[90:91]
	v_cndmask_b32_e64 v235, v41, v235, s[90:91]
	v_pk_add_f32 v[232:233], v[232:233], v[228:229]
	v_pk_add_f32 v[234:235], v[234:235], v[230:231]
	s_nop 0
	global_store_dwordx4 v244, v[232:235], s[46:47] offset:128
	v_cvt_pk_bf16_f32 v240, v232, v233
	v_cvt_pk_bf16_f32 v241, v234, v235
	v_pk_mul_f32 v[236:237], v[232:233], v[232:233]
	v_pk_mul_f32 v[238:239], v[234:235], v[234:235]
	global_store_dwordx2 v245, v[240:241], s[50:51] offset:64
	v_add_f32_e32 v191, v191, v236
	v_add_f32_e32 v191, v191, v237
	v_add_f32_e32 v191, v191, v238
	v_add_f32_e32 v191, v191, v239
	s_nop 1
	v_add_f32_dpp v242, v242, v242 row_ror:8 row_mask:0xf bank_mask:0xf
	v_add_f32_dpp v191, v191, v191 row_ror:8 row_mask:0xf bank_mask:0xf
	s_add_u32 s44, s44, 0x10000
	s_addc_u32 s45, s45, 0
	s_add_u32 s46, s46, 0x10000
	s_addc_u32 s47, s47, 0
	s_add_u32 s48, s48, 0x8000
	s_addc_u32 s49, s49, 0
	s_add_u32 s50, s50, 0x8000
	s_addc_u32 s51, s51, 0
	v_cndmask_b32_e64 v242, v191, v242, s[90:91]
	ds_bpermute_b32 v243, v189, v242
	s_waitcnt lgkmcnt(0)
	v_add_f32_e32 v242, v242, v243
	ds_bpermute_b32 v243, v190, v242
	s_waitcnt lgkmcnt(0)
	v_add_f32_e32 v242, v242, v243
	s_and_saveexec_b64 s[2:3], s[88:89]
	ds_write_b32 v188, v242 offset:448
	s_or_b64 exec, exec, s[2:3]
	s_branch .LBB0_936
